# G2 rope table via LDS; G4/G6 resid epilogue: all residual loads before stores (saddr dword)
# speedup vs baseline: 1.0161x; 1.0161x over previous
.LBB0_224:
	s_or_b64 exec, exec, s[0:1]
	v_add_u32_e32 v131, v130, v172
	ds_read_b128 v[132:135], v131
	ds_read_b128 v[136:139], v131 offset:4096
	ds_read_b128 v[140:143], v131 offset:8192
	ds_read_b128 v[150:153], v131 offset:12288
	v_add_u32_e32 v131, v128, v172
	ds_read_b128 v[154:157], v131 offset:32768
	ds_read_b128 v[158:161], v131 offset:36864
	s_setprio 1
	s_waitcnt lgkmcnt(0)
	v_mfma_f32_32x32x16_bf16 v[112:127], v[132:135], v[154:157], v[112:127]
	v_mfma_f32_32x32x16_bf16 v[96:111], v[132:135], v[158:161], v[96:111]
	v_mfma_f32_32x32x16_bf16 v[80:95], v[136:139], v[154:157], v[80:95]
	v_mfma_f32_32x32x16_bf16 v[64:79], v[136:139], v[158:161], v[64:79]
	v_mfma_f32_32x32x16_bf16 v[48:63], v[140:143], v[154:157], v[48:63]
	v_mfma_f32_32x32x16_bf16 v[32:47], v[140:143], v[158:161], v[32:47]
	v_mfma_f32_32x32x16_bf16 v[16:31], v[150:153], v[154:157], v[16:31]
	v_mfma_f32_32x32x16_bf16 v[0:15], v[150:153], v[158:161], v[0:15]
	s_setprio 0
	v_add_u32_e32 v142, v130, v171
	ds_read_b128 v[130:133], v142
	ds_read_b128 v[134:137], v142 offset:4096
	ds_read_b128 v[138:141], v142 offset:8192
	ds_read_b128 v[142:145], v142 offset:12288
	v_add_u32_e32 v128, v128, v171
	ds_read_b128 v[150:153], v128 offset:32768
	ds_read_b128 v[154:157], v128 offset:36864
	s_setprio 1
	s_waitcnt lgkmcnt(0)
	v_mfma_f32_32x32x16_bf16 v[112:127], v[130:133], v[150:153], v[112:127]
	v_mfma_f32_32x32x16_bf16 v[96:111], v[130:133], v[154:157], v[96:111]
	v_mfma_f32_32x32x16_bf16 v[80:95], v[134:137], v[150:153], v[80:95]
	v_mfma_f32_32x32x16_bf16 v[64:79], v[134:137], v[154:157], v[64:79]
	v_mfma_f32_32x32x16_bf16 v[48:63], v[138:141], v[150:153], v[48:63]
	v_mfma_f32_32x32x16_bf16 v[32:47], v[138:141], v[154:157], v[32:47]
	v_mfma_f32_32x32x16_bf16 v[16:31], v[142:145], v[150:153], v[16:31]
	v_mfma_f32_32x32x16_bf16 v[0:15], v[142:145], v[154:157], v[0:15]
	s_setprio 0
	v_add_u32_e32 v138, v170, v168
	v_or_b32_e32 v144, v169, v167
	v_lshlrev_b32_e32 v132, 12, v138
	v_lshl_add_u32 v132, v144, 2, v132
	v_readlane_b32 s1, v254, 62
	s_movk_i32 s0, 0x1fff
	v_add_u32_e32 v128, 0xffffe000, v170
	v_cmp_lt_i32_e32 vcc, s0, v170
	v_lshrrev_b32_e32 v128, 10, v128
	v_add_u32_e32 v128, 1, v128
	v_cndmask_b32_e32 v128, 0, v128, vcc
	v_mov_b64_e32 v[130:131], s[66:67]
	v_add_u32_e32 v128, s1, v128
	s_movk_i32 s0, 0x6000
	v_mad_u64_u32 v[130:131], s[0:1], v128, s0, v[130:131]
	s_mov_b64 s[0:1], 0x5000
	v_lshl_add_u64 v[130:131], v[130:131], 0, s[0:1]
	v_mov_b32_e32 v135, 0
	v_lshlrev_b32_e32 v134, 2, v144
	v_lshl_add_u64 v[130:131], v[130:131], 0, v[134:135]
	global_load_dword v128, v[130:131], off
	global_load_dword v133, v[130:131], off offset:128
	s_mov_b32 s0, s68
	s_mov_b32 s1, s69
	global_load_dword v150, v132, s[0:1]
	global_load_dword v172, v132, s[0:1] offset:128
	s_add_u32 s0, s68, 0x1000
	s_addc_u32 s1, s69, 0
	global_load_dword v151, v132, s[0:1]
	global_load_dword v173, v132, s[0:1] offset:128
	s_add_u32 s0, s68, 0x2000
	s_addc_u32 s1, s69, 0
	global_load_dword v152, v132, s[0:1]
	global_load_dword v174, v132, s[0:1] offset:128
	s_add_u32 s0, s68, 0x3000
	s_addc_u32 s1, s69, 0
	global_load_dword v153, v132, s[0:1]
	global_load_dword v175, v132, s[0:1] offset:128
	s_add_u32 s0, s68, 0x8000
	s_addc_u32 s1, s69, 0
	global_load_dword v154, v132, s[0:1]
	global_load_dword v176, v132, s[0:1] offset:128
	s_add_u32 s0, s68, 0x9000
	s_addc_u32 s1, s69, 0
	global_load_dword v155, v132, s[0:1]
	global_load_dword v177, v132, s[0:1] offset:128
	s_add_u32 s0, s68, 0xa000
	s_addc_u32 s1, s69, 0
	global_load_dword v156, v132, s[0:1]
	global_load_dword v178, v132, s[0:1] offset:128
	s_add_u32 s0, s68, 0xb000
	s_addc_u32 s1, s69, 0
	global_load_dword v157, v132, s[0:1]
	global_load_dword v179, v132, s[0:1] offset:128
	s_add_u32 s0, s68, 0x10000
	s_addc_u32 s1, s69, 0
	global_load_dword v158, v132, s[0:1]
	global_load_dword v180, v132, s[0:1] offset:128
	s_add_u32 s0, s68, 0x11000
	s_addc_u32 s1, s69, 0
	global_load_dword v159, v132, s[0:1]
	global_load_dword v181, v132, s[0:1] offset:128
	s_add_u32 s0, s68, 0x12000
	s_addc_u32 s1, s69, 0
	global_load_dword v160, v132, s[0:1]
	global_load_dword v182, v132, s[0:1] offset:128
	s_add_u32 s0, s68, 0x13000
	s_addc_u32 s1, s69, 0
	global_load_dword v161, v132, s[0:1]
	global_load_dword v183, v132, s[0:1] offset:128
	s_add_u32 s0, s68, 0x18000
	s_addc_u32 s1, s69, 0
	global_load_dword v162, v132, s[0:1]
	global_load_dword v184, v132, s[0:1] offset:128
	s_add_u32 s0, s68, 0x19000
	s_addc_u32 s1, s69, 0
	global_load_dword v163, v132, s[0:1]
	global_load_dword v185, v132, s[0:1] offset:128
	s_add_u32 s0, s68, 0x1a000
	s_addc_u32 s1, s69, 0
	global_load_dword v164, v132, s[0:1]
	global_load_dword v186, v132, s[0:1] offset:128
	s_add_u32 s0, s68, 0x1b000
	s_addc_u32 s1, s69, 0
	global_load_dword v165, v132, s[0:1]
	global_load_dword v187, v132, s[0:1] offset:128
	s_add_u32 s0, s68, 0x20000
	s_addc_u32 s1, s69, 0
	global_load_dword v188, v132, s[0:1]
	global_load_dword v204, v132, s[0:1] offset:128
	s_add_u32 s0, s68, 0x21000
	s_addc_u32 s1, s69, 0
	global_load_dword v189, v132, s[0:1]
	global_load_dword v205, v132, s[0:1] offset:128
	s_add_u32 s0, s68, 0x22000
	s_addc_u32 s1, s69, 0
	global_load_dword v190, v132, s[0:1]
	global_load_dword v206, v132, s[0:1] offset:128
	s_add_u32 s0, s68, 0x23000
	s_addc_u32 s1, s69, 0
	global_load_dword v191, v132, s[0:1]
	global_load_dword v207, v132, s[0:1] offset:128
	s_add_u32 s0, s68, 0x28000
	s_addc_u32 s1, s69, 0
	global_load_dword v192, v132, s[0:1]
	global_load_dword v208, v132, s[0:1] offset:128
	s_add_u32 s0, s68, 0x29000
	s_addc_u32 s1, s69, 0
	global_load_dword v193, v132, s[0:1]
	global_load_dword v209, v132, s[0:1] offset:128
	s_add_u32 s0, s68, 0x2a000
	s_addc_u32 s1, s69, 0
	global_load_dword v194, v132, s[0:1]
	global_load_dword v210, v132, s[0:1] offset:128
	s_add_u32 s0, s68, 0x2b000
	s_addc_u32 s1, s69, 0
	global_load_dword v195, v132, s[0:1]
	global_load_dword v211, v132, s[0:1] offset:128
	s_add_u32 s0, s68, 0x30000
	s_addc_u32 s1, s69, 0
	global_load_dword v196, v132, s[0:1]
	global_load_dword v212, v132, s[0:1] offset:128
	s_add_u32 s0, s68, 0x31000
	s_addc_u32 s1, s69, 0
	global_load_dword v197, v132, s[0:1]
	global_load_dword v213, v132, s[0:1] offset:128
	s_add_u32 s0, s68, 0x32000
	s_addc_u32 s1, s69, 0
	global_load_dword v198, v132, s[0:1]
	global_load_dword v214, v132, s[0:1] offset:128
	s_add_u32 s0, s68, 0x33000
	s_addc_u32 s1, s69, 0
	global_load_dword v199, v132, s[0:1]
	global_load_dword v215, v132, s[0:1] offset:128
	s_add_u32 s0, s68, 0x38000
	s_addc_u32 s1, s69, 0
	global_load_dword v200, v132, s[0:1]
	global_load_dword v216, v132, s[0:1] offset:128
	s_add_u32 s0, s68, 0x39000
	s_addc_u32 s1, s69, 0
	global_load_dword v201, v132, s[0:1]
	global_load_dword v217, v132, s[0:1] offset:128
	s_add_u32 s0, s68, 0x3a000
	s_addc_u32 s1, s69, 0
	global_load_dword v202, v132, s[0:1]
	global_load_dword v218, v132, s[0:1] offset:128
	s_add_u32 s0, s68, 0x3b000
	s_addc_u32 s1, s69, 0
	global_load_dword v203, v132, s[0:1]
	global_load_dword v219, v132, s[0:1] offset:128
	s_waitcnt vmcnt(32)
	v_fmac_f32_e32 v150, v112, v128
	v_fmac_f32_e32 v151, v113, v128
	v_fmac_f32_e32 v152, v114, v128
	v_fmac_f32_e32 v153, v115, v128
	v_fmac_f32_e32 v154, v116, v128
	v_fmac_f32_e32 v155, v117, v128
	v_fmac_f32_e32 v156, v118, v128
	v_fmac_f32_e32 v157, v119, v128
	v_fmac_f32_e32 v158, v120, v128
	v_fmac_f32_e32 v159, v121, v128
	v_fmac_f32_e32 v160, v122, v128
	v_fmac_f32_e32 v161, v123, v128
	v_fmac_f32_e32 v162, v124, v128
	v_fmac_f32_e32 v163, v125, v128
	v_fmac_f32_e32 v164, v126, v128
	v_fmac_f32_e32 v165, v127, v128
	v_fmac_f32_e32 v172, v96, v133
	v_fmac_f32_e32 v173, v97, v133
	v_fmac_f32_e32 v174, v98, v133
	v_fmac_f32_e32 v175, v99, v133
	v_fmac_f32_e32 v176, v100, v133
	v_fmac_f32_e32 v177, v101, v133
	v_fmac_f32_e32 v178, v102, v133
	v_fmac_f32_e32 v179, v103, v133
	v_fmac_f32_e32 v180, v104, v133
	v_fmac_f32_e32 v181, v105, v133
	v_fmac_f32_e32 v182, v106, v133
	v_fmac_f32_e32 v183, v107, v133
	v_fmac_f32_e32 v184, v108, v133
	v_fmac_f32_e32 v185, v109, v133
	v_fmac_f32_e32 v186, v110, v133
	v_fmac_f32_e32 v187, v111, v133
	s_add_u32 s0, s68, 0x40000
	s_addc_u32 s1, s69, 0
	global_load_dword v112, v132, s[0:1]
	global_load_dword v96, v132, s[0:1] offset:128
	s_add_u32 s0, s68, 0x41000
	s_addc_u32 s1, s69, 0
	global_load_dword v113, v132, s[0:1]
	global_load_dword v97, v132, s[0:1] offset:128
	s_add_u32 s0, s68, 0x42000
	s_addc_u32 s1, s69, 0
	global_load_dword v114, v132, s[0:1]
	global_load_dword v98, v132, s[0:1] offset:128
	s_add_u32 s0, s68, 0x43000
	s_addc_u32 s1, s69, 0
	global_load_dword v115, v132, s[0:1]
	global_load_dword v99, v132, s[0:1] offset:128
	s_add_u32 s0, s68, 0x48000
	s_addc_u32 s1, s69, 0
	global_load_dword v116, v132, s[0:1]
	global_load_dword v100, v132, s[0:1] offset:128
	s_add_u32 s0, s68, 0x49000
	s_addc_u32 s1, s69, 0
	global_load_dword v117, v132, s[0:1]
	global_load_dword v101, v132, s[0:1] offset:128
	s_add_u32 s0, s68, 0x4a000
	s_addc_u32 s1, s69, 0
	global_load_dword v118, v132, s[0:1]
	global_load_dword v102, v132, s[0:1] offset:128
	s_add_u32 s0, s68, 0x4b000
	s_addc_u32 s1, s69, 0
	global_load_dword v119, v132, s[0:1]
	global_load_dword v103, v132, s[0:1] offset:128
	s_add_u32 s0, s68, 0x50000
	s_addc_u32 s1, s69, 0
	global_load_dword v120, v132, s[0:1]
	global_load_dword v104, v132, s[0:1] offset:128
	s_add_u32 s0, s68, 0x51000
	s_addc_u32 s1, s69, 0
	global_load_dword v121, v132, s[0:1]
	global_load_dword v105, v132, s[0:1] offset:128
	s_add_u32 s0, s68, 0x52000
	s_addc_u32 s1, s69, 0
	global_load_dword v122, v132, s[0:1]
	global_load_dword v106, v132, s[0:1] offset:128
	s_add_u32 s0, s68, 0x53000
	s_addc_u32 s1, s69, 0
	global_load_dword v123, v132, s[0:1]
	global_load_dword v107, v132, s[0:1] offset:128
	s_add_u32 s0, s68, 0x58000
	s_addc_u32 s1, s69, 0
	global_load_dword v124, v132, s[0:1]
	global_load_dword v108, v132, s[0:1] offset:128
	s_add_u32 s0, s68, 0x59000
	s_addc_u32 s1, s69, 0
	global_load_dword v125, v132, s[0:1]
	global_load_dword v109, v132, s[0:1] offset:128
	s_add_u32 s0, s68, 0x5a000
	s_addc_u32 s1, s69, 0
	global_load_dword v126, v132, s[0:1]
	global_load_dword v110, v132, s[0:1] offset:128
	s_add_u32 s0, s68, 0x5b000
	s_addc_u32 s1, s69, 0
	global_load_dword v127, v132, s[0:1]
	global_load_dword v111, v132, s[0:1] offset:128
	s_waitcnt vmcnt(32)
	v_fmac_f32_e32 v188, v80, v128
	v_fmac_f32_e32 v189, v81, v128
	v_fmac_f32_e32 v190, v82, v128
	v_fmac_f32_e32 v191, v83, v128
	v_fmac_f32_e32 v192, v84, v128
	v_fmac_f32_e32 v193, v85, v128
	v_fmac_f32_e32 v194, v86, v128
	v_fmac_f32_e32 v195, v87, v128
	v_fmac_f32_e32 v196, v88, v128
	v_fmac_f32_e32 v197, v89, v128
	v_fmac_f32_e32 v198, v90, v128
	v_fmac_f32_e32 v199, v91, v128
	v_fmac_f32_e32 v200, v92, v128
	v_fmac_f32_e32 v201, v93, v128
	v_fmac_f32_e32 v202, v94, v128
	v_fmac_f32_e32 v203, v95, v128
	v_fmac_f32_e32 v204, v64, v133
	v_fmac_f32_e32 v205, v65, v133
	v_fmac_f32_e32 v206, v66, v133
	v_fmac_f32_e32 v207, v67, v133
	v_fmac_f32_e32 v208, v68, v133
	v_fmac_f32_e32 v209, v69, v133
	v_fmac_f32_e32 v210, v70, v133
	v_fmac_f32_e32 v211, v71, v133
	v_fmac_f32_e32 v212, v72, v133
	v_fmac_f32_e32 v213, v73, v133
	v_fmac_f32_e32 v214, v74, v133
	v_fmac_f32_e32 v215, v75, v133
	v_fmac_f32_e32 v216, v76, v133
	v_fmac_f32_e32 v217, v77, v133
	v_fmac_f32_e32 v218, v78, v133
	v_fmac_f32_e32 v219, v79, v133
	s_add_u32 s0, s68, 0x60000
	s_addc_u32 s1, s69, 0
	global_load_dword v80, v132, s[0:1]
	global_load_dword v64, v132, s[0:1] offset:128
	s_add_u32 s0, s68, 0x61000
	s_addc_u32 s1, s69, 0
	global_load_dword v81, v132, s[0:1]
	global_load_dword v65, v132, s[0:1] offset:128
	s_add_u32 s0, s68, 0x62000
	s_addc_u32 s1, s69, 0
	global_load_dword v82, v132, s[0:1]
	global_load_dword v66, v132, s[0:1] offset:128
	s_add_u32 s0, s68, 0x63000
	s_addc_u32 s1, s69, 0
	global_load_dword v83, v132, s[0:1]
	global_load_dword v67, v132, s[0:1] offset:128
	s_add_u32 s0, s68, 0x68000
	s_addc_u32 s1, s69, 0
	global_load_dword v84, v132, s[0:1]
	global_load_dword v68, v132, s[0:1] offset:128
	s_add_u32 s0, s68, 0x69000
	s_addc_u32 s1, s69, 0
	global_load_dword v85, v132, s[0:1]
	global_load_dword v69, v132, s[0:1] offset:128
	s_add_u32 s0, s68, 0x6a000
	s_addc_u32 s1, s69, 0
	global_load_dword v86, v132, s[0:1]
	global_load_dword v70, v132, s[0:1] offset:128
	s_add_u32 s0, s68, 0x6b000
	s_addc_u32 s1, s69, 0
	global_load_dword v87, v132, s[0:1]
	global_load_dword v71, v132, s[0:1] offset:128
	s_add_u32 s0, s68, 0x70000
	s_addc_u32 s1, s69, 0
	global_load_dword v88, v132, s[0:1]
	global_load_dword v72, v132, s[0:1] offset:128
	s_add_u32 s0, s68, 0x71000
	s_addc_u32 s1, s69, 0
	global_load_dword v89, v132, s[0:1]
	global_load_dword v73, v132, s[0:1] offset:128
	s_add_u32 s0, s68, 0x72000
	s_addc_u32 s1, s69, 0
	global_load_dword v90, v132, s[0:1]
	global_load_dword v74, v132, s[0:1] offset:128
	s_add_u32 s0, s68, 0x73000
	s_addc_u32 s1, s69, 0
	global_load_dword v91, v132, s[0:1]
	global_load_dword v75, v132, s[0:1] offset:128
	s_add_u32 s0, s68, 0x78000
	s_addc_u32 s1, s69, 0
	global_load_dword v92, v132, s[0:1]
	global_load_dword v76, v132, s[0:1] offset:128
	s_add_u32 s0, s68, 0x79000
	s_addc_u32 s1, s69, 0
	global_load_dword v93, v132, s[0:1]
	global_load_dword v77, v132, s[0:1] offset:128
	s_add_u32 s0, s68, 0x7a000
	s_addc_u32 s1, s69, 0
	global_load_dword v94, v132, s[0:1]
	global_load_dword v78, v132, s[0:1] offset:128
	s_add_u32 s0, s68, 0x7b000
	s_addc_u32 s1, s69, 0
	global_load_dword v95, v132, s[0:1]
	global_load_dword v79, v132, s[0:1] offset:128
	s_waitcnt vmcnt(32)
	v_fmac_f32_e32 v112, v48, v128
	v_fmac_f32_e32 v113, v49, v128
	v_fmac_f32_e32 v114, v50, v128
	v_fmac_f32_e32 v115, v51, v128
	v_fmac_f32_e32 v116, v52, v128
	v_fmac_f32_e32 v117, v53, v128
	v_fmac_f32_e32 v118, v54, v128
	v_fmac_f32_e32 v119, v55, v128
	v_fmac_f32_e32 v120, v56, v128
	v_fmac_f32_e32 v121, v57, v128
	v_fmac_f32_e32 v122, v58, v128
	v_fmac_f32_e32 v123, v59, v128
	v_fmac_f32_e32 v124, v60, v128
	v_fmac_f32_e32 v125, v61, v128
	v_fmac_f32_e32 v126, v62, v128
	v_fmac_f32_e32 v127, v63, v128
	v_fmac_f32_e32 v96, v32, v133
	v_fmac_f32_e32 v97, v33, v133
	v_fmac_f32_e32 v98, v34, v133
	v_fmac_f32_e32 v99, v35, v133
	v_fmac_f32_e32 v100, v36, v133
	v_fmac_f32_e32 v101, v37, v133
	v_fmac_f32_e32 v102, v38, v133
	v_fmac_f32_e32 v103, v39, v133
	v_fmac_f32_e32 v104, v40, v133
	v_fmac_f32_e32 v105, v41, v133
	v_fmac_f32_e32 v106, v42, v133
	v_fmac_f32_e32 v107, v43, v133
	v_fmac_f32_e32 v108, v44, v133
	v_fmac_f32_e32 v109, v45, v133
	v_fmac_f32_e32 v110, v46, v133
	v_fmac_f32_e32 v111, v47, v133
	s_waitcnt vmcnt(0)
	v_fmac_f32_e32 v80, v16, v128
	v_fmac_f32_e32 v81, v17, v128
	v_fmac_f32_e32 v82, v18, v128
	v_fmac_f32_e32 v83, v19, v128
	v_fmac_f32_e32 v84, v20, v128
	v_fmac_f32_e32 v85, v21, v128
	v_fmac_f32_e32 v86, v22, v128
	v_fmac_f32_e32 v87, v23, v128
	v_fmac_f32_e32 v88, v24, v128
	v_fmac_f32_e32 v89, v25, v128
	v_fmac_f32_e32 v90, v26, v128
	v_fmac_f32_e32 v91, v27, v128
	v_fmac_f32_e32 v92, v28, v128
	v_fmac_f32_e32 v93, v29, v128
	v_fmac_f32_e32 v94, v30, v128
	v_fmac_f32_e32 v95, v31, v128
	v_fmac_f32_e32 v64, v0, v133
	v_fmac_f32_e32 v65, v1, v133
	v_fmac_f32_e32 v66, v2, v133
	v_fmac_f32_e32 v67, v3, v133
	v_fmac_f32_e32 v68, v4, v133
	v_fmac_f32_e32 v69, v5, v133
	v_fmac_f32_e32 v70, v6, v133
	v_fmac_f32_e32 v71, v7, v133
	v_fmac_f32_e32 v72, v8, v133
	v_fmac_f32_e32 v73, v9, v133
	v_fmac_f32_e32 v74, v10, v133
	v_fmac_f32_e32 v75, v11, v133
	v_fmac_f32_e32 v76, v12, v133
	v_fmac_f32_e32 v77, v13, v133
	v_fmac_f32_e32 v78, v14, v133
	v_fmac_f32_e32 v79, v15, v133
	s_mov_b32 s0, s68
	s_mov_b32 s1, s69
	global_store_dword v132, v150, s[0:1]
	global_store_dword v132, v172, s[0:1] offset:128
	s_add_u32 s0, s68, 0x1000
	s_addc_u32 s1, s69, 0
	global_store_dword v132, v151, s[0:1]
	global_store_dword v132, v173, s[0:1] offset:128
	s_add_u32 s0, s68, 0x2000
	s_addc_u32 s1, s69, 0
	global_store_dword v132, v152, s[0:1]
	global_store_dword v132, v174, s[0:1] offset:128
	s_add_u32 s0, s68, 0x3000
	s_addc_u32 s1, s69, 0
	global_store_dword v132, v153, s[0:1]
	global_store_dword v132, v175, s[0:1] offset:128
	s_add_u32 s0, s68, 0x8000
	s_addc_u32 s1, s69, 0
	global_store_dword v132, v154, s[0:1]
	global_store_dword v132, v176, s[0:1] offset:128
	s_add_u32 s0, s68, 0x9000
	s_addc_u32 s1, s69, 0
	global_store_dword v132, v155, s[0:1]
	global_store_dword v132, v177, s[0:1] offset:128
	s_add_u32 s0, s68, 0xa000
	s_addc_u32 s1, s69, 0
	global_store_dword v132, v156, s[0:1]
	global_store_dword v132, v178, s[0:1] offset:128
	s_add_u32 s0, s68, 0xb000
	s_addc_u32 s1, s69, 0
	global_store_dword v132, v157, s[0:1]
	global_store_dword v132, v179, s[0:1] offset:128
	s_add_u32 s0, s68, 0x10000
	s_addc_u32 s1, s69, 0
	global_store_dword v132, v158, s[0:1]
	global_store_dword v132, v180, s[0:1] offset:128
	s_add_u32 s0, s68, 0x11000
	s_addc_u32 s1, s69, 0
	global_store_dword v132, v159, s[0:1]
	global_store_dword v132, v181, s[0:1] offset:128
	s_add_u32 s0, s68, 0x12000
	s_addc_u32 s1, s69, 0
	global_store_dword v132, v160, s[0:1]
	global_store_dword v132, v182, s[0:1] offset:128
	s_add_u32 s0, s68, 0x13000
	s_addc_u32 s1, s69, 0
	global_store_dword v132, v161, s[0:1]
	global_store_dword v132, v183, s[0:1] offset:128
	s_add_u32 s0, s68, 0x18000
	s_addc_u32 s1, s69, 0
	global_store_dword v132, v162, s[0:1]
	global_store_dword v132, v184, s[0:1] offset:128
	s_add_u32 s0, s68, 0x19000
	s_addc_u32 s1, s69, 0
	global_store_dword v132, v163, s[0:1]
	global_store_dword v132, v185, s[0:1] offset:128
	s_add_u32 s0, s68, 0x1a000
	s_addc_u32 s1, s69, 0
	global_store_dword v132, v164, s[0:1]
	global_store_dword v132, v186, s[0:1] offset:128
	s_add_u32 s0, s68, 0x1b000
	s_addc_u32 s1, s69, 0
	global_store_dword v132, v165, s[0:1]
	global_store_dword v132, v187, s[0:1] offset:128
	s_add_u32 s0, s68, 0x20000
	s_addc_u32 s1, s69, 0
	global_store_dword v132, v188, s[0:1]
	global_store_dword v132, v204, s[0:1] offset:128
	s_add_u32 s0, s68, 0x21000
	s_addc_u32 s1, s69, 0
	global_store_dword v132, v189, s[0:1]
	global_store_dword v132, v205, s[0:1] offset:128
	s_add_u32 s0, s68, 0x22000
	s_addc_u32 s1, s69, 0
	global_store_dword v132, v190, s[0:1]
	global_store_dword v132, v206, s[0:1] offset:128
	s_add_u32 s0, s68, 0x23000
	s_addc_u32 s1, s69, 0
	global_store_dword v132, v191, s[0:1]
	global_store_dword v132, v207, s[0:1] offset:128
	s_add_u32 s0, s68, 0x28000
	s_addc_u32 s1, s69, 0
	global_store_dword v132, v192, s[0:1]
	global_store_dword v132, v208, s[0:1] offset:128
	s_add_u32 s0, s68, 0x29000
	s_addc_u32 s1, s69, 0
	global_store_dword v132, v193, s[0:1]
	global_store_dword v132, v209, s[0:1] offset:128
	s_add_u32 s0, s68, 0x2a000
	s_addc_u32 s1, s69, 0
	global_store_dword v132, v194, s[0:1]
	global_store_dword v132, v210, s[0:1] offset:128
	s_add_u32 s0, s68, 0x2b000
	s_addc_u32 s1, s69, 0
	global_store_dword v132, v195, s[0:1]
	global_store_dword v132, v211, s[0:1] offset:128
	s_add_u32 s0, s68, 0x30000
	s_addc_u32 s1, s69, 0
	global_store_dword v132, v196, s[0:1]
	global_store_dword v132, v212, s[0:1] offset:128
	s_add_u32 s0, s68, 0x31000
	s_addc_u32 s1, s69, 0
	global_store_dword v132, v197, s[0:1]
	global_store_dword v132, v213, s[0:1] offset:128
	s_add_u32 s0, s68, 0x32000
	s_addc_u32 s1, s69, 0
	global_store_dword v132, v198, s[0:1]
	global_store_dword v132, v214, s[0:1] offset:128
	s_add_u32 s0, s68, 0x33000
	s_addc_u32 s1, s69, 0
	global_store_dword v132, v199, s[0:1]
	global_store_dword v132, v215, s[0:1] offset:128
	s_add_u32 s0, s68, 0x38000
	s_addc_u32 s1, s69, 0
	global_store_dword v132, v200, s[0:1]
	global_store_dword v132, v216, s[0:1] offset:128
	s_add_u32 s0, s68, 0x39000
	s_addc_u32 s1, s69, 0
	global_store_dword v132, v201, s[0:1]
	global_store_dword v132, v217, s[0:1] offset:128
	s_add_u32 s0, s68, 0x3a000
	s_addc_u32 s1, s69, 0
	global_store_dword v132, v202, s[0:1]
	global_store_dword v132, v218, s[0:1] offset:128
	s_add_u32 s0, s68, 0x3b000
	s_addc_u32 s1, s69, 0
	global_store_dword v132, v203, s[0:1]
	global_store_dword v132, v219, s[0:1] offset:128
	s_add_u32 s0, s68, 0x40000
	s_addc_u32 s1, s69, 0
	global_store_dword v132, v112, s[0:1]
	global_store_dword v132, v96, s[0:1] offset:128
	s_add_u32 s0, s68, 0x41000
	s_addc_u32 s1, s69, 0
	global_store_dword v132, v113, s[0:1]
	global_store_dword v132, v97, s[0:1] offset:128
	s_add_u32 s0, s68, 0x42000
	s_addc_u32 s1, s69, 0
	global_store_dword v132, v114, s[0:1]
	global_store_dword v132, v98, s[0:1] offset:128
	s_add_u32 s0, s68, 0x43000
	s_addc_u32 s1, s69, 0
	global_store_dword v132, v115, s[0:1]
	global_store_dword v132, v99, s[0:1] offset:128
	s_add_u32 s0, s68, 0x48000
	s_addc_u32 s1, s69, 0
	global_store_dword v132, v116, s[0:1]
	global_store_dword v132, v100, s[0:1] offset:128
	s_add_u32 s0, s68, 0x49000
	s_addc_u32 s1, s69, 0
	global_store_dword v132, v117, s[0:1]
	global_store_dword v132, v101, s[0:1] offset:128
	s_add_u32 s0, s68, 0x4a000
	s_addc_u32 s1, s69, 0
	global_store_dword v132, v118, s[0:1]
	global_store_dword v132, v102, s[0:1] offset:128
	s_add_u32 s0, s68, 0x4b000
	s_addc_u32 s1, s69, 0
	global_store_dword v132, v119, s[0:1]
	global_store_dword v132, v103, s[0:1] offset:128
	s_add_u32 s0, s68, 0x50000
	s_addc_u32 s1, s69, 0
	global_store_dword v132, v120, s[0:1]
	global_store_dword v132, v104, s[0:1] offset:128
	s_add_u32 s0, s68, 0x51000
	s_addc_u32 s1, s69, 0
	global_store_dword v132, v121, s[0:1]
	global_store_dword v132, v105, s[0:1] offset:128
	s_add_u32 s0, s68, 0x52000
	s_addc_u32 s1, s69, 0
	global_store_dword v132, v122, s[0:1]
	global_store_dword v132, v106, s[0:1] offset:128
	s_add_u32 s0, s68, 0x53000
	s_addc_u32 s1, s69, 0
	global_store_dword v132, v123, s[0:1]
	global_store_dword v132, v107, s[0:1] offset:128
	s_add_u32 s0, s68, 0x58000
	s_addc_u32 s1, s69, 0
	global_store_dword v132, v124, s[0:1]
	global_store_dword v132, v108, s[0:1] offset:128
	s_add_u32 s0, s68, 0x59000
	s_addc_u32 s1, s69, 0
	global_store_dword v132, v125, s[0:1]
	global_store_dword v132, v109, s[0:1] offset:128
	s_add_u32 s0, s68, 0x5a000
	s_addc_u32 s1, s69, 0
	global_store_dword v132, v126, s[0:1]
	global_store_dword v132, v110, s[0:1] offset:128
	s_add_u32 s0, s68, 0x5b000
	s_addc_u32 s1, s69, 0
	global_store_dword v132, v127, s[0:1]
	global_store_dword v132, v111, s[0:1] offset:128
	s_add_u32 s0, s68, 0x60000
	s_addc_u32 s1, s69, 0
	global_store_dword v132, v80, s[0:1]
	global_store_dword v132, v64, s[0:1] offset:128
	s_add_u32 s0, s68, 0x61000
	s_addc_u32 s1, s69, 0
	global_store_dword v132, v81, s[0:1]
	global_store_dword v132, v65, s[0:1] offset:128
	s_add_u32 s0, s68, 0x62000
	s_addc_u32 s1, s69, 0
	global_store_dword v132, v82, s[0:1]
	global_store_dword v132, v66, s[0:1] offset:128
	s_add_u32 s0, s68, 0x63000
	s_addc_u32 s1, s69, 0
	global_store_dword v132, v83, s[0:1]
	global_store_dword v132, v67, s[0:1] offset:128
	s_add_u32 s0, s68, 0x68000
	s_addc_u32 s1, s69, 0
	global_store_dword v132, v84, s[0:1]
	global_store_dword v132, v68, s[0:1] offset:128
	s_add_u32 s0, s68, 0x69000
	s_addc_u32 s1, s69, 0
	global_store_dword v132, v85, s[0:1]
	global_store_dword v132, v69, s[0:1] offset:128
	s_add_u32 s0, s68, 0x6a000
	s_addc_u32 s1, s69, 0
	global_store_dword v132, v86, s[0:1]
	global_store_dword v132, v70, s[0:1] offset:128
	s_add_u32 s0, s68, 0x6b000
	s_addc_u32 s1, s69, 0
	global_store_dword v132, v87, s[0:1]
	global_store_dword v132, v71, s[0:1] offset:128
	s_add_u32 s0, s68, 0x70000
	s_addc_u32 s1, s69, 0
	global_store_dword v132, v88, s[0:1]
	global_store_dword v132, v72, s[0:1] offset:128
	s_add_u32 s0, s68, 0x71000
	s_addc_u32 s1, s69, 0
	global_store_dword v132, v89, s[0:1]
	global_store_dword v132, v73, s[0:1] offset:128
	s_add_u32 s0, s68, 0x72000
	s_addc_u32 s1, s69, 0
	global_store_dword v132, v90, s[0:1]
	global_store_dword v132, v74, s[0:1] offset:128
	s_add_u32 s0, s68, 0x73000
	s_addc_u32 s1, s69, 0
	global_store_dword v132, v91, s[0:1]
	global_store_dword v132, v75, s[0:1] offset:128
	s_add_u32 s0, s68, 0x78000
	s_addc_u32 s1, s69, 0
	global_store_dword v132, v92, s[0:1]
	global_store_dword v132, v76, s[0:1] offset:128
	s_add_u32 s0, s68, 0x79000
	s_addc_u32 s1, s69, 0
	global_store_dword v132, v93, s[0:1]
	global_store_dword v132, v77, s[0:1] offset:128
	s_add_u32 s0, s68, 0x7a000
	s_addc_u32 s1, s69, 0
	global_store_dword v132, v94, s[0:1]
	global_store_dword v132, v78, s[0:1] offset:128
	s_add_u32 s0, s68, 0x7b000
	s_addc_u32 s1, s69, 0
	global_store_dword v132, v95, s[0:1]
	global_store_dword v132, v79, s[0:1] offset:128
	s_andn2_b64 exec, exec, s[46:47]
	s_cbranch_execz .LBB0_237

.LBB0_267:
	s_and_b64 s[0:1], exec, s[36:37]
	s_or_b64 s[52:53], s[0:1], s[52:53]
	s_andn2_b64 exec, exec, s[52:53]
	s_cbranch_execz .LBB0_792

.LBB0_280:
	s_or_b64 exec, exec, s[0:1]
	v_add_u32_e32 v131, v130, v169
	ds_read_b128 v[132:135], v131
	ds_read_b128 v[136:139], v131 offset:4096
	ds_read_b128 v[140:143], v131 offset:8192
	ds_read_b128 v[144:147], v131 offset:12288
	v_add_u32_e32 v131, v128, v169
	ds_read_b128 v[148:151], v131 offset:32768
	ds_read_b128 v[152:155], v131 offset:36864
	s_setprio 1
	s_waitcnt lgkmcnt(0)
	v_mfma_f32_32x32x16_bf16 v[112:127], v[132:135], v[148:151], v[112:127]
	v_mfma_f32_32x32x16_bf16 v[96:111], v[132:135], v[152:155], v[96:111]
	v_mfma_f32_32x32x16_bf16 v[80:95], v[136:139], v[148:151], v[80:95]
	v_mfma_f32_32x32x16_bf16 v[64:79], v[136:139], v[152:155], v[64:79]
	v_mfma_f32_32x32x16_bf16 v[48:63], v[140:143], v[148:151], v[48:63]
	v_mfma_f32_32x32x16_bf16 v[32:47], v[140:143], v[152:155], v[32:47]
	v_mfma_f32_32x32x16_bf16 v[16:31], v[144:147], v[148:151], v[16:31]
	v_mfma_f32_32x32x16_bf16 v[0:15], v[144:147], v[152:155], v[0:15]
	s_setprio 0
	v_add_u32_e32 v142, v130, v168
	ds_read_b128 v[130:133], v142
	ds_read_b128 v[134:137], v142 offset:4096
	ds_read_b128 v[138:141], v142 offset:8192
	ds_read_b128 v[142:145], v142 offset:12288
	v_add_u32_e32 v128, v128, v168
	ds_read_b128 v[146:149], v128 offset:32768
	ds_read_b128 v[150:153], v128 offset:36864
	s_setprio 1
	s_waitcnt lgkmcnt(0)
	v_mfma_f32_32x32x16_bf16 v[112:127], v[130:133], v[146:149], v[112:127]
	v_mfma_f32_32x32x16_bf16 v[96:111], v[130:133], v[150:153], v[96:111]
	v_mfma_f32_32x32x16_bf16 v[80:95], v[134:137], v[146:149], v[80:95]
	v_mfma_f32_32x32x16_bf16 v[64:79], v[134:137], v[150:153], v[64:79]
	v_mfma_f32_32x32x16_bf16 v[48:63], v[138:141], v[146:149], v[48:63]
	v_mfma_f32_32x32x16_bf16 v[32:47], v[138:141], v[150:153], v[32:47]
	v_mfma_f32_32x32x16_bf16 v[16:31], v[142:145], v[146:149], v[16:31]
	v_mfma_f32_32x32x16_bf16 v[0:15], v[142:145], v[150:153], v[0:15]
	s_setprio 0
	s_mov_b64 s[38:39], s[68:69]
	s_and_b64 vcc, exec, s[18:19]
	s_cbranch_vccnz .Lg4_src_done
	v_readfirstlane_b32 s0, v167
	s_nop 3
	s_cmp_lt_i32 s0, s33
	s_cselect_b32 s38, s76, s78
	s_cselect_b32 s39, s77, s79
	s_cbranch_scc1 .Lg4_src_done
	s_sub_u32 s38, s38, 0x2000000
	s_subb_u32 s39, s39, 0
.Lg4_src_done:
	v_add_u32_e32 v138, v167, v235
	v_or_b32_e32 v144, v166, v234
	v_lshlrev_b32_e32 v132, 12, v138
	v_lshl_add_u32 v132, v144, 2, v132
	v_readlane_b32 s1, v254, 62
	s_movk_i32 s0, 0x1fff
	v_add_u32_e32 v128, 0xffffe000, v167
	v_cmp_lt_i32_e32 vcc, s0, v167
	v_lshrrev_b32_e32 v128, 10, v128
	v_add_u32_e32 v128, 1, v128
	v_cndmask_b32_e32 v128, 0, v128, vcc
	v_mov_b64_e32 v[130:131], s[66:67]
	v_add_u32_e32 v128, s1, v128
	s_movk_i32 s0, 0x6000
	v_mad_u64_u32 v[130:131], s[0:1], v128, s0, v[130:131]
	s_mov_b64 s[0:1], 0x2000
	v_lshl_add_u64 v[130:131], v[130:131], 0, s[0:1]
	v_mov_b32_e32 v135, 0
	v_lshlrev_b32_e32 v134, 2, v144
	v_lshl_add_u64 v[130:131], v[130:131], 0, v[134:135]
	global_load_dword v128, v[130:131], off
	global_load_dword v133, v[130:131], off offset:128
	s_mov_b32 s0, s38
	s_mov_b32 s1, s39
	global_load_dword v150, v132, s[0:1]
	global_load_dword v172, v132, s[0:1] offset:128
	s_add_u32 s0, s38, 0x1000
	s_addc_u32 s1, s39, 0
	global_load_dword v151, v132, s[0:1]
	global_load_dword v173, v132, s[0:1] offset:128
	s_add_u32 s0, s38, 0x2000
	s_addc_u32 s1, s39, 0
	global_load_dword v152, v132, s[0:1]
	global_load_dword v174, v132, s[0:1] offset:128
	s_add_u32 s0, s38, 0x3000
	s_addc_u32 s1, s39, 0
	global_load_dword v153, v132, s[0:1]
	global_load_dword v175, v132, s[0:1] offset:128
	s_add_u32 s0, s38, 0x8000
	s_addc_u32 s1, s39, 0
	global_load_dword v154, v132, s[0:1]
	global_load_dword v176, v132, s[0:1] offset:128
	s_add_u32 s0, s38, 0x9000
	s_addc_u32 s1, s39, 0
	global_load_dword v155, v132, s[0:1]
	global_load_dword v177, v132, s[0:1] offset:128
	s_add_u32 s0, s38, 0xa000
	s_addc_u32 s1, s39, 0
	global_load_dword v156, v132, s[0:1]
	global_load_dword v178, v132, s[0:1] offset:128
	s_add_u32 s0, s38, 0xb000
	s_addc_u32 s1, s39, 0
	global_load_dword v157, v132, s[0:1]
	global_load_dword v179, v132, s[0:1] offset:128
	s_add_u32 s0, s38, 0x10000
	s_addc_u32 s1, s39, 0
	global_load_dword v158, v132, s[0:1]
	global_load_dword v180, v132, s[0:1] offset:128
	s_add_u32 s0, s38, 0x11000
	s_addc_u32 s1, s39, 0
	global_load_dword v159, v132, s[0:1]
	global_load_dword v181, v132, s[0:1] offset:128
	s_add_u32 s0, s38, 0x12000
	s_addc_u32 s1, s39, 0
	global_load_dword v160, v132, s[0:1]
	global_load_dword v182, v132, s[0:1] offset:128
	s_add_u32 s0, s38, 0x13000
	s_addc_u32 s1, s39, 0
	global_load_dword v161, v132, s[0:1]
	global_load_dword v183, v132, s[0:1] offset:128
	s_add_u32 s0, s38, 0x18000
	s_addc_u32 s1, s39, 0
	global_load_dword v162, v132, s[0:1]
	global_load_dword v184, v132, s[0:1] offset:128
	s_add_u32 s0, s38, 0x19000
	s_addc_u32 s1, s39, 0
	global_load_dword v163, v132, s[0:1]
	global_load_dword v185, v132, s[0:1] offset:128
	s_add_u32 s0, s38, 0x1a000
	s_addc_u32 s1, s39, 0
	global_load_dword v164, v132, s[0:1]
	global_load_dword v186, v132, s[0:1] offset:128
	s_add_u32 s0, s38, 0x1b000
	s_addc_u32 s1, s39, 0
	global_load_dword v165, v132, s[0:1]
	global_load_dword v187, v132, s[0:1] offset:128
	s_add_u32 s0, s38, 0x20000
	s_addc_u32 s1, s39, 0
	global_load_dword v188, v132, s[0:1]
	global_load_dword v204, v132, s[0:1] offset:128
	s_add_u32 s0, s38, 0x21000
	s_addc_u32 s1, s39, 0
	global_load_dword v189, v132, s[0:1]
	global_load_dword v205, v132, s[0:1] offset:128
	s_add_u32 s0, s38, 0x22000
	s_addc_u32 s1, s39, 0
	global_load_dword v190, v132, s[0:1]
	global_load_dword v206, v132, s[0:1] offset:128
	s_add_u32 s0, s38, 0x23000
	s_addc_u32 s1, s39, 0
	global_load_dword v191, v132, s[0:1]
	global_load_dword v207, v132, s[0:1] offset:128
	s_add_u32 s0, s38, 0x28000
	s_addc_u32 s1, s39, 0
	global_load_dword v192, v132, s[0:1]
	global_load_dword v208, v132, s[0:1] offset:128
	s_add_u32 s0, s38, 0x29000
	s_addc_u32 s1, s39, 0
	global_load_dword v193, v132, s[0:1]
	global_load_dword v209, v132, s[0:1] offset:128
	s_add_u32 s0, s38, 0x2a000
	s_addc_u32 s1, s39, 0
	global_load_dword v194, v132, s[0:1]
	global_load_dword v210, v132, s[0:1] offset:128
	s_add_u32 s0, s38, 0x2b000
	s_addc_u32 s1, s39, 0
	global_load_dword v195, v132, s[0:1]
	global_load_dword v211, v132, s[0:1] offset:128
	s_add_u32 s0, s38, 0x30000
	s_addc_u32 s1, s39, 0
	global_load_dword v196, v132, s[0:1]
	global_load_dword v212, v132, s[0:1] offset:128
	s_add_u32 s0, s38, 0x31000
	s_addc_u32 s1, s39, 0
	global_load_dword v197, v132, s[0:1]
	global_load_dword v213, v132, s[0:1] offset:128
	s_add_u32 s0, s38, 0x32000
	s_addc_u32 s1, s39, 0
	global_load_dword v198, v132, s[0:1]
	global_load_dword v214, v132, s[0:1] offset:128
	s_add_u32 s0, s38, 0x33000
	s_addc_u32 s1, s39, 0
	global_load_dword v199, v132, s[0:1]
	global_load_dword v215, v132, s[0:1] offset:128
	s_add_u32 s0, s38, 0x38000
	s_addc_u32 s1, s39, 0
	global_load_dword v200, v132, s[0:1]
	global_load_dword v216, v132, s[0:1] offset:128
	s_add_u32 s0, s38, 0x39000
	s_addc_u32 s1, s39, 0
	global_load_dword v201, v132, s[0:1]
	global_load_dword v217, v132, s[0:1] offset:128
	s_add_u32 s0, s38, 0x3a000
	s_addc_u32 s1, s39, 0
	global_load_dword v202, v132, s[0:1]
	global_load_dword v218, v132, s[0:1] offset:128
	s_add_u32 s0, s38, 0x3b000
	s_addc_u32 s1, s39, 0
	global_load_dword v203, v132, s[0:1]
	global_load_dword v219, v132, s[0:1] offset:128
	s_waitcnt vmcnt(32)
	v_fmac_f32_e32 v150, v112, v128
	v_fmac_f32_e32 v151, v113, v128
	v_fmac_f32_e32 v152, v114, v128
	v_fmac_f32_e32 v153, v115, v128
	v_fmac_f32_e32 v154, v116, v128
	v_fmac_f32_e32 v155, v117, v128
	v_fmac_f32_e32 v156, v118, v128
	v_fmac_f32_e32 v157, v119, v128
	v_fmac_f32_e32 v158, v120, v128
	v_fmac_f32_e32 v159, v121, v128
	v_fmac_f32_e32 v160, v122, v128
	v_fmac_f32_e32 v161, v123, v128
	v_fmac_f32_e32 v162, v124, v128
	v_fmac_f32_e32 v163, v125, v128
	v_fmac_f32_e32 v164, v126, v128
	v_fmac_f32_e32 v165, v127, v128
	v_fmac_f32_e32 v172, v96, v133
	v_fmac_f32_e32 v173, v97, v133
	v_fmac_f32_e32 v174, v98, v133
	v_fmac_f32_e32 v175, v99, v133
	v_fmac_f32_e32 v176, v100, v133
	v_fmac_f32_e32 v177, v101, v133
	v_fmac_f32_e32 v178, v102, v133
	v_fmac_f32_e32 v179, v103, v133
	v_fmac_f32_e32 v180, v104, v133
	v_fmac_f32_e32 v181, v105, v133
	v_fmac_f32_e32 v182, v106, v133
	v_fmac_f32_e32 v183, v107, v133
	v_fmac_f32_e32 v184, v108, v133
	v_fmac_f32_e32 v185, v109, v133
	v_fmac_f32_e32 v186, v110, v133
	v_fmac_f32_e32 v187, v111, v133
	s_add_u32 s0, s38, 0x40000
	s_addc_u32 s1, s39, 0
	global_load_dword v112, v132, s[0:1]
	global_load_dword v96, v132, s[0:1] offset:128
	s_add_u32 s0, s38, 0x41000
	s_addc_u32 s1, s39, 0
	global_load_dword v113, v132, s[0:1]
	global_load_dword v97, v132, s[0:1] offset:128
	s_add_u32 s0, s38, 0x42000
	s_addc_u32 s1, s39, 0
	global_load_dword v114, v132, s[0:1]
	global_load_dword v98, v132, s[0:1] offset:128
	s_add_u32 s0, s38, 0x43000
	s_addc_u32 s1, s39, 0
	global_load_dword v115, v132, s[0:1]
	global_load_dword v99, v132, s[0:1] offset:128
	s_add_u32 s0, s38, 0x48000
	s_addc_u32 s1, s39, 0
	global_load_dword v116, v132, s[0:1]
	global_load_dword v100, v132, s[0:1] offset:128
	s_add_u32 s0, s38, 0x49000
	s_addc_u32 s1, s39, 0
	global_load_dword v117, v132, s[0:1]
	global_load_dword v101, v132, s[0:1] offset:128
	s_add_u32 s0, s38, 0x4a000
	s_addc_u32 s1, s39, 0
	global_load_dword v118, v132, s[0:1]
	global_load_dword v102, v132, s[0:1] offset:128
	s_add_u32 s0, s38, 0x4b000
	s_addc_u32 s1, s39, 0
	global_load_dword v119, v132, s[0:1]
	global_load_dword v103, v132, s[0:1] offset:128
	s_add_u32 s0, s38, 0x50000
	s_addc_u32 s1, s39, 0
	global_load_dword v120, v132, s[0:1]
	global_load_dword v104, v132, s[0:1] offset:128
	s_add_u32 s0, s38, 0x51000
	s_addc_u32 s1, s39, 0
	global_load_dword v121, v132, s[0:1]
	global_load_dword v105, v132, s[0:1] offset:128
	s_add_u32 s0, s38, 0x52000
	s_addc_u32 s1, s39, 0
	global_load_dword v122, v132, s[0:1]
	global_load_dword v106, v132, s[0:1] offset:128
	s_add_u32 s0, s38, 0x53000
	s_addc_u32 s1, s39, 0
	global_load_dword v123, v132, s[0:1]
	global_load_dword v107, v132, s[0:1] offset:128
	s_add_u32 s0, s38, 0x58000
	s_addc_u32 s1, s39, 0
	global_load_dword v124, v132, s[0:1]
	global_load_dword v108, v132, s[0:1] offset:128
	s_add_u32 s0, s38, 0x59000
	s_addc_u32 s1, s39, 0
	global_load_dword v125, v132, s[0:1]
	global_load_dword v109, v132, s[0:1] offset:128
	s_add_u32 s0, s38, 0x5a000
	s_addc_u32 s1, s39, 0
	global_load_dword v126, v132, s[0:1]
	global_load_dword v110, v132, s[0:1] offset:128
	s_add_u32 s0, s38, 0x5b000
	s_addc_u32 s1, s39, 0
	global_load_dword v127, v132, s[0:1]
	global_load_dword v111, v132, s[0:1] offset:128
	s_waitcnt vmcnt(32)
	v_fmac_f32_e32 v188, v80, v128
	v_fmac_f32_e32 v189, v81, v128
	v_fmac_f32_e32 v190, v82, v128
	v_fmac_f32_e32 v191, v83, v128
	v_fmac_f32_e32 v192, v84, v128
	v_fmac_f32_e32 v193, v85, v128
	v_fmac_f32_e32 v194, v86, v128
	v_fmac_f32_e32 v195, v87, v128
	v_fmac_f32_e32 v196, v88, v128
	v_fmac_f32_e32 v197, v89, v128
	v_fmac_f32_e32 v198, v90, v128
	v_fmac_f32_e32 v199, v91, v128
	v_fmac_f32_e32 v200, v92, v128
	v_fmac_f32_e32 v201, v93, v128
	v_fmac_f32_e32 v202, v94, v128
	v_fmac_f32_e32 v203, v95, v128
	v_fmac_f32_e32 v204, v64, v133
	v_fmac_f32_e32 v205, v65, v133
	v_fmac_f32_e32 v206, v66, v133
	v_fmac_f32_e32 v207, v67, v133
	v_fmac_f32_e32 v208, v68, v133
	v_fmac_f32_e32 v209, v69, v133
	v_fmac_f32_e32 v210, v70, v133
	v_fmac_f32_e32 v211, v71, v133
	v_fmac_f32_e32 v212, v72, v133
	v_fmac_f32_e32 v213, v73, v133
	v_fmac_f32_e32 v214, v74, v133
	v_fmac_f32_e32 v215, v75, v133
	v_fmac_f32_e32 v216, v76, v133
	v_fmac_f32_e32 v217, v77, v133
	v_fmac_f32_e32 v218, v78, v133
	v_fmac_f32_e32 v219, v79, v133
	s_add_u32 s0, s38, 0x60000
	s_addc_u32 s1, s39, 0
	global_load_dword v80, v132, s[0:1]
	global_load_dword v64, v132, s[0:1] offset:128
	s_add_u32 s0, s38, 0x61000
	s_addc_u32 s1, s39, 0
	global_load_dword v81, v132, s[0:1]
	global_load_dword v65, v132, s[0:1] offset:128
	s_add_u32 s0, s38, 0x62000
	s_addc_u32 s1, s39, 0
	global_load_dword v82, v132, s[0:1]
	global_load_dword v66, v132, s[0:1] offset:128
	s_add_u32 s0, s38, 0x63000
	s_addc_u32 s1, s39, 0
	global_load_dword v83, v132, s[0:1]
	global_load_dword v67, v132, s[0:1] offset:128
	s_add_u32 s0, s38, 0x68000
	s_addc_u32 s1, s39, 0
	global_load_dword v84, v132, s[0:1]
	global_load_dword v68, v132, s[0:1] offset:128
	s_add_u32 s0, s38, 0x69000
	s_addc_u32 s1, s39, 0
	global_load_dword v85, v132, s[0:1]
	global_load_dword v69, v132, s[0:1] offset:128
	s_add_u32 s0, s38, 0x6a000
	s_addc_u32 s1, s39, 0
	global_load_dword v86, v132, s[0:1]
	global_load_dword v70, v132, s[0:1] offset:128
	s_add_u32 s0, s38, 0x6b000
	s_addc_u32 s1, s39, 0
	global_load_dword v87, v132, s[0:1]
	global_load_dword v71, v132, s[0:1] offset:128
	s_add_u32 s0, s38, 0x70000
	s_addc_u32 s1, s39, 0
	global_load_dword v88, v132, s[0:1]
	global_load_dword v72, v132, s[0:1] offset:128
	s_add_u32 s0, s38, 0x71000
	s_addc_u32 s1, s39, 0
	global_load_dword v89, v132, s[0:1]
	global_load_dword v73, v132, s[0:1] offset:128
	s_add_u32 s0, s38, 0x72000
	s_addc_u32 s1, s39, 0
	global_load_dword v90, v132, s[0:1]
	global_load_dword v74, v132, s[0:1] offset:128
	s_add_u32 s0, s38, 0x73000
	s_addc_u32 s1, s39, 0
	global_load_dword v91, v132, s[0:1]
	global_load_dword v75, v132, s[0:1] offset:128
	s_add_u32 s0, s38, 0x78000
	s_addc_u32 s1, s39, 0
	global_load_dword v92, v132, s[0:1]
	global_load_dword v76, v132, s[0:1] offset:128
	s_add_u32 s0, s38, 0x79000
	s_addc_u32 s1, s39, 0
	global_load_dword v93, v132, s[0:1]
	global_load_dword v77, v132, s[0:1] offset:128
	s_add_u32 s0, s38, 0x7a000
	s_addc_u32 s1, s39, 0
	global_load_dword v94, v132, s[0:1]
	global_load_dword v78, v132, s[0:1] offset:128
	s_add_u32 s0, s38, 0x7b000
	s_addc_u32 s1, s39, 0
	global_load_dword v95, v132, s[0:1]
	global_load_dword v79, v132, s[0:1] offset:128
	s_waitcnt vmcnt(32)
	v_fmac_f32_e32 v112, v48, v128
	v_fmac_f32_e32 v113, v49, v128
	v_fmac_f32_e32 v114, v50, v128
	v_fmac_f32_e32 v115, v51, v128
	v_fmac_f32_e32 v116, v52, v128
	v_fmac_f32_e32 v117, v53, v128
	v_fmac_f32_e32 v118, v54, v128
	v_fmac_f32_e32 v119, v55, v128
	v_fmac_f32_e32 v120, v56, v128
	v_fmac_f32_e32 v121, v57, v128
	v_fmac_f32_e32 v122, v58, v128
	v_fmac_f32_e32 v123, v59, v128
	v_fmac_f32_e32 v124, v60, v128
	v_fmac_f32_e32 v125, v61, v128
	v_fmac_f32_e32 v126, v62, v128
	v_fmac_f32_e32 v127, v63, v128
	v_fmac_f32_e32 v96, v32, v133
	v_fmac_f32_e32 v97, v33, v133
	v_fmac_f32_e32 v98, v34, v133
	v_fmac_f32_e32 v99, v35, v133
	v_fmac_f32_e32 v100, v36, v133
	v_fmac_f32_e32 v101, v37, v133
	v_fmac_f32_e32 v102, v38, v133
	v_fmac_f32_e32 v103, v39, v133
	v_fmac_f32_e32 v104, v40, v133
	v_fmac_f32_e32 v105, v41, v133
	v_fmac_f32_e32 v106, v42, v133
	v_fmac_f32_e32 v107, v43, v133
	v_fmac_f32_e32 v108, v44, v133
	v_fmac_f32_e32 v109, v45, v133
	v_fmac_f32_e32 v110, v46, v133
	v_fmac_f32_e32 v111, v47, v133
	s_waitcnt vmcnt(0)
	v_fmac_f32_e32 v80, v16, v128
	v_fmac_f32_e32 v81, v17, v128
	v_fmac_f32_e32 v82, v18, v128
	v_fmac_f32_e32 v83, v19, v128
	v_fmac_f32_e32 v84, v20, v128
	v_fmac_f32_e32 v85, v21, v128
	v_fmac_f32_e32 v86, v22, v128
	v_fmac_f32_e32 v87, v23, v128
	v_fmac_f32_e32 v88, v24, v128
	v_fmac_f32_e32 v89, v25, v128
	v_fmac_f32_e32 v90, v26, v128
	v_fmac_f32_e32 v91, v27, v128
	v_fmac_f32_e32 v92, v28, v128
	v_fmac_f32_e32 v93, v29, v128
	v_fmac_f32_e32 v94, v30, v128
	v_fmac_f32_e32 v95, v31, v128
	v_fmac_f32_e32 v64, v0, v133
	v_fmac_f32_e32 v65, v1, v133
	v_fmac_f32_e32 v66, v2, v133
	v_fmac_f32_e32 v67, v3, v133
	v_fmac_f32_e32 v68, v4, v133
	v_fmac_f32_e32 v69, v5, v133
	v_fmac_f32_e32 v70, v6, v133
	v_fmac_f32_e32 v71, v7, v133
	v_fmac_f32_e32 v72, v8, v133
	v_fmac_f32_e32 v73, v9, v133
	v_fmac_f32_e32 v74, v10, v133
	v_fmac_f32_e32 v75, v11, v133
	v_fmac_f32_e32 v76, v12, v133
	v_fmac_f32_e32 v77, v13, v133
	v_fmac_f32_e32 v78, v14, v133
	v_fmac_f32_e32 v79, v15, v133
	s_mov_b32 s0, s68
	s_mov_b32 s1, s69
	global_store_dword v132, v150, s[0:1]
	global_store_dword v132, v172, s[0:1] offset:128
	s_add_u32 s0, s68, 0x1000
	s_addc_u32 s1, s69, 0
	global_store_dword v132, v151, s[0:1]
	global_store_dword v132, v173, s[0:1] offset:128
	s_add_u32 s0, s68, 0x2000
	s_addc_u32 s1, s69, 0
	global_store_dword v132, v152, s[0:1]
	global_store_dword v132, v174, s[0:1] offset:128
	s_add_u32 s0, s68, 0x3000
	s_addc_u32 s1, s69, 0
	global_store_dword v132, v153, s[0:1]
	global_store_dword v132, v175, s[0:1] offset:128
	s_add_u32 s0, s68, 0x8000
	s_addc_u32 s1, s69, 0
	global_store_dword v132, v154, s[0:1]
	global_store_dword v132, v176, s[0:1] offset:128
	s_add_u32 s0, s68, 0x9000
	s_addc_u32 s1, s69, 0
	global_store_dword v132, v155, s[0:1]
	global_store_dword v132, v177, s[0:1] offset:128
	s_add_u32 s0, s68, 0xa000
	s_addc_u32 s1, s69, 0
	global_store_dword v132, v156, s[0:1]
	global_store_dword v132, v178, s[0:1] offset:128
	s_add_u32 s0, s68, 0xb000
	s_addc_u32 s1, s69, 0
	global_store_dword v132, v157, s[0:1]
	global_store_dword v132, v179, s[0:1] offset:128
	s_add_u32 s0, s68, 0x10000
	s_addc_u32 s1, s69, 0
	global_store_dword v132, v158, s[0:1]
	global_store_dword v132, v180, s[0:1] offset:128
	s_add_u32 s0, s68, 0x11000
	s_addc_u32 s1, s69, 0
	global_store_dword v132, v159, s[0:1]
	global_store_dword v132, v181, s[0:1] offset:128
	s_add_u32 s0, s68, 0x12000
	s_addc_u32 s1, s69, 0
	global_store_dword v132, v160, s[0:1]
	global_store_dword v132, v182, s[0:1] offset:128
	s_add_u32 s0, s68, 0x13000
	s_addc_u32 s1, s69, 0
	global_store_dword v132, v161, s[0:1]
	global_store_dword v132, v183, s[0:1] offset:128
	s_add_u32 s0, s68, 0x18000
	s_addc_u32 s1, s69, 0
	global_store_dword v132, v162, s[0:1]
	global_store_dword v132, v184, s[0:1] offset:128
	s_add_u32 s0, s68, 0x19000
	s_addc_u32 s1, s69, 0
	global_store_dword v132, v163, s[0:1]
	global_store_dword v132, v185, s[0:1] offset:128
	s_add_u32 s0, s68, 0x1a000
	s_addc_u32 s1, s69, 0
	global_store_dword v132, v164, s[0:1]
	global_store_dword v132, v186, s[0:1] offset:128
	s_add_u32 s0, s68, 0x1b000
	s_addc_u32 s1, s69, 0
	global_store_dword v132, v165, s[0:1]
	global_store_dword v132, v187, s[0:1] offset:128
	s_add_u32 s0, s68, 0x20000
	s_addc_u32 s1, s69, 0
	global_store_dword v132, v188, s[0:1]
	global_store_dword v132, v204, s[0:1] offset:128
	s_add_u32 s0, s68, 0x21000
	s_addc_u32 s1, s69, 0
	global_store_dword v132, v189, s[0:1]
	global_store_dword v132, v205, s[0:1] offset:128
	s_add_u32 s0, s68, 0x22000
	s_addc_u32 s1, s69, 0
	global_store_dword v132, v190, s[0:1]
	global_store_dword v132, v206, s[0:1] offset:128
	s_add_u32 s0, s68, 0x23000
	s_addc_u32 s1, s69, 0
	global_store_dword v132, v191, s[0:1]
	global_store_dword v132, v207, s[0:1] offset:128
	s_add_u32 s0, s68, 0x28000
	s_addc_u32 s1, s69, 0
	global_store_dword v132, v192, s[0:1]
	global_store_dword v132, v208, s[0:1] offset:128
	s_add_u32 s0, s68, 0x29000
	s_addc_u32 s1, s69, 0
	global_store_dword v132, v193, s[0:1]
	global_store_dword v132, v209, s[0:1] offset:128
	s_add_u32 s0, s68, 0x2a000
	s_addc_u32 s1, s69, 0
	global_store_dword v132, v194, s[0:1]
	global_store_dword v132, v210, s[0:1] offset:128
	s_add_u32 s0, s68, 0x2b000
	s_addc_u32 s1, s69, 0
	global_store_dword v132, v195, s[0:1]
	global_store_dword v132, v211, s[0:1] offset:128
	s_add_u32 s0, s68, 0x30000
	s_addc_u32 s1, s69, 0
	global_store_dword v132, v196, s[0:1]
	global_store_dword v132, v212, s[0:1] offset:128
	s_add_u32 s0, s68, 0x31000
	s_addc_u32 s1, s69, 0
	global_store_dword v132, v197, s[0:1]
	global_store_dword v132, v213, s[0:1] offset:128
	s_add_u32 s0, s68, 0x32000
	s_addc_u32 s1, s69, 0
	global_store_dword v132, v198, s[0:1]
	global_store_dword v132, v214, s[0:1] offset:128
	s_add_u32 s0, s68, 0x33000
	s_addc_u32 s1, s69, 0
	global_store_dword v132, v199, s[0:1]
	global_store_dword v132, v215, s[0:1] offset:128
	s_add_u32 s0, s68, 0x38000
	s_addc_u32 s1, s69, 0
	global_store_dword v132, v200, s[0:1]
	global_store_dword v132, v216, s[0:1] offset:128
	s_add_u32 s0, s68, 0x39000
	s_addc_u32 s1, s69, 0
	global_store_dword v132, v201, s[0:1]
	global_store_dword v132, v217, s[0:1] offset:128
	s_add_u32 s0, s68, 0x3a000
	s_addc_u32 s1, s69, 0
	global_store_dword v132, v202, s[0:1]
	global_store_dword v132, v218, s[0:1] offset:128
	s_add_u32 s0, s68, 0x3b000
	s_addc_u32 s1, s69, 0
	global_store_dword v132, v203, s[0:1]
	global_store_dword v132, v219, s[0:1] offset:128
	s_add_u32 s0, s68, 0x40000
	s_addc_u32 s1, s69, 0
	global_store_dword v132, v112, s[0:1]
	global_store_dword v132, v96, s[0:1] offset:128
	s_add_u32 s0, s68, 0x41000
	s_addc_u32 s1, s69, 0
	global_store_dword v132, v113, s[0:1]
	global_store_dword v132, v97, s[0:1] offset:128
	s_add_u32 s0, s68, 0x42000
	s_addc_u32 s1, s69, 0
	global_store_dword v132, v114, s[0:1]
	global_store_dword v132, v98, s[0:1] offset:128
	s_add_u32 s0, s68, 0x43000
	s_addc_u32 s1, s69, 0
	global_store_dword v132, v115, s[0:1]
	global_store_dword v132, v99, s[0:1] offset:128
	s_add_u32 s0, s68, 0x48000
	s_addc_u32 s1, s69, 0
	global_store_dword v132, v116, s[0:1]
	global_store_dword v132, v100, s[0:1] offset:128
	s_add_u32 s0, s68, 0x49000
	s_addc_u32 s1, s69, 0
	global_store_dword v132, v117, s[0:1]
	global_store_dword v132, v101, s[0:1] offset:128
	s_add_u32 s0, s68, 0x4a000
	s_addc_u32 s1, s69, 0
	global_store_dword v132, v118, s[0:1]
	global_store_dword v132, v102, s[0:1] offset:128
	s_add_u32 s0, s68, 0x4b000
	s_addc_u32 s1, s69, 0
	global_store_dword v132, v119, s[0:1]
	global_store_dword v132, v103, s[0:1] offset:128
	s_add_u32 s0, s68, 0x50000
	s_addc_u32 s1, s69, 0
	global_store_dword v132, v120, s[0:1]
	global_store_dword v132, v104, s[0:1] offset:128
	s_add_u32 s0, s68, 0x51000
	s_addc_u32 s1, s69, 0
	global_store_dword v132, v121, s[0:1]
	global_store_dword v132, v105, s[0:1] offset:128
	s_add_u32 s0, s68, 0x52000
	s_addc_u32 s1, s69, 0
	global_store_dword v132, v122, s[0:1]
	global_store_dword v132, v106, s[0:1] offset:128
	s_add_u32 s0, s68, 0x53000
	s_addc_u32 s1, s69, 0
	global_store_dword v132, v123, s[0:1]
	global_store_dword v132, v107, s[0:1] offset:128
	s_add_u32 s0, s68, 0x58000
	s_addc_u32 s1, s69, 0
	global_store_dword v132, v124, s[0:1]
	global_store_dword v132, v108, s[0:1] offset:128
	s_add_u32 s0, s68, 0x59000
	s_addc_u32 s1, s69, 0
	global_store_dword v132, v125, s[0:1]
	global_store_dword v132, v109, s[0:1] offset:128
	s_add_u32 s0, s68, 0x5a000
	s_addc_u32 s1, s69, 0
	global_store_dword v132, v126, s[0:1]
	global_store_dword v132, v110, s[0:1] offset:128
	s_add_u32 s0, s68, 0x5b000
	s_addc_u32 s1, s69, 0
	global_store_dword v132, v127, s[0:1]
	global_store_dword v132, v111, s[0:1] offset:128
	s_add_u32 s0, s68, 0x60000
	s_addc_u32 s1, s69, 0
	global_store_dword v132, v80, s[0:1]
	global_store_dword v132, v64, s[0:1] offset:128
	s_add_u32 s0, s68, 0x61000
	s_addc_u32 s1, s69, 0
	global_store_dword v132, v81, s[0:1]
	global_store_dword v132, v65, s[0:1] offset:128
	s_add_u32 s0, s68, 0x62000
	s_addc_u32 s1, s69, 0
	global_store_dword v132, v82, s[0:1]
	global_store_dword v132, v66, s[0:1] offset:128
	s_add_u32 s0, s68, 0x63000
	s_addc_u32 s1, s69, 0
	global_store_dword v132, v83, s[0:1]
	global_store_dword v132, v67, s[0:1] offset:128
	s_add_u32 s0, s68, 0x68000
	s_addc_u32 s1, s69, 0
	global_store_dword v132, v84, s[0:1]
	global_store_dword v132, v68, s[0:1] offset:128
	s_add_u32 s0, s68, 0x69000
	s_addc_u32 s1, s69, 0
	global_store_dword v132, v85, s[0:1]
	global_store_dword v132, v69, s[0:1] offset:128
	s_add_u32 s0, s68, 0x6a000
	s_addc_u32 s1, s69, 0
	global_store_dword v132, v86, s[0:1]
	global_store_dword v132, v70, s[0:1] offset:128
	s_add_u32 s0, s68, 0x6b000
	s_addc_u32 s1, s69, 0
	global_store_dword v132, v87, s[0:1]
	global_store_dword v132, v71, s[0:1] offset:128
	s_add_u32 s0, s68, 0x70000
	s_addc_u32 s1, s69, 0
	global_store_dword v132, v88, s[0:1]
	global_store_dword v132, v72, s[0:1] offset:128
	s_add_u32 s0, s68, 0x71000
	s_addc_u32 s1, s69, 0
	global_store_dword v132, v89, s[0:1]
	global_store_dword v132, v73, s[0:1] offset:128
	s_add_u32 s0, s68, 0x72000
	s_addc_u32 s1, s69, 0
	global_store_dword v132, v90, s[0:1]
	global_store_dword v132, v74, s[0:1] offset:128
	s_add_u32 s0, s68, 0x73000
	s_addc_u32 s1, s69, 0
	global_store_dword v132, v91, s[0:1]
	global_store_dword v132, v75, s[0:1] offset:128
	s_add_u32 s0, s68, 0x78000
	s_addc_u32 s1, s69, 0
	global_store_dword v132, v92, s[0:1]
	global_store_dword v132, v76, s[0:1] offset:128
	s_add_u32 s0, s68, 0x79000
	s_addc_u32 s1, s69, 0
	global_store_dword v132, v93, s[0:1]
	global_store_dword v132, v77, s[0:1] offset:128
	s_add_u32 s0, s68, 0x7a000
	s_addc_u32 s1, s69, 0
	global_store_dword v132, v94, s[0:1]
	global_store_dword v132, v78, s[0:1] offset:128
	s_add_u32 s0, s68, 0x7b000
	s_addc_u32 s1, s69, 0
	global_store_dword v132, v95, s[0:1]
	global_store_dword v132, v79, s[0:1] offset:128
	s_branch .LBB0_267

.LBB0_1218:
	s_and_b64 vcc, exec, s[0:1]
	s_cbranch_vccz .LBB0_1561
	v_mov_b32_e32 v139, v224
	s_load_dword s6, s[24:25], 0x0
	v_readlane_b32 s0, v251, 34
	v_readlane_b32 s1, v251, 35
	v_and_b32_e32 v137, 63, v139
	s_andn2_b64 vcc, exec, s[0:1]
	s_cbranch_vccnz .LBB0_1673
	s_add_u32 s46, s66, 0x3f700
	s_addc_u32 s47, s67, 0
	v_lshrrev_b32_e32 v0, 3, v139
	v_and_b32_e32 v1, 7, v139
	v_lshlrev_b32_e32 v1, 3, v1
	v_lshl_or_b32 v0, v0, 7, v1
	global_load_dwordx2 v[2:3], v0, s[46:47]
	v_lshlrev_b32_e32 v1, 3, v139
	v_add_u32_e32 v1, 0x20000, v1
	s_waitcnt vmcnt(0)
	ds_write_b64 v1, v[2:3]
	s_waitcnt lgkmcnt(0)
	s_barrier
	v_readlane_b32 s0, v252, 55
	s_add_u32 s0, s66, s0
	s_addc_u32 s1, s67, 0
	v_readlane_b32 s4, v254, 52
	s_add_u32 s4, s0, s4
	v_readlane_b32 s0, v254, 48
	v_lshrrev_b32_e32 v0, 4, v139
	s_addc_u32 s5, s1, s0
	v_readlane_b32 s0, v252, 56
	v_xor_b32_e32 v0, v0, v139
	v_ashrrev_i32_e32 v5, 3, v139
	v_readlane_b32 s55, v252, 54
	s_add_u32 s44, s66, s0
	v_lshlrev_b32_e32 v0, 4, v0
	v_add_u32_e32 v2, s55, v5
	v_readlane_b32 s7, v252, 57
	s_addc_u32 s45, s67, 0
	v_and_b32_e32 v128, 0x70, v0
	v_mad_i64_i32 v[2:3], s[0:1], v2, s7, 0
	v_lshl_add_u32 v6, v139, 4, 0
	v_lshl_add_u64 v[0:1], s[44:45], 0, v[128:129]
	v_readfirstlane_b32 s0, v6
	v_add_u32_e32 v7, 0x200, v139
	v_lshl_add_u64 v[2:3], v[2:3], 1, v[0:1]
	s_mov_b32 m0, s0
	v_ashrrev_i32_e32 v8, 3, v7
	global_load_lds_dwordx4 v[2:3], off
	v_add_u32_e32 v2, s55, v8
	v_mad_i64_i32 v[2:3], s[0:1], v2, s7, 0
	v_lshl_add_u32 v7, v7, 4, 0
	v_add_u32_e32 v9, 0x400, v139
	v_readfirstlane_b32 s0, v7
	v_lshl_add_u64 v[2:3], v[2:3], 1, v[0:1]
	s_mov_b32 m0, s0
	v_ashrrev_i32_e32 v10, 3, v9
	global_load_lds_dwordx4 v[2:3], off
	v_add_u32_e32 v2, s55, v10
	v_mad_i64_i32 v[2:3], s[0:1], v2, s7, 0
	v_lshl_add_u32 v9, v9, 4, 0
	v_add_u32_e32 v11, 0x600, v139
	v_readfirstlane_b32 s0, v9
	v_lshl_add_u64 v[2:3], v[2:3], 1, v[0:1]
	s_mov_b32 m0, s0
	v_ashrrev_i32_e32 v12, 3, v11
	global_load_lds_dwordx4 v[2:3], off
	v_add_u32_e32 v2, s55, v12
	v_mad_i64_i32 v[2:3], s[0:1], v2, s7, 0
	v_lshl_add_u32 v11, v11, 4, 0
	v_readlane_b32 s54, v251, 36
	v_lshl_add_u64 v[0:1], v[2:3], 1, v[0:1]
	v_readfirstlane_b32 s0, v11
	v_add_u32_e32 v2, s54, v5
	s_mov_b32 m0, s0
	v_mad_i64_i32 v[2:3], s[0:1], s7, v2, 0
	v_add_u32_e32 v5, 0x8000, v6
	global_load_lds_dwordx4 v[0:1], off
	v_lshl_add_u64 v[0:1], s[4:5], 0, v[128:129]
	v_readfirstlane_b32 s0, v5
	v_lshl_add_u64 v[2:3], v[2:3], 1, v[0:1]
	s_mov_b32 m0, s0
	v_add_u32_e32 v5, 0x8000, v7
	global_load_lds_dwordx4 v[2:3], off
	v_add_u32_e32 v2, s54, v8
	v_mad_i64_i32 v[2:3], s[0:1], s7, v2, 0
	v_readfirstlane_b32 s0, v5
	v_lshl_add_u64 v[2:3], v[2:3], 1, v[0:1]
	s_mov_b32 m0, s0
	v_add_u32_e32 v5, 0x8000, v9
	global_load_lds_dwordx4 v[2:3], off
	v_add_u32_e32 v2, s54, v10
	v_mad_i64_i32 v[2:3], s[0:1], s7, v2, 0
	v_readfirstlane_b32 s0, v5
	v_lshl_add_u64 v[2:3], v[2:3], 1, v[0:1]
	s_mov_b32 m0, s0
	v_lshrrev_b32_e32 v4, 5, v137
	global_load_lds_dwordx4 v[2:3], off
	v_add_u32_e32 v2, s54, v12
	v_mad_i64_i32 v[2:3], s[0:1], s7, v2, 0
	v_lshl_add_u64 v[0:1], v[2:3], 1, v[0:1]
	v_add_u32_e32 v2, 0x8000, v11
	v_and_b32_e32 v141, 31, v139
	v_readfirstlane_b32 s0, v2
	s_mov_b32 m0, s0
	s_load_dword s0, s[24:25], 0x10
	global_load_lds_dwordx4 v[0:1], off
	v_ashrrev_i32_e32 v0, 1, v139
	v_and_b32_e32 v134, 0xffffff80, v0
	s_waitcnt lgkmcnt(0)
	s_lshr_b32 s0, s0, 16
	s_cmp_lg_u32 s0, 0
	s_cselect_b64 s[0:1], -1, 0
	s_cmp_lg_u64 s[0:1], 0
	s_addc_u32 s9, s6, 0
	s_add_u32 s96, s66, 0xdf53700
	s_addc_u32 s97, s67, 0
	v_readlane_b32 s0, v254, 49
	v_readlane_b32 s1, v254, 50
	s_add_u32 s0, s66, s0
	s_addc_u32 s1, s67, s1
	s_add_u32 s56, s0, 0x2c93700
	s_addc_u32 s57, s1, 0
	s_add_u32 s52, s66, 0xdad3700
	s_addc_u32 s53, s67, 0
	v_readlane_b32 s0, v254, 51
	s_add_u32 s0, s66, s0
	s_addc_u32 s1, s67, 0
	s_add_u32 s92, s0, 0x2c4b700
	s_addc_u32 s93, s1, 0
	s_add_u32 s30, s66, 0xc953700
	s_addc_u32 s31, s67, 0
	s_add_u32 s58, s66, 0xd3d3700
	v_and_b32_e32 v0, 8, v139
	s_addc_u32 s59, s67, 0
	v_lshlrev_b32_e32 v176, 2, v4
	v_cmp_eq_u32_e64 s[36:37], 0, v0
	v_and_b32_e32 v138, 0x5f, v139
	v_and_b32_e32 v0, 64, v139
	s_add_u32 s70, s66, 0xc053700
	v_readlane_b32 s0, v252, 58
	s_mov_b32 s12, 0x1ffff80
	s_mov_b32 s8, 0
	v_and_b32_e32 v143, 0xc0, v139
	v_lshlrev_b32_e32 v136, 3, v4
	v_and_b32_e32 v177, 7, v139
	v_cmp_lt_u32_e64 s[38:39], 15, v141
	v_or_b32_e32 v178, v176, v134
	v_ashrrev_i32_e32 v135, 31, v134
	v_cmp_ne_u32_e64 s[40:41], 0, v0
	v_subrev_u32_e32 v140, 64, v138
	v_subrev_u32_e32 v142, 32, v138
	v_or_b32_e32 v179, 32, v134
	v_or_b32_e32 v180, 64, v134
	v_or_b32_e32 v181, 0x60, v134
	s_addc_u32 s71, s67, 0
	v_readlane_b32 s13, v250, 0
	s_mov_b32 s60, s0
	s_mov_b32 s6, s7
	s_branch .LBB0_1224

.LBB0_1281:
	s_and_saveexec_b64 s[6:7], s[54:55]
	s_cbranch_execz .LBB0_1283
	v_and_b32_e32 v128, 63, v148
	v_bfe_u32 v130, v148, 6, 4
	v_cndmask_b32_e64 v128, v130, v128, s[38:39]
	v_lshlrev_b32_e32 v130, 3, v177
	v_lshl_or_b32 v128, v128, 6, v130
	v_add_u32_e32 v128, 0x20000, v128
	ds_read_b64 v[130:131], v128
	v_and_b32_e32 v132, 64, v226
	v_xor_b32_e32 v128, 8, v226
	v_add_u32_e32 v132, 64, v132
	v_cmp_lt_i32_e32 vcc, v128, v132
	v_mov_b32_e32 v132, v112
	s_waitcnt lgkmcnt(0)
	v_mov_b32_e32 v133, v131
	v_cndmask_b32_e32 v128, v226, v128, vcc
	v_lshlrev_b32_e32 v128, 2, v128
	ds_bpermute_b32 v128, v128, v112
	s_waitcnt lgkmcnt(0)
	v_cndmask_b32_e64 v112, v128, -v128, s[36:37]
	v_mov_b32_e32 v131, v112
	v_pk_mul_f32 v[130:131], v[132:133], v[130:131]
	s_nop 0
	v_add_f32_e32 v112, v130, v131
.LBB0_1283:
	s_or_b64 exec, exec, s[6:7]
	v_mov_b32_e32 v145, v129
	v_lshl_add_u64 v[146:147], v[144:145], 1, s[70:71]
	v_mul_f32_e32 v112, 0x3e16c740, v112
	v_cvt_pk_bf16_f32 v112, v112, s0
	v_mad_i64_i32 v[130:131], s[6:7], v148, s10, v[146:147]
	global_store_short v[130:131], v112, off
	v_add_u32_e32 v112, 1, v148
	s_and_saveexec_b64 s[6:7], s[54:55]
	s_cbranch_execz .LBB0_1285
	v_and_b32_e32 v128, 63, v112
	v_bfe_u32 v130, v112, 6, 4
	v_cndmask_b32_e64 v128, v130, v128, s[38:39]
	v_lshlrev_b32_e32 v130, 3, v177
	v_lshl_or_b32 v128, v128, 6, v130
	v_add_u32_e32 v128, 0x20000, v128
	ds_read_b64 v[130:131], v128
	v_and_b32_e32 v132, 64, v226
	v_xor_b32_e32 v128, 8, v226
	v_add_u32_e32 v132, 64, v132
	v_cmp_lt_i32_e32 vcc, v128, v132
	v_mov_b32_e32 v132, v113
	s_waitcnt lgkmcnt(0)
	v_mov_b32_e32 v133, v131
	v_cndmask_b32_e32 v128, v226, v128, vcc
	v_lshlrev_b32_e32 v128, 2, v128
	ds_bpermute_b32 v128, v128, v113
	s_waitcnt lgkmcnt(0)
	v_cndmask_b32_e64 v113, v128, -v128, s[36:37]
	v_mov_b32_e32 v131, v113
	v_pk_mul_f32 v[130:131], v[132:133], v[130:131]
	s_nop 0
	v_add_f32_e32 v113, v130, v131
.LBB0_1285:
	s_or_b64 exec, exec, s[6:7]
	v_mul_f32_e32 v113, 0x3e16c740, v113
	v_cvt_pk_bf16_f32 v128, v113, s0
	v_mad_i64_i32 v[112:113], s[6:7], v112, s10, v[146:147]
	global_store_short v[112:113], v128, off
	v_add_u32_e32 v112, 2, v148
	s_and_saveexec_b64 s[6:7], s[54:55]
	s_cbranch_execz .LBB0_1287
	v_and_b32_e32 v113, 63, v112
	v_bfe_u32 v128, v112, 6, 4
	v_cndmask_b32_e64 v113, v128, v113, s[38:39]
	v_lshlrev_b32_e32 v128, 3, v177
	v_lshl_or_b32 v113, v113, 6, v128
	v_add_u32_e32 v113, 0x20000, v113
	ds_read_b64 v[130:131], v113
	v_and_b32_e32 v128, 64, v226
	v_xor_b32_e32 v113, 8, v226
	v_add_u32_e32 v128, 64, v128
	v_cmp_lt_i32_e32 vcc, v113, v128
	v_mov_b32_e32 v132, v114
	s_waitcnt lgkmcnt(0)
	v_mov_b32_e32 v133, v131
	v_cndmask_b32_e32 v113, v226, v113, vcc
	v_lshlrev_b32_e32 v113, 2, v113
	ds_bpermute_b32 v113, v113, v114
	s_waitcnt lgkmcnt(0)
	v_cndmask_b32_e64 v113, v113, -v113, s[36:37]
	v_mov_b32_e32 v131, v113
	v_pk_mul_f32 v[130:131], v[132:133], v[130:131]
	s_nop 0
	v_add_f32_e32 v114, v130, v131
.LBB0_1287:
	s_or_b64 exec, exec, s[6:7]
	v_mul_f32_e32 v113, 0x3e16c740, v114
	v_cvt_pk_bf16_f32 v114, v113, s0
	v_mad_i64_i32 v[112:113], s[6:7], v112, s10, v[146:147]
	global_store_short v[112:113], v114, off
	v_add_u32_e32 v112, 3, v148
	s_and_saveexec_b64 s[6:7], s[54:55]
	s_cbranch_execz .LBB0_1289
	v_and_b32_e32 v113, 63, v112
	v_bfe_u32 v114, v112, 6, 4
	v_cndmask_b32_e64 v113, v114, v113, s[38:39]
	v_lshlrev_b32_e32 v114, 3, v177
	v_lshl_or_b32 v113, v113, 6, v114
	v_add_u32_e32 v113, 0x20000, v113
	ds_read_b64 v[130:131], v113
	v_and_b32_e32 v114, 64, v226
	v_xor_b32_e32 v113, 8, v226
	v_add_u32_e32 v114, 64, v114
	v_cmp_lt_i32_e32 vcc, v113, v114
	v_mov_b32_e32 v114, v115
	s_nop 0
	v_cndmask_b32_e32 v113, v226, v113, vcc
	v_lshlrev_b32_e32 v113, 2, v113
	ds_bpermute_b32 v113, v113, v115
	s_waitcnt lgkmcnt(0)
	v_cndmask_b32_e64 v113, v113, -v113, s[36:37]
	s_waitcnt lgkmcnt(0)
	v_mov_b32_e32 v115, v131
	v_mov_b32_e32 v131, v113
	v_pk_mul_f32 v[114:115], v[114:115], v[130:131]
	s_nop 0
	v_add_f32_e32 v115, v114, v115
.LBB0_1289:
	s_or_b64 exec, exec, s[6:7]
	v_mul_f32_e32 v113, 0x3e16c740, v115
	v_cvt_pk_bf16_f32 v114, v113, s0
	v_mad_i64_i32 v[112:113], s[6:7], v112, s10, v[146:147]
	global_store_short v[112:113], v114, off
	v_add_u32_e32 v112, 8, v148
	s_and_saveexec_b64 s[6:7], s[54:55]
	s_cbranch_execz .LBB0_1291
	v_and_b32_e32 v113, 63, v112
	v_bfe_u32 v114, v112, 6, 4
	v_cndmask_b32_e64 v113, v114, v113, s[38:39]
	v_lshlrev_b32_e32 v114, 3, v177
	v_lshl_or_b32 v113, v113, 6, v114
	v_add_u32_e32 v113, 0x20000, v113
	ds_read_b64 v[114:115], v113
	v_and_b32_e32 v128, 64, v226
	v_xor_b32_e32 v113, 8, v226
	v_add_u32_e32 v128, 64, v128
	v_cmp_lt_i32_e32 vcc, v113, v128
	v_mov_b32_e32 v130, v116
	s_waitcnt lgkmcnt(0)
	v_mov_b32_e32 v131, v115
	v_cndmask_b32_e32 v113, v226, v113, vcc
	v_lshlrev_b32_e32 v113, 2, v113
	ds_bpermute_b32 v113, v113, v116
	s_waitcnt lgkmcnt(0)
	v_cndmask_b32_e64 v113, v113, -v113, s[36:37]
	v_mov_b32_e32 v115, v113
	v_pk_mul_f32 v[114:115], v[130:131], v[114:115]
	s_nop 0
	v_add_f32_e32 v116, v114, v115
.LBB0_1291:
	s_or_b64 exec, exec, s[6:7]
	v_mul_f32_e32 v113, 0x3e16c740, v116
	v_cvt_pk_bf16_f32 v114, v113, s0
	v_mad_i64_i32 v[112:113], s[6:7], v112, s10, v[146:147]
	global_store_short v[112:113], v114, off
	v_add_u32_e32 v112, 9, v148
	s_and_saveexec_b64 s[6:7], s[54:55]
	s_cbranch_execz .LBB0_1293
	v_and_b32_e32 v113, 63, v112
	v_bfe_u32 v114, v112, 6, 4
	v_cndmask_b32_e64 v113, v114, v113, s[38:39]
	v_lshlrev_b32_e32 v114, 3, v177
	v_lshl_or_b32 v113, v113, 6, v114
	v_add_u32_e32 v113, 0x20000, v113
	ds_read_b64 v[114:115], v113
	v_and_b32_e32 v116, 64, v226
	v_xor_b32_e32 v113, 8, v226
	v_add_u32_e32 v116, 64, v116
	v_cmp_lt_i32_e32 vcc, v113, v116
	v_mov_b32_e32 v116, v117
	s_nop 0
	v_cndmask_b32_e32 v113, v226, v113, vcc
	v_lshlrev_b32_e32 v113, 2, v113
	ds_bpermute_b32 v113, v113, v117
	s_waitcnt lgkmcnt(0)
	v_cndmask_b32_e64 v113, v113, -v113, s[36:37]
	s_waitcnt lgkmcnt(0)
	v_mov_b32_e32 v117, v115
	v_mov_b32_e32 v115, v113
	v_pk_mul_f32 v[114:115], v[116:117], v[114:115]
	s_nop 0
	v_add_f32_e32 v117, v114, v115
.LBB0_1293:
	s_or_b64 exec, exec, s[6:7]
	v_mul_f32_e32 v113, 0x3e16c740, v117
	v_cvt_pk_bf16_f32 v114, v113, s0
	v_mad_i64_i32 v[112:113], s[6:7], v112, s10, v[146:147]
	global_store_short v[112:113], v114, off
	v_add_u32_e32 v112, 10, v148
	s_and_saveexec_b64 s[6:7], s[54:55]
	s_cbranch_execz .LBB0_1295
	v_and_b32_e32 v113, 63, v112
	v_bfe_u32 v114, v112, 6, 4
	v_cndmask_b32_e64 v113, v114, v113, s[38:39]
	v_lshlrev_b32_e32 v114, 3, v177
	v_lshl_or_b32 v113, v113, 6, v114
	v_add_u32_e32 v113, 0x20000, v113
	ds_read_b64 v[114:115], v113
	v_and_b32_e32 v116, 64, v226
	v_xor_b32_e32 v113, 8, v226
	v_add_u32_e32 v116, 64, v116
	v_cmp_lt_i32_e32 vcc, v113, v116
	v_mov_b32_e32 v116, v118
	s_waitcnt lgkmcnt(0)
	v_mov_b32_e32 v117, v115
	v_cndmask_b32_e32 v113, v226, v113, vcc
	v_lshlrev_b32_e32 v113, 2, v113
	ds_bpermute_b32 v113, v113, v118
	s_waitcnt lgkmcnt(0)
	v_cndmask_b32_e64 v113, v113, -v113, s[36:37]
	v_mov_b32_e32 v115, v113
	v_pk_mul_f32 v[114:115], v[116:117], v[114:115]
	s_nop 0
	v_add_f32_e32 v118, v114, v115
.LBB0_1295:
	s_or_b64 exec, exec, s[6:7]
	v_mul_f32_e32 v113, 0x3e16c740, v118
	v_cvt_pk_bf16_f32 v114, v113, s0
	v_mad_i64_i32 v[112:113], s[6:7], v112, s10, v[146:147]
	global_store_short v[112:113], v114, off
	v_add_u32_e32 v112, 11, v148
	s_and_saveexec_b64 s[6:7], s[54:55]
	s_cbranch_execz .LBB0_1297
	v_and_b32_e32 v113, 63, v112
	v_bfe_u32 v114, v112, 6, 4
	v_cndmask_b32_e64 v113, v114, v113, s[38:39]
	v_lshlrev_b32_e32 v114, 3, v177
	v_lshl_or_b32 v113, v113, 6, v114
	v_add_u32_e32 v113, 0x20000, v113
	ds_read_b64 v[114:115], v113
	v_and_b32_e32 v116, 64, v226
	v_xor_b32_e32 v113, 8, v226
	v_add_u32_e32 v116, 64, v116
	v_cmp_lt_i32_e32 vcc, v113, v116
	v_mov_b32_e32 v116, v119
	s_waitcnt lgkmcnt(0)
	v_mov_b32_e32 v117, v115
	v_cndmask_b32_e32 v113, v226, v113, vcc
	v_lshlrev_b32_e32 v113, 2, v113
	ds_bpermute_b32 v113, v113, v119
	s_waitcnt lgkmcnt(0)
	v_cndmask_b32_e64 v113, v113, -v113, s[36:37]
	v_mov_b32_e32 v115, v113
	v_pk_mul_f32 v[114:115], v[116:117], v[114:115]
	s_nop 0
	v_add_f32_e32 v119, v114, v115
.LBB0_1297:
	s_or_b64 exec, exec, s[6:7]
	v_mul_f32_e32 v113, 0x3e16c740, v119
	v_cvt_pk_bf16_f32 v114, v113, s0
	v_mad_i64_i32 v[112:113], s[6:7], v112, s10, v[146:147]
	global_store_short v[112:113], v114, off
	v_add_u32_e32 v112, 16, v148
	s_and_saveexec_b64 s[6:7], s[54:55]
	s_cbranch_execz .LBB0_1299
	v_and_b32_e32 v113, 63, v112
	v_bfe_u32 v114, v112, 6, 4
	v_cndmask_b32_e64 v113, v114, v113, s[38:39]
	v_lshlrev_b32_e32 v114, 3, v177
	v_lshl_or_b32 v113, v113, 6, v114
	v_add_u32_e32 v113, 0x20000, v113
	ds_read_b64 v[114:115], v113
	v_and_b32_e32 v116, 64, v226
	v_xor_b32_e32 v113, 8, v226
	v_add_u32_e32 v116, 64, v116
	v_cmp_lt_i32_e32 vcc, v113, v116
	v_mov_b32_e32 v116, v120
	s_waitcnt lgkmcnt(0)
	v_mov_b32_e32 v117, v115
	v_cndmask_b32_e32 v113, v226, v113, vcc
	v_lshlrev_b32_e32 v113, 2, v113
	ds_bpermute_b32 v113, v113, v120
	s_waitcnt lgkmcnt(0)
	v_cndmask_b32_e64 v113, v113, -v113, s[36:37]
	v_mov_b32_e32 v115, v113
	v_pk_mul_f32 v[114:115], v[116:117], v[114:115]
	s_nop 0
	v_add_f32_e32 v120, v114, v115
.LBB0_1299:
	s_or_b64 exec, exec, s[6:7]
	v_mul_f32_e32 v113, 0x3e16c740, v120
	v_cvt_pk_bf16_f32 v114, v113, s0
	v_mad_i64_i32 v[112:113], s[6:7], v112, s10, v[146:147]
	global_store_short v[112:113], v114, off
	v_add_u32_e32 v112, 17, v148
	s_and_saveexec_b64 s[6:7], s[54:55]
	s_cbranch_execz .LBB0_1301
	v_and_b32_e32 v113, 63, v112
	v_bfe_u32 v114, v112, 6, 4
	v_cndmask_b32_e64 v113, v114, v113, s[38:39]
	v_lshlrev_b32_e32 v114, 3, v177
	v_lshl_or_b32 v113, v113, 6, v114
	v_add_u32_e32 v113, 0x20000, v113
	ds_read_b64 v[114:115], v113
	v_and_b32_e32 v116, 64, v226
	v_xor_b32_e32 v113, 8, v226
	v_add_u32_e32 v116, 64, v116
	v_cmp_lt_i32_e32 vcc, v113, v116
	v_mov_b32_e32 v116, v121
	s_waitcnt lgkmcnt(0)
	v_mov_b32_e32 v117, v115
	v_cndmask_b32_e32 v113, v226, v113, vcc
	v_lshlrev_b32_e32 v113, 2, v113
	ds_bpermute_b32 v113, v113, v121
	s_waitcnt lgkmcnt(0)
	v_cndmask_b32_e64 v113, v113, -v113, s[36:37]
	v_mov_b32_e32 v115, v113
	v_pk_mul_f32 v[114:115], v[116:117], v[114:115]
	s_nop 0
	v_add_f32_e32 v121, v114, v115
.LBB0_1301:
	s_or_b64 exec, exec, s[6:7]
	v_mul_f32_e32 v113, 0x3e16c740, v121
	v_cvt_pk_bf16_f32 v114, v113, s0
	v_mad_i64_i32 v[112:113], s[6:7], v112, s10, v[146:147]
	global_store_short v[112:113], v114, off
	v_add_u32_e32 v112, 18, v148
	s_and_saveexec_b64 s[6:7], s[54:55]
	s_cbranch_execz .LBB0_1303
	v_and_b32_e32 v113, 63, v112
	v_bfe_u32 v114, v112, 6, 4
	v_cndmask_b32_e64 v113, v114, v113, s[38:39]
	v_lshlrev_b32_e32 v114, 3, v177
	v_lshl_or_b32 v113, v113, 6, v114
	v_add_u32_e32 v113, 0x20000, v113
	ds_read_b64 v[114:115], v113
	v_and_b32_e32 v116, 64, v226
	v_xor_b32_e32 v113, 8, v226
	v_add_u32_e32 v116, 64, v116
	v_cmp_lt_i32_e32 vcc, v113, v116
	v_mov_b32_e32 v116, v122
	s_waitcnt lgkmcnt(0)
	v_mov_b32_e32 v117, v115
	v_cndmask_b32_e32 v113, v226, v113, vcc
	v_lshlrev_b32_e32 v113, 2, v113
	ds_bpermute_b32 v113, v113, v122
	s_waitcnt lgkmcnt(0)
	v_cndmask_b32_e64 v113, v113, -v113, s[36:37]
	v_mov_b32_e32 v115, v113
	v_pk_mul_f32 v[114:115], v[116:117], v[114:115]
	s_nop 0
	v_add_f32_e32 v122, v114, v115
.LBB0_1303:
	s_or_b64 exec, exec, s[6:7]
	v_mul_f32_e32 v113, 0x3e16c740, v122
	v_cvt_pk_bf16_f32 v114, v113, s0
	v_mad_i64_i32 v[112:113], s[6:7], v112, s10, v[146:147]
	global_store_short v[112:113], v114, off
	v_add_u32_e32 v112, 19, v148
	s_and_saveexec_b64 s[6:7], s[54:55]
	s_cbranch_execz .LBB0_1305
	v_and_b32_e32 v113, 63, v112
	v_bfe_u32 v114, v112, 6, 4
	v_cndmask_b32_e64 v113, v114, v113, s[38:39]
	v_lshlrev_b32_e32 v114, 3, v177
	v_lshl_or_b32 v113, v113, 6, v114
	v_add_u32_e32 v113, 0x20000, v113
	ds_read_b64 v[114:115], v113
	v_and_b32_e32 v116, 64, v226
	v_xor_b32_e32 v113, 8, v226
	v_add_u32_e32 v116, 64, v116
	v_cmp_lt_i32_e32 vcc, v113, v116
	v_mov_b32_e32 v116, v123
	s_waitcnt lgkmcnt(0)
	v_mov_b32_e32 v117, v115
	v_cndmask_b32_e32 v113, v226, v113, vcc
	v_lshlrev_b32_e32 v113, 2, v113
	ds_bpermute_b32 v113, v113, v123
	s_waitcnt lgkmcnt(0)
	v_cndmask_b32_e64 v113, v113, -v113, s[36:37]
	v_mov_b32_e32 v115, v113
	v_pk_mul_f32 v[114:115], v[116:117], v[114:115]
	s_nop 0
	v_add_f32_e32 v123, v114, v115
.LBB0_1305:
	s_or_b64 exec, exec, s[6:7]
	v_mul_f32_e32 v113, 0x3e16c740, v123
	v_cvt_pk_bf16_f32 v114, v113, s0
	v_mad_i64_i32 v[112:113], s[6:7], v112, s10, v[146:147]
	global_store_short v[112:113], v114, off
	v_add_u32_e32 v112, 24, v148
	s_and_saveexec_b64 s[6:7], s[54:55]
	s_cbranch_execz .LBB0_1307
	v_and_b32_e32 v113, 63, v112
	v_bfe_u32 v114, v112, 6, 4
	v_cndmask_b32_e64 v113, v114, v113, s[38:39]
	v_lshlrev_b32_e32 v114, 3, v177
	v_lshl_or_b32 v113, v113, 6, v114
	v_add_u32_e32 v113, 0x20000, v113
	ds_read_b64 v[114:115], v113
	v_and_b32_e32 v116, 64, v226
	v_xor_b32_e32 v113, 8, v226
	v_add_u32_e32 v116, 64, v116
	v_cmp_lt_i32_e32 vcc, v113, v116
	v_mov_b32_e32 v116, v124
	s_waitcnt lgkmcnt(0)
	v_mov_b32_e32 v117, v115
	v_cndmask_b32_e32 v113, v226, v113, vcc
	v_lshlrev_b32_e32 v113, 2, v113
	ds_bpermute_b32 v113, v113, v124
	s_waitcnt lgkmcnt(0)
	v_cndmask_b32_e64 v113, v113, -v113, s[36:37]
	v_mov_b32_e32 v115, v113
	v_pk_mul_f32 v[114:115], v[116:117], v[114:115]
	s_nop 0
	v_add_f32_e32 v124, v114, v115
.LBB0_1307:
	s_or_b64 exec, exec, s[6:7]
	v_mul_f32_e32 v113, 0x3e16c740, v124
	v_cvt_pk_bf16_f32 v114, v113, s0
	v_mad_i64_i32 v[112:113], s[6:7], v112, s10, v[146:147]
	global_store_short v[112:113], v114, off
	v_add_u32_e32 v112, 25, v148
	s_and_saveexec_b64 s[6:7], s[54:55]
	s_cbranch_execz .LBB0_1309
	v_and_b32_e32 v113, 63, v112
	v_bfe_u32 v114, v112, 6, 4
	v_cndmask_b32_e64 v113, v114, v113, s[38:39]
	v_lshlrev_b32_e32 v114, 3, v177
	v_lshl_or_b32 v113, v113, 6, v114
	v_add_u32_e32 v113, 0x20000, v113
	ds_read_b64 v[114:115], v113
	v_and_b32_e32 v116, 64, v226
	v_xor_b32_e32 v113, 8, v226
	v_add_u32_e32 v116, 64, v116
	v_cmp_lt_i32_e32 vcc, v113, v116
	v_mov_b32_e32 v116, v125
	s_waitcnt lgkmcnt(0)
	v_mov_b32_e32 v117, v115
	v_cndmask_b32_e32 v113, v226, v113, vcc
	v_lshlrev_b32_e32 v113, 2, v113
	ds_bpermute_b32 v113, v113, v125
	s_waitcnt lgkmcnt(0)
	v_cndmask_b32_e64 v113, v113, -v113, s[36:37]
	v_mov_b32_e32 v115, v113
	v_pk_mul_f32 v[114:115], v[116:117], v[114:115]
	s_nop 0
	v_add_f32_e32 v125, v114, v115
.LBB0_1309:
	s_or_b64 exec, exec, s[6:7]
	v_mul_f32_e32 v113, 0x3e16c740, v125
	v_cvt_pk_bf16_f32 v114, v113, s0
	v_mad_i64_i32 v[112:113], s[6:7], v112, s10, v[146:147]
	global_store_short v[112:113], v114, off
	v_add_u32_e32 v112, 26, v148
	s_and_saveexec_b64 s[6:7], s[54:55]
	s_cbranch_execz .LBB0_1311
	v_and_b32_e32 v113, 63, v112
	v_bfe_u32 v114, v112, 6, 4
	v_cndmask_b32_e64 v113, v114, v113, s[38:39]
	v_lshlrev_b32_e32 v114, 3, v177
	v_lshl_or_b32 v113, v113, 6, v114
	v_add_u32_e32 v113, 0x20000, v113
	ds_read_b64 v[114:115], v113
	v_and_b32_e32 v116, 64, v226
	v_xor_b32_e32 v113, 8, v226
	v_add_u32_e32 v116, 64, v116
	v_cmp_lt_i32_e32 vcc, v113, v116
	v_mov_b32_e32 v116, v126
	s_waitcnt lgkmcnt(0)
	v_mov_b32_e32 v117, v115
	v_cndmask_b32_e32 v113, v226, v113, vcc
	v_lshlrev_b32_e32 v113, 2, v113
	ds_bpermute_b32 v113, v113, v126
	s_waitcnt lgkmcnt(0)
	v_cndmask_b32_e64 v113, v113, -v113, s[36:37]
	v_mov_b32_e32 v115, v113
	v_pk_mul_f32 v[114:115], v[116:117], v[114:115]
	s_nop 0
	v_add_f32_e32 v126, v114, v115
.LBB0_1311:
	s_or_b64 exec, exec, s[6:7]
	v_mul_f32_e32 v113, 0x3e16c740, v126
	v_cvt_pk_bf16_f32 v114, v113, s0
	v_mad_i64_i32 v[112:113], s[6:7], v112, s10, v[146:147]
	global_store_short v[112:113], v114, off
	v_add_u32_e32 v112, 27, v148
	s_and_saveexec_b64 s[6:7], s[54:55]
	s_cbranch_execz .LBB0_1313
	v_and_b32_e32 v113, 63, v112
	v_bfe_u32 v114, v112, 6, 4
	v_cndmask_b32_e64 v113, v114, v113, s[38:39]
	v_lshlrev_b32_e32 v114, 3, v177
	v_lshl_or_b32 v113, v113, 6, v114
	v_add_u32_e32 v113, 0x20000, v113
	ds_read_b64 v[114:115], v113
	v_and_b32_e32 v116, 64, v226
	v_xor_b32_e32 v113, 8, v226
	v_add_u32_e32 v116, 64, v116
	v_cmp_lt_i32_e32 vcc, v113, v116
	v_mov_b32_e32 v116, v127
	s_waitcnt lgkmcnt(0)
	v_mov_b32_e32 v117, v115
	v_cndmask_b32_e32 v113, v226, v113, vcc
	v_lshlrev_b32_e32 v113, 2, v113
	ds_bpermute_b32 v113, v113, v127
	s_waitcnt lgkmcnt(0)
	v_cndmask_b32_e64 v113, v113, -v113, s[36:37]
	v_mov_b32_e32 v115, v113
	v_pk_mul_f32 v[114:115], v[116:117], v[114:115]
	s_nop 0
	v_add_f32_e32 v127, v114, v115

.LBB0_1317:
	s_and_saveexec_b64 s[6:7], s[54:55]
	s_cbranch_execz .LBB0_1319
	v_and_b32_e32 v113, 63, v148
	v_bfe_u32 v114, v148, 6, 4
	v_cndmask_b32_e64 v113, v114, v113, s[38:39]
	v_lshlrev_b32_e32 v114, 3, v177
	v_lshl_or_b32 v113, v113, 6, v114
	v_add_u32_e32 v113, 0x20000, v113
	ds_read_b64 v[114:115], v113
	v_and_b32_e32 v116, 64, v226
	v_xor_b32_e32 v113, 8, v226
	v_add_u32_e32 v116, 64, v116
	v_cmp_lt_i32_e32 vcc, v113, v116
	v_mov_b32_e32 v116, v96
	s_waitcnt lgkmcnt(0)
	v_mov_b32_e32 v117, v115
	v_cndmask_b32_e32 v113, v226, v113, vcc
	v_lshlrev_b32_e32 v113, 2, v113
	ds_bpermute_b32 v113, v113, v96
	s_waitcnt lgkmcnt(0)
	v_cndmask_b32_e64 v96, v113, -v113, s[36:37]
	v_mov_b32_e32 v115, v96
	v_pk_mul_f32 v[114:115], v[116:117], v[114:115]
	s_nop 0
	v_add_f32_e32 v96, v114, v115
.LBB0_1319:
	s_or_b64 exec, exec, s[6:7]
	v_mov_b64_e32 v[114:115], s[70:71]
	v_mul_f32_e32 v96, 0x3e16c740, v96
	v_mad_i64_i32 v[114:115], s[6:7], v148, s10, v[114:115]
	v_cvt_pk_bf16_f32 v96, v96, s0
	v_lshl_add_u64 v[114:115], v[128:129], 1, v[114:115]
	global_store_short v[114:115], v96, off
	v_add_u32_e32 v96, 1, v148
	s_and_saveexec_b64 s[6:7], s[54:55]
	s_cbranch_execz .LBB0_1321
	v_and_b32_e32 v113, 63, v96
	v_bfe_u32 v114, v96, 6, 4
	v_cndmask_b32_e64 v113, v114, v113, s[38:39]
	v_lshlrev_b32_e32 v114, 3, v177
	v_lshl_or_b32 v113, v113, 6, v114
	v_add_u32_e32 v113, 0x20000, v113
	ds_read_b64 v[114:115], v113
	v_and_b32_e32 v116, 64, v226
	v_xor_b32_e32 v113, 8, v226
	v_add_u32_e32 v116, 64, v116
	v_cmp_lt_i32_e32 vcc, v113, v116
	v_mov_b32_e32 v116, v97
	s_waitcnt lgkmcnt(0)
	v_mov_b32_e32 v117, v115
	v_cndmask_b32_e32 v113, v226, v113, vcc
	v_lshlrev_b32_e32 v113, 2, v113
	ds_bpermute_b32 v113, v113, v97
	s_waitcnt lgkmcnt(0)
	v_cndmask_b32_e64 v97, v113, -v113, s[36:37]
	v_mov_b32_e32 v115, v97
	v_pk_mul_f32 v[114:115], v[116:117], v[114:115]
	s_nop 0
	v_add_f32_e32 v97, v114, v115
.LBB0_1321:
	s_or_b64 exec, exec, s[6:7]
	v_mul_f32_e32 v97, 0x3e16c740, v97
	v_mov_b64_e32 v[114:115], s[70:71]
	v_cvt_pk_bf16_f32 v113, v97, s0
	v_mad_i64_i32 v[96:97], s[6:7], v96, s10, v[114:115]
	v_lshl_add_u64 v[96:97], v[128:129], 1, v[96:97]
	global_store_short v[96:97], v113, off
	v_add_u32_e32 v96, 2, v148
	s_and_saveexec_b64 s[6:7], s[54:55]
	s_cbranch_execz .LBB0_1323
	v_and_b32_e32 v97, 63, v96
	v_bfe_u32 v113, v96, 6, 4
	v_cndmask_b32_e64 v97, v113, v97, s[38:39]
	v_lshlrev_b32_e32 v113, 3, v177
	v_lshl_or_b32 v97, v97, 6, v113
	v_add_u32_e32 v97, 0x20000, v97
	ds_read_b64 v[114:115], v97
	v_and_b32_e32 v113, 64, v226
	v_xor_b32_e32 v97, 8, v226
	v_add_u32_e32 v113, 64, v113
	v_cmp_lt_i32_e32 vcc, v97, v113
	v_mov_b32_e32 v116, v98
	s_waitcnt lgkmcnt(0)
	v_mov_b32_e32 v117, v115
	v_cndmask_b32_e32 v97, v226, v97, vcc
	v_lshlrev_b32_e32 v97, 2, v97
	ds_bpermute_b32 v97, v97, v98
	s_waitcnt lgkmcnt(0)
	v_cndmask_b32_e64 v97, v97, -v97, s[36:37]
	v_mov_b32_e32 v115, v97
	v_pk_mul_f32 v[114:115], v[116:117], v[114:115]
	s_nop 0
	v_add_f32_e32 v98, v114, v115
.LBB0_1323:
	s_or_b64 exec, exec, s[6:7]
	v_mul_f32_e32 v97, 0x3e16c740, v98
	v_mov_b64_e32 v[114:115], s[70:71]
	v_cvt_pk_bf16_f32 v98, v97, s0
	v_mad_i64_i32 v[96:97], s[6:7], v96, s10, v[114:115]
	v_lshl_add_u64 v[96:97], v[128:129], 1, v[96:97]
	global_store_short v[96:97], v98, off
	v_add_u32_e32 v96, 3, v148
	s_and_saveexec_b64 s[6:7], s[54:55]
	s_cbranch_execz .LBB0_1325
	v_and_b32_e32 v97, 63, v96
	v_bfe_u32 v98, v96, 6, 4
	v_cndmask_b32_e64 v97, v98, v97, s[38:39]
	v_lshlrev_b32_e32 v98, 3, v177
	v_lshl_or_b32 v97, v97, 6, v98
	v_add_u32_e32 v97, 0x20000, v97
	ds_read_b64 v[114:115], v97
	v_and_b32_e32 v98, 64, v226
	v_xor_b32_e32 v97, 8, v226
	v_add_u32_e32 v98, 64, v98
	v_cmp_lt_i32_e32 vcc, v97, v98
	v_mov_b32_e32 v98, v99
	s_nop 0
	v_cndmask_b32_e32 v97, v226, v97, vcc
	v_lshlrev_b32_e32 v97, 2, v97
	ds_bpermute_b32 v97, v97, v99
	s_waitcnt lgkmcnt(0)
	v_cndmask_b32_e64 v97, v97, -v97, s[36:37]
	s_waitcnt lgkmcnt(0)
	v_mov_b32_e32 v99, v115
	v_mov_b32_e32 v115, v97
	v_pk_mul_f32 v[98:99], v[98:99], v[114:115]
	s_nop 0
	v_add_f32_e32 v99, v98, v99
.LBB0_1325:
	s_or_b64 exec, exec, s[6:7]
	v_mul_f32_e32 v97, 0x3e16c740, v99
	v_mov_b64_e32 v[98:99], s[70:71]
	v_cvt_pk_bf16_f32 v113, v97, s0
	v_mad_i64_i32 v[96:97], s[6:7], v96, s10, v[98:99]
	v_lshl_add_u64 v[96:97], v[128:129], 1, v[96:97]
	global_store_short v[96:97], v113, off
	v_add_u32_e32 v96, 8, v148
	s_and_saveexec_b64 s[6:7], s[54:55]
	s_cbranch_execz .LBB0_1327
	v_and_b32_e32 v97, 63, v96
	v_bfe_u32 v98, v96, 6, 4
	v_cndmask_b32_e64 v97, v98, v97, s[38:39]
	v_lshlrev_b32_e32 v98, 3, v177
	v_lshl_or_b32 v97, v97, 6, v98
	v_add_u32_e32 v97, 0x20000, v97
	ds_read_b64 v[98:99], v97
	v_and_b32_e32 v113, 64, v226
	v_xor_b32_e32 v97, 8, v226
	v_add_u32_e32 v113, 64, v113
	v_cmp_lt_i32_e32 vcc, v97, v113
	v_mov_b32_e32 v114, v100
	s_waitcnt lgkmcnt(0)
	v_mov_b32_e32 v115, v99
	v_cndmask_b32_e32 v97, v226, v97, vcc
	v_lshlrev_b32_e32 v97, 2, v97
	ds_bpermute_b32 v97, v97, v100
	s_waitcnt lgkmcnt(0)
	v_cndmask_b32_e64 v97, v97, -v97, s[36:37]
	v_mov_b32_e32 v99, v97
	v_pk_mul_f32 v[98:99], v[114:115], v[98:99]
	s_nop 0
	v_add_f32_e32 v100, v98, v99
.LBB0_1327:
	s_or_b64 exec, exec, s[6:7]
	v_mul_f32_e32 v97, 0x3e16c740, v100
	v_mov_b64_e32 v[98:99], s[70:71]
	v_cvt_pk_bf16_f32 v100, v97, s0
	v_mad_i64_i32 v[96:97], s[6:7], v96, s10, v[98:99]
	v_lshl_add_u64 v[96:97], v[128:129], 1, v[96:97]
	global_store_short v[96:97], v100, off
	v_add_u32_e32 v96, 9, v148
	s_and_saveexec_b64 s[6:7], s[54:55]
	s_cbranch_execz .LBB0_1329
	v_and_b32_e32 v97, 63, v96
	v_bfe_u32 v98, v96, 6, 4
	v_cndmask_b32_e64 v97, v98, v97, s[38:39]
	v_lshlrev_b32_e32 v98, 3, v177
	v_lshl_or_b32 v97, v97, 6, v98
	v_add_u32_e32 v97, 0x20000, v97
	ds_read_b64 v[98:99], v97
	v_and_b32_e32 v100, 64, v226
	v_xor_b32_e32 v97, 8, v226
	v_add_u32_e32 v100, 64, v100
	v_cmp_lt_i32_e32 vcc, v97, v100
	v_mov_b32_e32 v100, v101
	s_nop 0
	v_cndmask_b32_e32 v97, v226, v97, vcc
	v_lshlrev_b32_e32 v97, 2, v97
	ds_bpermute_b32 v97, v97, v101
	s_waitcnt lgkmcnt(0)
	v_cndmask_b32_e64 v97, v97, -v97, s[36:37]
	s_waitcnt lgkmcnt(0)
	v_mov_b32_e32 v101, v99
	v_mov_b32_e32 v99, v97
	v_pk_mul_f32 v[98:99], v[100:101], v[98:99]
	s_nop 0
	v_add_f32_e32 v101, v98, v99
.LBB0_1329:
	s_or_b64 exec, exec, s[6:7]
	v_mul_f32_e32 v97, 0x3e16c740, v101
	v_mov_b64_e32 v[98:99], s[70:71]
	v_cvt_pk_bf16_f32 v100, v97, s0
	v_mad_i64_i32 v[96:97], s[6:7], v96, s10, v[98:99]
	v_lshl_add_u64 v[96:97], v[128:129], 1, v[96:97]
	global_store_short v[96:97], v100, off
	v_add_u32_e32 v96, 10, v148
	s_and_saveexec_b64 s[6:7], s[54:55]
	s_cbranch_execz .LBB0_1331
	v_and_b32_e32 v97, 63, v96
	v_bfe_u32 v98, v96, 6, 4
	v_cndmask_b32_e64 v97, v98, v97, s[38:39]
	v_lshlrev_b32_e32 v98, 3, v177
	v_lshl_or_b32 v97, v97, 6, v98
	v_add_u32_e32 v97, 0x20000, v97
	ds_read_b64 v[98:99], v97
	v_and_b32_e32 v100, 64, v226
	v_xor_b32_e32 v97, 8, v226
	v_add_u32_e32 v100, 64, v100
	v_cmp_lt_i32_e32 vcc, v97, v100
	v_mov_b32_e32 v100, v102
	s_waitcnt lgkmcnt(0)
	v_mov_b32_e32 v101, v99
	v_cndmask_b32_e32 v97, v226, v97, vcc
	v_lshlrev_b32_e32 v97, 2, v97
	ds_bpermute_b32 v97, v97, v102
	s_waitcnt lgkmcnt(0)
	v_cndmask_b32_e64 v97, v97, -v97, s[36:37]
	v_mov_b32_e32 v99, v97
	v_pk_mul_f32 v[98:99], v[100:101], v[98:99]
	s_nop 0
	v_add_f32_e32 v102, v98, v99
.LBB0_1331:
	s_or_b64 exec, exec, s[6:7]
	v_mul_f32_e32 v97, 0x3e16c740, v102
	v_mov_b64_e32 v[98:99], s[70:71]
	v_cvt_pk_bf16_f32 v100, v97, s0
	v_mad_i64_i32 v[96:97], s[6:7], v96, s10, v[98:99]
	v_lshl_add_u64 v[96:97], v[128:129], 1, v[96:97]
	global_store_short v[96:97], v100, off
	v_add_u32_e32 v96, 11, v148
	s_and_saveexec_b64 s[6:7], s[54:55]
	s_cbranch_execz .LBB0_1333
	v_and_b32_e32 v97, 63, v96
	v_bfe_u32 v98, v96, 6, 4
	v_cndmask_b32_e64 v97, v98, v97, s[38:39]
	v_lshlrev_b32_e32 v98, 3, v177
	v_lshl_or_b32 v97, v97, 6, v98
	v_add_u32_e32 v97, 0x20000, v97
	ds_read_b64 v[98:99], v97
	v_and_b32_e32 v100, 64, v226
	v_xor_b32_e32 v97, 8, v226
	v_add_u32_e32 v100, 64, v100
	v_cmp_lt_i32_e32 vcc, v97, v100
	v_mov_b32_e32 v100, v103
	s_waitcnt lgkmcnt(0)
	v_mov_b32_e32 v101, v99
	v_cndmask_b32_e32 v97, v226, v97, vcc
	v_lshlrev_b32_e32 v97, 2, v97
	ds_bpermute_b32 v97, v97, v103
	s_waitcnt lgkmcnt(0)
	v_cndmask_b32_e64 v97, v97, -v97, s[36:37]
	v_mov_b32_e32 v99, v97
	v_pk_mul_f32 v[98:99], v[100:101], v[98:99]
	s_nop 0
	v_add_f32_e32 v103, v98, v99
.LBB0_1333:
	s_or_b64 exec, exec, s[6:7]
	v_mul_f32_e32 v97, 0x3e16c740, v103
	v_mov_b64_e32 v[98:99], s[70:71]
	v_cvt_pk_bf16_f32 v100, v97, s0
	v_mad_i64_i32 v[96:97], s[6:7], v96, s10, v[98:99]
	v_lshl_add_u64 v[96:97], v[128:129], 1, v[96:97]
	global_store_short v[96:97], v100, off
	v_add_u32_e32 v96, 16, v148
	s_and_saveexec_b64 s[6:7], s[54:55]
	s_cbranch_execz .LBB0_1335
	v_and_b32_e32 v97, 63, v96
	v_bfe_u32 v98, v96, 6, 4
	v_cndmask_b32_e64 v97, v98, v97, s[38:39]
	v_lshlrev_b32_e32 v98, 3, v177
	v_lshl_or_b32 v97, v97, 6, v98
	v_add_u32_e32 v97, 0x20000, v97
	ds_read_b64 v[98:99], v97
	v_and_b32_e32 v100, 64, v226
	v_xor_b32_e32 v97, 8, v226
	v_add_u32_e32 v100, 64, v100
	v_cmp_lt_i32_e32 vcc, v97, v100
	v_mov_b32_e32 v100, v104
	s_waitcnt lgkmcnt(0)
	v_mov_b32_e32 v101, v99
	v_cndmask_b32_e32 v97, v226, v97, vcc
	v_lshlrev_b32_e32 v97, 2, v97
	ds_bpermute_b32 v97, v97, v104
	s_waitcnt lgkmcnt(0)
	v_cndmask_b32_e64 v97, v97, -v97, s[36:37]
	v_mov_b32_e32 v99, v97
	v_pk_mul_f32 v[98:99], v[100:101], v[98:99]
	s_nop 0
	v_add_f32_e32 v104, v98, v99
.LBB0_1335:
	s_or_b64 exec, exec, s[6:7]
	v_mul_f32_e32 v97, 0x3e16c740, v104
	v_mov_b64_e32 v[98:99], s[70:71]
	v_cvt_pk_bf16_f32 v100, v97, s0
	v_mad_i64_i32 v[96:97], s[6:7], v96, s10, v[98:99]
	v_lshl_add_u64 v[96:97], v[128:129], 1, v[96:97]
	global_store_short v[96:97], v100, off
	v_add_u32_e32 v96, 17, v148
	s_and_saveexec_b64 s[6:7], s[54:55]
	s_cbranch_execz .LBB0_1337
	v_and_b32_e32 v97, 63, v96
	v_bfe_u32 v98, v96, 6, 4
	v_cndmask_b32_e64 v97, v98, v97, s[38:39]
	v_lshlrev_b32_e32 v98, 3, v177
	v_lshl_or_b32 v97, v97, 6, v98
	v_add_u32_e32 v97, 0x20000, v97
	ds_read_b64 v[98:99], v97
	v_and_b32_e32 v100, 64, v226
	v_xor_b32_e32 v97, 8, v226
	v_add_u32_e32 v100, 64, v100
	v_cmp_lt_i32_e32 vcc, v97, v100
	v_mov_b32_e32 v100, v105
	s_waitcnt lgkmcnt(0)
	v_mov_b32_e32 v101, v99
	v_cndmask_b32_e32 v97, v226, v97, vcc
	v_lshlrev_b32_e32 v97, 2, v97
	ds_bpermute_b32 v97, v97, v105
	s_waitcnt lgkmcnt(0)
	v_cndmask_b32_e64 v97, v97, -v97, s[36:37]
	v_mov_b32_e32 v99, v97
	v_pk_mul_f32 v[98:99], v[100:101], v[98:99]
	s_nop 0
	v_add_f32_e32 v105, v98, v99
.LBB0_1337:
	s_or_b64 exec, exec, s[6:7]
	v_mul_f32_e32 v97, 0x3e16c740, v105
	v_mov_b64_e32 v[98:99], s[70:71]
	v_cvt_pk_bf16_f32 v100, v97, s0
	v_mad_i64_i32 v[96:97], s[6:7], v96, s10, v[98:99]
	v_lshl_add_u64 v[96:97], v[128:129], 1, v[96:97]
	global_store_short v[96:97], v100, off
	v_add_u32_e32 v96, 18, v148
	s_and_saveexec_b64 s[6:7], s[54:55]
	s_cbranch_execz .LBB0_1339
	v_and_b32_e32 v97, 63, v96
	v_bfe_u32 v98, v96, 6, 4
	v_cndmask_b32_e64 v97, v98, v97, s[38:39]
	v_lshlrev_b32_e32 v98, 3, v177
	v_lshl_or_b32 v97, v97, 6, v98
	v_add_u32_e32 v97, 0x20000, v97
	ds_read_b64 v[98:99], v97
	v_and_b32_e32 v100, 64, v226
	v_xor_b32_e32 v97, 8, v226
	v_add_u32_e32 v100, 64, v100
	v_cmp_lt_i32_e32 vcc, v97, v100
	v_mov_b32_e32 v100, v106
	s_waitcnt lgkmcnt(0)
	v_mov_b32_e32 v101, v99
	v_cndmask_b32_e32 v97, v226, v97, vcc
	v_lshlrev_b32_e32 v97, 2, v97
	ds_bpermute_b32 v97, v97, v106
	s_waitcnt lgkmcnt(0)
	v_cndmask_b32_e64 v97, v97, -v97, s[36:37]
	v_mov_b32_e32 v99, v97
	v_pk_mul_f32 v[98:99], v[100:101], v[98:99]
	s_nop 0
	v_add_f32_e32 v106, v98, v99
.LBB0_1339:
	s_or_b64 exec, exec, s[6:7]
	v_mul_f32_e32 v97, 0x3e16c740, v106
	v_mov_b64_e32 v[98:99], s[70:71]
	v_cvt_pk_bf16_f32 v100, v97, s0
	v_mad_i64_i32 v[96:97], s[6:7], v96, s10, v[98:99]
	v_lshl_add_u64 v[96:97], v[128:129], 1, v[96:97]
	global_store_short v[96:97], v100, off
	v_add_u32_e32 v96, 19, v148
	s_and_saveexec_b64 s[6:7], s[54:55]
	s_cbranch_execz .LBB0_1341
	v_and_b32_e32 v97, 63, v96
	v_bfe_u32 v98, v96, 6, 4
	v_cndmask_b32_e64 v97, v98, v97, s[38:39]
	v_lshlrev_b32_e32 v98, 3, v177
	v_lshl_or_b32 v97, v97, 6, v98
	v_add_u32_e32 v97, 0x20000, v97
	ds_read_b64 v[98:99], v97
	v_and_b32_e32 v100, 64, v226
	v_xor_b32_e32 v97, 8, v226
	v_add_u32_e32 v100, 64, v100
	v_cmp_lt_i32_e32 vcc, v97, v100
	v_mov_b32_e32 v100, v107
	s_waitcnt lgkmcnt(0)
	v_mov_b32_e32 v101, v99
	v_cndmask_b32_e32 v97, v226, v97, vcc
	v_lshlrev_b32_e32 v97, 2, v97
	ds_bpermute_b32 v97, v97, v107
	s_waitcnt lgkmcnt(0)
	v_cndmask_b32_e64 v97, v97, -v97, s[36:37]
	v_mov_b32_e32 v99, v97
	v_pk_mul_f32 v[98:99], v[100:101], v[98:99]
	s_nop 0
	v_add_f32_e32 v107, v98, v99
.LBB0_1341:
	s_or_b64 exec, exec, s[6:7]
	v_mul_f32_e32 v97, 0x3e16c740, v107
	v_mov_b64_e32 v[98:99], s[70:71]
	v_cvt_pk_bf16_f32 v100, v97, s0
	v_mad_i64_i32 v[96:97], s[6:7], v96, s10, v[98:99]
	v_lshl_add_u64 v[96:97], v[128:129], 1, v[96:97]
	global_store_short v[96:97], v100, off
	v_add_u32_e32 v96, 24, v148
	s_and_saveexec_b64 s[6:7], s[54:55]
	s_cbranch_execz .LBB0_1343
	v_and_b32_e32 v97, 63, v96
	v_bfe_u32 v98, v96, 6, 4
	v_cndmask_b32_e64 v97, v98, v97, s[38:39]
	v_lshlrev_b32_e32 v98, 3, v177
	v_lshl_or_b32 v97, v97, 6, v98
	v_add_u32_e32 v97, 0x20000, v97
	ds_read_b64 v[98:99], v97
	v_and_b32_e32 v100, 64, v226
	v_xor_b32_e32 v97, 8, v226
	v_add_u32_e32 v100, 64, v100
	v_cmp_lt_i32_e32 vcc, v97, v100
	v_mov_b32_e32 v100, v108
	s_waitcnt lgkmcnt(0)
	v_mov_b32_e32 v101, v99
	v_cndmask_b32_e32 v97, v226, v97, vcc
	v_lshlrev_b32_e32 v97, 2, v97
	ds_bpermute_b32 v97, v97, v108
	s_waitcnt lgkmcnt(0)
	v_cndmask_b32_e64 v97, v97, -v97, s[36:37]
	v_mov_b32_e32 v99, v97
	v_pk_mul_f32 v[98:99], v[100:101], v[98:99]
	s_nop 0
	v_add_f32_e32 v108, v98, v99
.LBB0_1343:
	s_or_b64 exec, exec, s[6:7]
	v_mul_f32_e32 v97, 0x3e16c740, v108
	v_mov_b64_e32 v[98:99], s[70:71]
	v_cvt_pk_bf16_f32 v100, v97, s0
	v_mad_i64_i32 v[96:97], s[6:7], v96, s10, v[98:99]
	v_lshl_add_u64 v[96:97], v[128:129], 1, v[96:97]
	global_store_short v[96:97], v100, off
	v_add_u32_e32 v96, 25, v148
	s_and_saveexec_b64 s[6:7], s[54:55]
	s_cbranch_execz .LBB0_1345
	v_and_b32_e32 v97, 63, v96
	v_bfe_u32 v98, v96, 6, 4
	v_cndmask_b32_e64 v97, v98, v97, s[38:39]
	v_lshlrev_b32_e32 v98, 3, v177
	v_lshl_or_b32 v97, v97, 6, v98
	v_add_u32_e32 v97, 0x20000, v97
	ds_read_b64 v[98:99], v97
	v_and_b32_e32 v100, 64, v226
	v_xor_b32_e32 v97, 8, v226
	v_add_u32_e32 v100, 64, v100
	v_cmp_lt_i32_e32 vcc, v97, v100
	v_mov_b32_e32 v100, v109
	s_waitcnt lgkmcnt(0)
	v_mov_b32_e32 v101, v99
	v_cndmask_b32_e32 v97, v226, v97, vcc
	v_lshlrev_b32_e32 v97, 2, v97
	ds_bpermute_b32 v97, v97, v109
	s_waitcnt lgkmcnt(0)
	v_cndmask_b32_e64 v97, v97, -v97, s[36:37]
	v_mov_b32_e32 v99, v97
	v_pk_mul_f32 v[98:99], v[100:101], v[98:99]
	s_nop 0
	v_add_f32_e32 v109, v98, v99
.LBB0_1345:
	s_or_b64 exec, exec, s[6:7]
	v_mul_f32_e32 v97, 0x3e16c740, v109
	v_mov_b64_e32 v[98:99], s[70:71]
	v_cvt_pk_bf16_f32 v100, v97, s0
	v_mad_i64_i32 v[96:97], s[6:7], v96, s10, v[98:99]
	v_lshl_add_u64 v[96:97], v[128:129], 1, v[96:97]
	global_store_short v[96:97], v100, off
	v_add_u32_e32 v96, 26, v148
	s_and_saveexec_b64 s[6:7], s[54:55]
	s_cbranch_execz .LBB0_1347
	v_and_b32_e32 v97, 63, v96
	v_bfe_u32 v98, v96, 6, 4
	v_cndmask_b32_e64 v97, v98, v97, s[38:39]
	v_lshlrev_b32_e32 v98, 3, v177
	v_lshl_or_b32 v97, v97, 6, v98
	v_add_u32_e32 v97, 0x20000, v97
	ds_read_b64 v[98:99], v97
	v_and_b32_e32 v100, 64, v226
	v_xor_b32_e32 v97, 8, v226
	v_add_u32_e32 v100, 64, v100
	v_cmp_lt_i32_e32 vcc, v97, v100
	v_mov_b32_e32 v100, v110
	s_waitcnt lgkmcnt(0)
	v_mov_b32_e32 v101, v99
	v_cndmask_b32_e32 v97, v226, v97, vcc
	v_lshlrev_b32_e32 v97, 2, v97
	ds_bpermute_b32 v97, v97, v110
	s_waitcnt lgkmcnt(0)
	v_cndmask_b32_e64 v97, v97, -v97, s[36:37]
	v_mov_b32_e32 v99, v97
	v_pk_mul_f32 v[98:99], v[100:101], v[98:99]
	s_nop 0
	v_add_f32_e32 v110, v98, v99
.LBB0_1347:
	s_or_b64 exec, exec, s[6:7]
	v_mul_f32_e32 v97, 0x3e16c740, v110
	v_mov_b64_e32 v[98:99], s[70:71]
	v_cvt_pk_bf16_f32 v100, v97, s0
	v_mad_i64_i32 v[96:97], s[6:7], v96, s10, v[98:99]
	v_lshl_add_u64 v[96:97], v[128:129], 1, v[96:97]
	global_store_short v[96:97], v100, off
	v_add_u32_e32 v96, 27, v148
	s_and_saveexec_b64 s[6:7], s[54:55]
	s_cbranch_execz .LBB0_1349
	v_and_b32_e32 v97, 63, v96
	v_bfe_u32 v98, v96, 6, 4
	v_cndmask_b32_e64 v97, v98, v97, s[38:39]
	v_lshlrev_b32_e32 v98, 3, v177
	v_lshl_or_b32 v97, v97, 6, v98
	v_add_u32_e32 v97, 0x20000, v97
	ds_read_b64 v[98:99], v97
	v_and_b32_e32 v100, 64, v226
	v_xor_b32_e32 v97, 8, v226
	v_add_u32_e32 v100, 64, v100
	v_cmp_lt_i32_e32 vcc, v97, v100
	v_mov_b32_e32 v100, v111
	s_waitcnt lgkmcnt(0)
	v_mov_b32_e32 v101, v99
	v_cndmask_b32_e32 v97, v226, v97, vcc
	v_lshlrev_b32_e32 v97, 2, v97
	ds_bpermute_b32 v97, v97, v111
	s_waitcnt lgkmcnt(0)
	v_cndmask_b32_e64 v97, v97, -v97, s[36:37]
	v_mov_b32_e32 v99, v97
	v_pk_mul_f32 v[98:99], v[100:101], v[98:99]
	s_nop 0
	v_add_f32_e32 v111, v98, v99

.LBB0_1353:
	v_add_u32_e32 v66, 64, v148
	v_and_b32_e32 v64, 63, v148
	v_bfe_u32 v65, v66, 6, 4
	v_cndmask_b32_e64 v71, v65, v64, s[38:39]
	s_and_saveexec_b64 s[6:7], s[54:55]
	s_cbranch_execz .LBB0_1355
	v_lshlrev_b32_e32 v64, 3, v177
	v_lshl_or_b32 v64, v71, 6, v64
	v_add_u32_e32 v64, 0x20000, v64
	ds_read_b64 v[64:65], v64
	v_and_b32_e32 v68, 64, v226
	v_xor_b32_e32 v67, 8, v226
	v_add_u32_e32 v68, 64, v68
	v_cmp_lt_i32_e32 vcc, v67, v68
	v_mov_b32_e32 v68, v48
	s_waitcnt lgkmcnt(0)
	v_mov_b32_e32 v69, v65
	v_cndmask_b32_e32 v67, v226, v67, vcc
	v_lshlrev_b32_e32 v67, 2, v67
	ds_bpermute_b32 v67, v67, v48
	s_waitcnt lgkmcnt(0)
	v_cndmask_b32_e64 v48, v67, -v67, s[36:37]
	v_mov_b32_e32 v65, v48
	v_pk_mul_f32 v[64:65], v[68:69], v[64:65]
	s_nop 0
	v_add_f32_e32 v48, v64, v65
.LBB0_1355:
	s_or_b64 exec, exec, s[6:7]
	v_mov_b32_e32 v145, v129
	v_lshl_add_u64 v[64:65], v[144:145], 1, s[70:71]
	v_mul_f32_e32 v48, 0x3e16c740, v48
	v_cvt_pk_bf16_f32 v48, v48, s0
	v_mad_i64_i32 v[68:69], s[6:7], v66, s10, v[64:65]
	global_store_short v[68:69], v48, off
	v_add_u32_e32 v48, 0x41, v148
	v_and_b32_e32 v67, 63, v48
	v_bfe_u32 v68, v48, 6, 4
	v_cndmask_b32_e64 v84, v68, v67, s[38:39]
	s_and_saveexec_b64 s[6:7], s[54:55]
	s_cbranch_execz .LBB0_1357
	v_lshlrev_b32_e32 v67, 3, v177
	v_lshl_or_b32 v67, v84, 6, v67
	v_add_u32_e32 v67, 0x20000, v67
	ds_read_b64 v[68:69], v67
	v_and_b32_e32 v70, 64, v226
	v_xor_b32_e32 v67, 8, v226
	v_add_u32_e32 v70, 64, v70
	v_cmp_lt_i32_e32 vcc, v67, v70
	v_mov_b32_e32 v72, v49
	s_waitcnt lgkmcnt(0)
	v_mov_b32_e32 v73, v69
	v_cndmask_b32_e32 v67, v226, v67, vcc
	v_lshlrev_b32_e32 v67, 2, v67
	ds_bpermute_b32 v67, v67, v49
	s_waitcnt lgkmcnt(0)
	v_cndmask_b32_e64 v49, v67, -v67, s[36:37]
	v_mov_b32_e32 v69, v49
	v_pk_mul_f32 v[68:69], v[72:73], v[68:69]
	s_nop 0
	v_add_f32_e32 v49, v68, v69
.LBB0_1357:
	s_or_b64 exec, exec, s[6:7]
	v_mul_f32_e32 v49, 0x3e16c740, v49
	v_cvt_pk_bf16_f32 v49, v49, s0
	v_mad_i64_i32 v[68:69], s[6:7], v48, s10, v[64:65]
	v_add_u32_e32 v67, 0x42, v148
	global_store_short v[68:69], v49, off
	v_and_b32_e32 v49, 63, v67
	v_bfe_u32 v68, v67, 6, 4
	v_cndmask_b32_e64 v83, v68, v49, s[38:39]
	s_and_saveexec_b64 s[6:7], s[54:55]
	s_cbranch_execz .LBB0_1359
	v_lshlrev_b32_e32 v49, 3, v177
	v_lshl_or_b32 v49, v83, 6, v49
	v_add_u32_e32 v49, 0x20000, v49
	ds_read_b64 v[68:69], v49
	v_and_b32_e32 v70, 64, v226
	v_xor_b32_e32 v49, 8, v226
	v_add_u32_e32 v70, 64, v70
	v_cmp_lt_i32_e32 vcc, v49, v70
	v_mov_b32_e32 v72, v50
	s_waitcnt lgkmcnt(0)
	v_mov_b32_e32 v73, v69
	v_cndmask_b32_e32 v49, v226, v49, vcc
	v_lshlrev_b32_e32 v49, 2, v49
	ds_bpermute_b32 v49, v49, v50
	s_waitcnt lgkmcnt(0)
	v_cndmask_b32_e64 v49, v49, -v49, s[36:37]
	v_mov_b32_e32 v69, v49
	v_pk_mul_f32 v[68:69], v[72:73], v[68:69]
	s_nop 0
	v_add_f32_e32 v50, v68, v69
.LBB0_1359:
	s_or_b64 exec, exec, s[6:7]
	v_mul_f32_e32 v49, 0x3e16c740, v50
	v_cvt_pk_bf16_f32 v49, v49, s0
	v_mad_i64_i32 v[68:69], s[6:7], v67, s10, v[64:65]
	global_store_short v[68:69], v49, off
	v_add_u32_e32 v49, 0x43, v148
	v_and_b32_e32 v50, 63, v49
	v_bfe_u32 v68, v49, 6, 4
	v_cndmask_b32_e64 v82, v68, v50, s[38:39]
	s_and_saveexec_b64 s[6:7], s[54:55]
	s_cbranch_execz .LBB0_1361
	v_lshlrev_b32_e32 v50, 3, v177
	v_lshl_or_b32 v50, v82, 6, v50
	v_add_u32_e32 v50, 0x20000, v50
	ds_read_b64 v[68:69], v50
	v_and_b32_e32 v70, 64, v226
	v_xor_b32_e32 v50, 8, v226
	v_add_u32_e32 v70, 64, v70
	v_cmp_lt_i32_e32 vcc, v50, v70
	s_nop 1
	v_cndmask_b32_e32 v50, v226, v50, vcc
	v_lshlrev_b32_e32 v50, 2, v50
	ds_bpermute_b32 v70, v50, v51
	v_mov_b32_e32 v50, v51
	s_waitcnt lgkmcnt(0)
	v_cndmask_b32_e64 v70, v70, -v70, s[36:37]
	s_waitcnt lgkmcnt(0)
	v_mov_b32_e32 v51, v69
	v_mov_b32_e32 v69, v70
	v_pk_mul_f32 v[50:51], v[50:51], v[68:69]
	s_nop 0
	v_add_f32_e32 v51, v50, v51
.LBB0_1361:
	s_or_b64 exec, exec, s[6:7]
	v_mul_f32_e32 v50, 0x3e16c740, v51
	v_cvt_pk_bf16_f32 v68, v50, s0
	v_mad_i64_i32 v[50:51], s[6:7], v49, s10, v[64:65]
	global_store_short v[50:51], v68, off
	v_add_u32_e32 v68, 0x48, v148
	v_and_b32_e32 v50, 63, v68
	v_bfe_u32 v51, v68, 6, 4
	v_cndmask_b32_e64 v81, v51, v50, s[38:39]
	s_and_saveexec_b64 s[6:7], s[54:55]
	s_cbranch_execz .LBB0_1363
	v_lshlrev_b32_e32 v50, 3, v177
	v_lshl_or_b32 v50, v81, 6, v50
	v_add_u32_e32 v50, 0x20000, v50
	ds_read_b64 v[50:51], v50
	v_and_b32_e32 v70, 64, v226
	v_xor_b32_e32 v69, 8, v226
	v_add_u32_e32 v70, 64, v70
	v_cmp_lt_i32_e32 vcc, v69, v70
	v_mov_b32_e32 v72, v52
	s_waitcnt lgkmcnt(0)
	v_mov_b32_e32 v73, v51
	v_cndmask_b32_e32 v69, v226, v69, vcc
	v_lshlrev_b32_e32 v69, 2, v69
	ds_bpermute_b32 v69, v69, v52
	s_waitcnt lgkmcnt(0)
	v_cndmask_b32_e64 v52, v69, -v69, s[36:37]
	v_mov_b32_e32 v51, v52
	v_pk_mul_f32 v[50:51], v[72:73], v[50:51]
	s_nop 0
	v_add_f32_e32 v52, v50, v51
.LBB0_1363:
	s_or_b64 exec, exec, s[6:7]
	v_mul_f32_e32 v50, 0x3e16c740, v52
	v_cvt_pk_bf16_f32 v52, v50, s0
	v_mad_i64_i32 v[50:51], s[6:7], v68, s10, v[64:65]
	global_store_short v[50:51], v52, off
	v_add_u32_e32 v50, 0x49, v148
	v_and_b32_e32 v51, 63, v50
	v_bfe_u32 v52, v50, 6, 4
	v_cndmask_b32_e64 v80, v52, v51, s[38:39]
	s_and_saveexec_b64 s[6:7], s[54:55]
	s_cbranch_execz .LBB0_1365
	v_lshlrev_b32_e32 v51, 3, v177
	v_lshl_or_b32 v51, v80, 6, v51
	v_add_u32_e32 v51, 0x20000, v51
	ds_read_b64 v[72:73], v51
	v_and_b32_e32 v52, 64, v226
	v_xor_b32_e32 v51, 8, v226
	v_add_u32_e32 v52, 64, v52
	v_cmp_lt_i32_e32 vcc, v51, v52
	v_mov_b32_e32 v52, v53
	s_nop 0
	v_cndmask_b32_e32 v51, v226, v51, vcc
	v_lshlrev_b32_e32 v51, 2, v51
	ds_bpermute_b32 v51, v51, v53
	s_waitcnt lgkmcnt(0)
	v_cndmask_b32_e64 v51, v51, -v51, s[36:37]
	s_waitcnt lgkmcnt(0)
	v_mov_b32_e32 v53, v73
	v_mov_b32_e32 v73, v51
	v_pk_mul_f32 v[52:53], v[52:53], v[72:73]
	s_nop 0
	v_add_f32_e32 v53, v52, v53
.LBB0_1365:
	s_or_b64 exec, exec, s[6:7]
	v_mul_f32_e32 v51, 0x3e16c740, v53
	v_cvt_pk_bf16_f32 v51, v51, s0
	v_mad_i64_i32 v[52:53], s[6:7], v50, s10, v[64:65]
	v_add_u32_e32 v69, 0x4a, v148
	global_store_short v[52:53], v51, off
	v_and_b32_e32 v51, 63, v69
	v_bfe_u32 v52, v69, 6, 4
	v_cndmask_b32_e64 v79, v52, v51, s[38:39]
	s_and_saveexec_b64 s[6:7], s[54:55]
	s_cbranch_execz .LBB0_1367
	v_lshlrev_b32_e32 v51, 3, v177
	v_lshl_or_b32 v51, v79, 6, v51
	v_add_u32_e32 v51, 0x20000, v51
	ds_read_b64 v[52:53], v51
	v_and_b32_e32 v70, 64, v226
	v_xor_b32_e32 v51, 8, v226
	v_add_u32_e32 v70, 64, v70
	v_cmp_lt_i32_e32 vcc, v51, v70
	v_mov_b32_e32 v72, v54
	s_waitcnt lgkmcnt(0)
	v_mov_b32_e32 v73, v53
	v_cndmask_b32_e32 v51, v226, v51, vcc
	v_lshlrev_b32_e32 v51, 2, v51
	ds_bpermute_b32 v51, v51, v54
	s_waitcnt lgkmcnt(0)
	v_cndmask_b32_e64 v51, v51, -v51, s[36:37]
	v_mov_b32_e32 v53, v51
	v_pk_mul_f32 v[52:53], v[72:73], v[52:53]
	s_nop 0
	v_add_f32_e32 v54, v52, v53
.LBB0_1367:
	s_or_b64 exec, exec, s[6:7]
	v_mul_f32_e32 v51, 0x3e16c740, v54
	v_cvt_pk_bf16_f32 v51, v51, s0
	v_mad_i64_i32 v[52:53], s[6:7], v69, s10, v[64:65]
	global_store_short v[52:53], v51, off
	v_add_u32_e32 v51, 0x4b, v148
	v_and_b32_e32 v52, 63, v51
	v_bfe_u32 v53, v51, 6, 4
	v_cndmask_b32_e64 v78, v53, v52, s[38:39]
	s_and_saveexec_b64 s[6:7], s[54:55]
	s_cbranch_execz .LBB0_1369
	v_lshlrev_b32_e32 v52, 3, v177
	v_lshl_or_b32 v52, v78, 6, v52
	v_add_u32_e32 v52, 0x20000, v52
	ds_read_b64 v[52:53], v52
	v_and_b32_e32 v70, 64, v226
	v_xor_b32_e32 v54, 8, v226
	v_add_u32_e32 v70, 64, v70
	v_cmp_lt_i32_e32 vcc, v54, v70
	s_nop 1
	v_cndmask_b32_e32 v54, v226, v54, vcc
	v_lshlrev_b32_e32 v54, 2, v54
	ds_bpermute_b32 v70, v54, v55
	v_mov_b32_e32 v54, v55
	s_waitcnt lgkmcnt(0)
	v_cndmask_b32_e64 v70, v70, -v70, s[36:37]
	s_waitcnt lgkmcnt(0)
	v_mov_b32_e32 v55, v53
	v_mov_b32_e32 v53, v70
	v_pk_mul_f32 v[52:53], v[54:55], v[52:53]
	s_nop 0
	v_add_f32_e32 v55, v52, v53
.LBB0_1369:
	s_or_b64 exec, exec, s[6:7]
	v_mul_f32_e32 v52, 0x3e16c740, v55
	v_cvt_pk_bf16_f32 v54, v52, s0
	v_mad_i64_i32 v[52:53], s[6:7], v51, s10, v[64:65]
	v_add_u32_e32 v70, 0x50, v148
	global_store_short v[52:53], v54, off
	v_and_b32_e32 v52, 63, v70
	v_bfe_u32 v53, v70, 6, 4
	v_cndmask_b32_e64 v77, v53, v52, s[38:39]
	s_and_saveexec_b64 s[6:7], s[54:55]
	s_cbranch_execz .LBB0_1371
	v_lshlrev_b32_e32 v52, 3, v177
	v_lshl_or_b32 v52, v77, 6, v52
	v_add_u32_e32 v52, 0x20000, v52
	ds_read_b64 v[52:53], v52
	v_and_b32_e32 v55, 64, v226
	v_xor_b32_e32 v54, 8, v226
	v_add_u32_e32 v55, 64, v55
	v_cmp_lt_i32_e32 vcc, v54, v55
	s_nop 1
	v_cndmask_b32_e32 v54, v226, v54, vcc
	v_lshlrev_b32_e32 v54, 2, v54
	ds_bpermute_b32 v55, v54, v56
	v_mov_b32_e32 v54, v56
	s_waitcnt lgkmcnt(0)
	v_cndmask_b32_e64 v56, v55, -v55, s[36:37]
	s_waitcnt lgkmcnt(0)
	v_mov_b32_e32 v55, v53
	v_mov_b32_e32 v53, v56
	v_pk_mul_f32 v[52:53], v[54:55], v[52:53]
	s_nop 0
	v_add_f32_e32 v56, v52, v53
.LBB0_1371:
	s_or_b64 exec, exec, s[6:7]
	v_mul_f32_e32 v52, 0x3e16c740, v56
	v_cvt_pk_bf16_f32 v54, v52, s0
	v_mad_i64_i32 v[52:53], s[6:7], v70, s10, v[64:65]
	global_store_short v[52:53], v54, off
	v_add_u32_e32 v52, 0x51, v148
	v_and_b32_e32 v53, 63, v52
	v_bfe_u32 v54, v52, 6, 4
	v_cndmask_b32_e64 v76, v54, v53, s[38:39]
	s_and_saveexec_b64 s[6:7], s[54:55]
	s_cbranch_execz .LBB0_1373
	v_lshlrev_b32_e32 v53, 3, v177
	v_lshl_or_b32 v53, v76, 6, v53
	v_add_u32_e32 v53, 0x20000, v53
	ds_read_b64 v[54:55], v53
	v_and_b32_e32 v56, 64, v226
	v_xor_b32_e32 v53, 8, v226
	v_add_u32_e32 v56, 64, v56
	v_cmp_lt_i32_e32 vcc, v53, v56
	v_mov_b32_e32 v56, v57
	s_nop 0
	v_cndmask_b32_e32 v53, v226, v53, vcc
	v_lshlrev_b32_e32 v53, 2, v53
	ds_bpermute_b32 v53, v53, v57
	s_waitcnt lgkmcnt(0)
	v_cndmask_b32_e64 v53, v53, -v53, s[36:37]
	s_waitcnt lgkmcnt(0)
	v_mov_b32_e32 v57, v55
	v_mov_b32_e32 v55, v53
	v_pk_mul_f32 v[54:55], v[56:57], v[54:55]
	s_nop 0
	v_add_f32_e32 v57, v54, v55
.LBB0_1373:
	s_or_b64 exec, exec, s[6:7]
	v_mul_f32_e32 v53, 0x3e16c740, v57
	v_cvt_pk_bf16_f32 v53, v53, s0
	v_mad_i64_i32 v[54:55], s[6:7], v52, s10, v[64:65]
	v_add_u32_e32 v56, 0x52, v148
	global_store_short v[54:55], v53, off
	v_and_b32_e32 v53, 63, v56
	v_bfe_u32 v54, v56, 6, 4
	v_cndmask_b32_e64 v75, v54, v53, s[38:39]
	s_and_saveexec_b64 s[6:7], s[54:55]
	s_cbranch_execz .LBB0_1375
	v_lshlrev_b32_e32 v53, 3, v177
	v_lshl_or_b32 v53, v75, 6, v53
	v_add_u32_e32 v53, 0x20000, v53
	ds_read_b64 v[54:55], v53
	v_and_b32_e32 v57, 64, v226
	v_xor_b32_e32 v53, 8, v226
	v_add_u32_e32 v57, 64, v57
	v_cmp_lt_i32_e32 vcc, v53, v57
	v_mov_b32_e32 v72, v58
	s_waitcnt lgkmcnt(0)
	v_mov_b32_e32 v73, v55
	v_cndmask_b32_e32 v53, v226, v53, vcc
	v_lshlrev_b32_e32 v53, 2, v53
	ds_bpermute_b32 v53, v53, v58
	s_waitcnt lgkmcnt(0)
	v_cndmask_b32_e64 v53, v53, -v53, s[36:37]
	v_mov_b32_e32 v55, v53
	v_pk_mul_f32 v[54:55], v[72:73], v[54:55]
	s_nop 0
	v_add_f32_e32 v58, v54, v55
.LBB0_1375:
	s_or_b64 exec, exec, s[6:7]
	v_mul_f32_e32 v53, 0x3e16c740, v58
	v_cvt_pk_bf16_f32 v53, v53, s0
	v_mad_i64_i32 v[54:55], s[6:7], v56, s10, v[64:65]
	global_store_short v[54:55], v53, off
	v_add_u32_e32 v53, 0x53, v148
	v_and_b32_e32 v54, 63, v53
	v_bfe_u32 v55, v53, 6, 4
	v_cndmask_b32_e64 v74, v55, v54, s[38:39]
	s_and_saveexec_b64 s[6:7], s[54:55]
	s_cbranch_execz .LBB0_1377
	v_lshlrev_b32_e32 v54, 3, v177
	v_lshl_or_b32 v54, v74, 6, v54
	v_add_u32_e32 v54, 0x20000, v54
	ds_read_b64 v[54:55], v54
	v_and_b32_e32 v58, 64, v226
	v_xor_b32_e32 v57, 8, v226
	v_add_u32_e32 v58, 64, v58
	v_cmp_lt_i32_e32 vcc, v57, v58
	v_mov_b32_e32 v58, v59
	s_nop 0
	v_cndmask_b32_e32 v57, v226, v57, vcc
	v_lshlrev_b32_e32 v57, 2, v57
	ds_bpermute_b32 v57, v57, v59
	s_waitcnt lgkmcnt(0)
	v_cndmask_b32_e64 v57, v57, -v57, s[36:37]
	s_waitcnt lgkmcnt(0)
	v_mov_b32_e32 v59, v55
	v_mov_b32_e32 v55, v57
	v_pk_mul_f32 v[54:55], v[58:59], v[54:55]
	s_nop 0
	v_add_f32_e32 v59, v54, v55
.LBB0_1377:
	s_or_b64 exec, exec, s[6:7]
	v_mul_f32_e32 v54, 0x3e16c740, v59
	v_cvt_pk_bf16_f32 v57, v54, s0
	v_mad_i64_i32 v[54:55], s[6:7], v53, s10, v[64:65]
	global_store_short v[54:55], v57, off
	v_add_u32_e32 v57, 0x58, v148
	v_and_b32_e32 v54, 63, v57
	v_bfe_u32 v55, v57, 6, 4
	v_cndmask_b32_e64 v73, v55, v54, s[38:39]
	s_and_saveexec_b64 s[6:7], s[54:55]
	s_cbranch_execz .LBB0_1379
	v_lshlrev_b32_e32 v54, 3, v177
	v_lshl_or_b32 v54, v73, 6, v54
	v_add_u32_e32 v54, 0x20000, v54
	ds_read_b64 v[54:55], v54
	v_and_b32_e32 v59, 64, v226
	v_xor_b32_e32 v58, 8, v226
	v_add_u32_e32 v59, 64, v59
	v_cmp_lt_i32_e32 vcc, v58, v59
	s_nop 1
	v_cndmask_b32_e32 v58, v226, v58, vcc
	v_lshlrev_b32_e32 v58, 2, v58
	ds_bpermute_b32 v59, v58, v60
	v_mov_b32_e32 v58, v60
	s_waitcnt lgkmcnt(0)
	v_cndmask_b32_e64 v60, v59, -v59, s[36:37]
	s_waitcnt lgkmcnt(0)
	v_mov_b32_e32 v59, v55
	v_mov_b32_e32 v55, v60
	v_pk_mul_f32 v[54:55], v[58:59], v[54:55]
	s_nop 0
	v_add_f32_e32 v60, v54, v55
.LBB0_1379:
	s_or_b64 exec, exec, s[6:7]
	v_mul_f32_e32 v54, 0x3e16c740, v60
	v_cvt_pk_bf16_f32 v58, v54, s0
	v_mad_i64_i32 v[54:55], s[6:7], v57, s10, v[64:65]
	global_store_short v[54:55], v58, off
	v_add_u32_e32 v54, 0x59, v148
	v_and_b32_e32 v55, 63, v54
	v_bfe_u32 v58, v54, 6, 4
	v_cndmask_b32_e64 v72, v58, v55, s[38:39]
	s_and_saveexec_b64 s[6:7], s[54:55]
	s_cbranch_execz .LBB0_1381
	v_lshlrev_b32_e32 v55, 3, v177
	v_lshl_or_b32 v55, v72, 6, v55
	v_add_u32_e32 v55, 0x20000, v55
	ds_read_b64 v[58:59], v55
	v_and_b32_e32 v60, 64, v226
	v_xor_b32_e32 v55, 8, v226
	v_add_u32_e32 v60, 64, v60
	v_cmp_lt_i32_e32 vcc, v55, v60
	v_mov_b32_e32 v60, v61
	s_nop 0
	v_cndmask_b32_e32 v55, v226, v55, vcc
	v_lshlrev_b32_e32 v55, 2, v55
	ds_bpermute_b32 v55, v55, v61
	s_waitcnt lgkmcnt(0)
	v_cndmask_b32_e64 v55, v55, -v55, s[36:37]
	s_waitcnt lgkmcnt(0)
	v_mov_b32_e32 v61, v59
	v_mov_b32_e32 v59, v55
	v_pk_mul_f32 v[58:59], v[60:61], v[58:59]
	s_nop 0
	v_add_f32_e32 v61, v58, v59
.LBB0_1381:
	s_or_b64 exec, exec, s[6:7]
	v_mul_f32_e32 v55, 0x3e16c740, v61
	v_cvt_pk_bf16_f32 v55, v55, s0
	v_mad_i64_i32 v[58:59], s[6:7], v54, s10, v[64:65]
	global_store_short v[58:59], v55, off
	v_add_u32_e32 v58, 0x5a, v148
	v_and_b32_e32 v55, 63, v58
	v_bfe_u32 v59, v58, 6, 4
	v_cndmask_b32_e64 v60, v59, v55, s[38:39]
	s_and_saveexec_b64 s[6:7], s[54:55]
	s_cbranch_execz .LBB0_1383
	v_lshlrev_b32_e32 v55, 3, v177
	v_lshl_or_b32 v55, v60, 6, v55
	v_add_u32_e32 v55, 0x20000, v55
	ds_read_b64 v[86:87], v55
	v_and_b32_e32 v59, 64, v226
	v_xor_b32_e32 v55, 8, v226
	v_add_u32_e32 v59, 64, v59
	v_cmp_lt_i32_e32 vcc, v55, v59
	v_mov_b32_e32 v88, v62
	s_waitcnt lgkmcnt(0)
	v_mov_b32_e32 v89, v87
	v_cndmask_b32_e32 v55, v226, v55, vcc
	v_lshlrev_b32_e32 v55, 2, v55
	ds_bpermute_b32 v55, v55, v62
	s_waitcnt lgkmcnt(0)
	v_cndmask_b32_e64 v55, v55, -v55, s[36:37]
	v_mov_b32_e32 v87, v55
	v_pk_mul_f32 v[86:87], v[88:89], v[86:87]
	s_nop 0
	v_add_f32_e32 v62, v86, v87
.LBB0_1383:
	s_or_b64 exec, exec, s[6:7]
	v_mul_f32_e32 v55, 0x3e16c740, v62
	v_cvt_pk_bf16_f32 v55, v55, s0
	v_mad_i64_i32 v[86:87], s[6:7], v58, s10, v[64:65]
	global_store_short v[86:87], v55, off
	v_add_u32_e32 v55, 0x5b, v148
	v_and_b32_e32 v59, 63, v55
	v_bfe_u32 v61, v55, 6, 4
	v_cndmask_b32_e64 v59, v61, v59, s[38:39]
	s_and_saveexec_b64 s[6:7], s[54:55]
	s_cbranch_execz .LBB0_1385
	v_lshlrev_b32_e32 v61, 3, v177
	v_lshl_or_b32 v61, v59, 6, v61
	v_add_u32_e32 v61, 0x20000, v61
	ds_read_b64 v[86:87], v61
	v_and_b32_e32 v62, 64, v226
	v_xor_b32_e32 v61, 8, v226
	v_add_u32_e32 v62, 64, v62
	v_cmp_lt_i32_e32 vcc, v61, v62
	v_mov_b32_e32 v62, v63
	s_nop 0
	v_cndmask_b32_e32 v61, v226, v61, vcc
	v_lshlrev_b32_e32 v61, 2, v61
	ds_bpermute_b32 v61, v61, v63
	s_waitcnt lgkmcnt(0)
	v_cndmask_b32_e64 v61, v61, -v61, s[36:37]
	s_waitcnt lgkmcnt(0)
	v_mov_b32_e32 v63, v87
	v_mov_b32_e32 v87, v61
	v_pk_mul_f32 v[62:63], v[62:63], v[86:87]
	s_nop 0
	v_add_f32_e32 v63, v62, v63

.LBB0_1387:
	s_and_saveexec_b64 s[6:7], s[54:55]
	s_cbranch_execz .LBB0_1389
	v_lshlrev_b32_e32 v61, 3, v177
	v_lshl_or_b32 v61, v71, 6, v61
	v_add_u32_e32 v61, 0x20000, v61
	ds_read_b64 v[62:63], v61
	v_and_b32_e32 v64, 64, v226
	v_xor_b32_e32 v61, 8, v226
	v_add_u32_e32 v64, 64, v64
	v_cmp_lt_i32_e32 vcc, v61, v64
	v_mov_b32_e32 v64, v32
	s_waitcnt lgkmcnt(0)
	v_mov_b32_e32 v65, v63
	v_cndmask_b32_e32 v61, v226, v61, vcc
	v_lshlrev_b32_e32 v61, 2, v61
	ds_bpermute_b32 v61, v61, v32
	s_waitcnt lgkmcnt(0)
	v_cndmask_b32_e64 v32, v61, -v61, s[36:37]
	v_mov_b32_e32 v63, v32
	v_pk_mul_f32 v[62:63], v[64:65], v[62:63]
	s_nop 0
	v_add_f32_e32 v32, v62, v63
.LBB0_1389:
	s_or_b64 exec, exec, s[6:7]
	v_mad_i64_i32 v[62:63], s[6:7], v66, s10, 0
	v_mul_f32_e32 v32, 0x3e16c740, v32
	v_lshl_add_u64 v[62:63], s[70:71], 0, v[62:63]
	v_cvt_pk_bf16_f32 v32, v32, s0
	v_lshl_add_u64 v[62:63], v[128:129], 1, v[62:63]
	global_store_short v[62:63], v32, off
	s_and_saveexec_b64 s[6:7], s[54:55]
	s_cbranch_execz .LBB0_1391
	v_lshlrev_b32_e32 v32, 3, v177
	v_lshl_or_b32 v32, v84, 6, v32
	v_add_u32_e32 v32, 0x20000, v32
	ds_read_b64 v[62:63], v32
	v_and_b32_e32 v61, 64, v226
	v_xor_b32_e32 v32, 8, v226
	v_add_u32_e32 v61, 64, v61
	v_cmp_lt_i32_e32 vcc, v32, v61
	s_nop 1
	v_cndmask_b32_e32 v32, v226, v32, vcc
	v_lshlrev_b32_e32 v32, 2, v32
	ds_bpermute_b32 v61, v32, v33
	v_mov_b32_e32 v32, v33
	s_waitcnt lgkmcnt(0)
	v_cndmask_b32_e64 v61, v61, -v61, s[36:37]
	s_waitcnt lgkmcnt(0)
	v_mov_b32_e32 v33, v63
	v_mov_b32_e32 v63, v61
	v_pk_mul_f32 v[32:33], v[32:33], v[62:63]
	s_nop 0
	v_add_f32_e32 v33, v32, v33
.LBB0_1391:
	s_or_b64 exec, exec, s[6:7]
	v_mad_i64_i32 v[62:63], s[6:7], v48, s10, 0
	v_mul_f32_e32 v32, 0x3e16c740, v33
	v_cvt_pk_bf16_f32 v48, v32, s0
	v_lshl_add_u64 v[32:33], s[70:71], 0, v[62:63]
	v_lshl_add_u64 v[32:33], v[128:129], 1, v[32:33]
	global_store_short v[32:33], v48, off
	s_and_saveexec_b64 s[6:7], s[54:55]
	s_cbranch_execz .LBB0_1393
	v_lshlrev_b32_e32 v32, 3, v177
	v_lshl_or_b32 v32, v83, 6, v32
	v_add_u32_e32 v32, 0x20000, v32
	ds_read_b64 v[32:33], v32
	v_and_b32_e32 v61, 64, v226
	v_xor_b32_e32 v48, 8, v226
	v_add_u32_e32 v61, 64, v61
	v_cmp_lt_i32_e32 vcc, v48, v61
	v_mov_b32_e32 v62, v34
	s_waitcnt lgkmcnt(0)
	v_mov_b32_e32 v63, v33
	v_cndmask_b32_e32 v48, v226, v48, vcc
	v_lshlrev_b32_e32 v48, 2, v48
	ds_bpermute_b32 v48, v48, v34
	s_waitcnt lgkmcnt(0)
	v_cndmask_b32_e64 v34, v48, -v48, s[36:37]
	v_mov_b32_e32 v33, v34
	v_pk_mul_f32 v[32:33], v[62:63], v[32:33]
	s_nop 0
	v_add_f32_e32 v34, v32, v33
.LBB0_1393:
	s_or_b64 exec, exec, s[6:7]
	v_mad_i64_i32 v[32:33], s[6:7], v67, s10, 0
	v_mul_f32_e32 v34, 0x3e16c740, v34
	v_lshl_add_u64 v[32:33], s[70:71], 0, v[32:33]
	v_cvt_pk_bf16_f32 v34, v34, s0
	v_lshl_add_u64 v[32:33], v[128:129], 1, v[32:33]
	global_store_short v[32:33], v34, off
	s_and_saveexec_b64 s[6:7], s[54:55]
	s_cbranch_execz .LBB0_1395
	v_lshlrev_b32_e32 v32, 3, v177
	v_lshl_or_b32 v32, v82, 6, v32
	v_add_u32_e32 v32, 0x20000, v32
	ds_read_b64 v[32:33], v32
	v_and_b32_e32 v48, 64, v226
	v_xor_b32_e32 v34, 8, v226
	v_add_u32_e32 v48, 64, v48
	v_cmp_lt_i32_e32 vcc, v34, v48
	s_nop 1
	v_cndmask_b32_e32 v34, v226, v34, vcc
	v_lshlrev_b32_e32 v34, 2, v34
	ds_bpermute_b32 v48, v34, v35
	v_mov_b32_e32 v34, v35
	s_waitcnt lgkmcnt(0)
	v_cndmask_b32_e64 v48, v48, -v48, s[36:37]
	s_waitcnt lgkmcnt(0)
	v_mov_b32_e32 v35, v33
	v_mov_b32_e32 v33, v48
	v_pk_mul_f32 v[32:33], v[34:35], v[32:33]
	s_nop 0
	v_add_f32_e32 v35, v32, v33
.LBB0_1395:
	s_or_b64 exec, exec, s[6:7]
	v_mad_i64_i32 v[32:33], s[6:7], v49, s10, 0
	v_mul_f32_e32 v34, 0x3e16c740, v35
	v_lshl_add_u64 v[32:33], s[70:71], 0, v[32:33]
	v_cvt_pk_bf16_f32 v34, v34, s0
	v_lshl_add_u64 v[32:33], v[128:129], 1, v[32:33]
	global_store_short v[32:33], v34, off
	s_and_saveexec_b64 s[6:7], s[54:55]
	s_cbranch_execz .LBB0_1397
	v_lshlrev_b32_e32 v32, 3, v177
	v_lshl_or_b32 v32, v81, 6, v32
	v_add_u32_e32 v32, 0x20000, v32
	ds_read_b64 v[32:33], v32
	v_and_b32_e32 v35, 64, v226
	v_xor_b32_e32 v34, 8, v226
	v_add_u32_e32 v35, 64, v35
	v_cmp_lt_i32_e32 vcc, v34, v35
	s_nop 1
	v_cndmask_b32_e32 v34, v226, v34, vcc
	v_lshlrev_b32_e32 v34, 2, v34
	ds_bpermute_b32 v35, v34, v36
	v_mov_b32_e32 v34, v36
	s_waitcnt lgkmcnt(0)
	v_cndmask_b32_e64 v36, v35, -v35, s[36:37]
	s_waitcnt lgkmcnt(0)
	v_mov_b32_e32 v35, v33
	v_mov_b32_e32 v33, v36
	v_pk_mul_f32 v[32:33], v[34:35], v[32:33]
	s_nop 0
	v_add_f32_e32 v36, v32, v33
.LBB0_1397:
	s_or_b64 exec, exec, s[6:7]
	v_mad_i64_i32 v[32:33], s[6:7], v68, s10, 0
	v_mul_f32_e32 v34, 0x3e16c740, v36
	v_lshl_add_u64 v[32:33], s[70:71], 0, v[32:33]
	v_cvt_pk_bf16_f32 v34, v34, s0
	v_lshl_add_u64 v[32:33], v[128:129], 1, v[32:33]
	global_store_short v[32:33], v34, off
	s_and_saveexec_b64 s[6:7], s[54:55]
	s_cbranch_execz .LBB0_1399
	v_lshlrev_b32_e32 v32, 3, v177
	v_lshl_or_b32 v32, v80, 6, v32
	v_add_u32_e32 v32, 0x20000, v32
	ds_read_b64 v[32:33], v32
	v_and_b32_e32 v35, 64, v226
	v_xor_b32_e32 v34, 8, v226
	v_add_u32_e32 v35, 64, v35
	v_cmp_lt_i32_e32 vcc, v34, v35
	s_nop 1
	v_cndmask_b32_e32 v34, v226, v34, vcc
	v_lshlrev_b32_e32 v34, 2, v34
	ds_bpermute_b32 v35, v34, v37
	v_mov_b32_e32 v34, v37
	s_waitcnt lgkmcnt(0)
	v_cndmask_b32_e64 v36, v35, -v35, s[36:37]
	s_waitcnt lgkmcnt(0)
	v_mov_b32_e32 v35, v33
	v_mov_b32_e32 v33, v36
	v_pk_mul_f32 v[32:33], v[34:35], v[32:33]
	s_nop 0
	v_add_f32_e32 v37, v32, v33
.LBB0_1399:
	s_or_b64 exec, exec, s[6:7]
	v_mad_i64_i32 v[32:33], s[6:7], v50, s10, 0
	v_mul_f32_e32 v34, 0x3e16c740, v37
	v_lshl_add_u64 v[32:33], s[70:71], 0, v[32:33]
	v_cvt_pk_bf16_f32 v34, v34, s0
	v_lshl_add_u64 v[32:33], v[128:129], 1, v[32:33]
	global_store_short v[32:33], v34, off
	s_and_saveexec_b64 s[6:7], s[54:55]
	s_cbranch_execz .LBB0_1401
	v_lshlrev_b32_e32 v32, 3, v177
	v_lshl_or_b32 v32, v79, 6, v32
	v_add_u32_e32 v32, 0x20000, v32
	ds_read_b64 v[32:33], v32
	v_and_b32_e32 v35, 64, v226
	v_xor_b32_e32 v34, 8, v226
	v_add_u32_e32 v35, 64, v35
	v_cmp_lt_i32_e32 vcc, v34, v35
	s_nop 1
	v_cndmask_b32_e32 v34, v226, v34, vcc
	v_lshlrev_b32_e32 v34, 2, v34
	ds_bpermute_b32 v35, v34, v38
	v_mov_b32_e32 v34, v38
	s_waitcnt lgkmcnt(0)
	v_cndmask_b32_e64 v36, v35, -v35, s[36:37]
	s_waitcnt lgkmcnt(0)
	v_mov_b32_e32 v35, v33
	v_mov_b32_e32 v33, v36
	v_pk_mul_f32 v[32:33], v[34:35], v[32:33]
	s_nop 0
	v_add_f32_e32 v38, v32, v33
.LBB0_1401:
	s_or_b64 exec, exec, s[6:7]
	v_mad_i64_i32 v[32:33], s[6:7], v69, s10, 0
	v_mul_f32_e32 v34, 0x3e16c740, v38
	v_lshl_add_u64 v[32:33], s[70:71], 0, v[32:33]
	v_cvt_pk_bf16_f32 v34, v34, s0
	v_lshl_add_u64 v[32:33], v[128:129], 1, v[32:33]
	global_store_short v[32:33], v34, off
	s_and_saveexec_b64 s[6:7], s[54:55]
	s_cbranch_execz .LBB0_1403
	v_lshlrev_b32_e32 v32, 3, v177
	v_lshl_or_b32 v32, v78, 6, v32
	v_add_u32_e32 v32, 0x20000, v32
	ds_read_b64 v[32:33], v32
	v_and_b32_e32 v35, 64, v226
	v_xor_b32_e32 v34, 8, v226
	v_add_u32_e32 v35, 64, v35
	v_cmp_lt_i32_e32 vcc, v34, v35
	s_nop 1
	v_cndmask_b32_e32 v34, v226, v34, vcc
	v_lshlrev_b32_e32 v34, 2, v34
	ds_bpermute_b32 v35, v34, v39
	v_mov_b32_e32 v34, v39
	s_waitcnt lgkmcnt(0)
	v_cndmask_b32_e64 v36, v35, -v35, s[36:37]
	s_waitcnt lgkmcnt(0)
	v_mov_b32_e32 v35, v33
	v_mov_b32_e32 v33, v36
	v_pk_mul_f32 v[32:33], v[34:35], v[32:33]
	s_nop 0
	v_add_f32_e32 v39, v32, v33
.LBB0_1403:
	s_or_b64 exec, exec, s[6:7]
	v_mad_i64_i32 v[32:33], s[6:7], v51, s10, 0
	v_mul_f32_e32 v34, 0x3e16c740, v39
	v_lshl_add_u64 v[32:33], s[70:71], 0, v[32:33]
	v_cvt_pk_bf16_f32 v34, v34, s0
	v_lshl_add_u64 v[32:33], v[128:129], 1, v[32:33]
	global_store_short v[32:33], v34, off
	s_and_saveexec_b64 s[6:7], s[54:55]
	s_cbranch_execz .LBB0_1405
	v_lshlrev_b32_e32 v32, 3, v177
	v_lshl_or_b32 v32, v77, 6, v32
	v_add_u32_e32 v32, 0x20000, v32
	ds_read_b64 v[32:33], v32
	v_and_b32_e32 v35, 64, v226
	v_xor_b32_e32 v34, 8, v226
	v_add_u32_e32 v35, 64, v35
	v_cmp_lt_i32_e32 vcc, v34, v35
	s_nop 1
	v_cndmask_b32_e32 v34, v226, v34, vcc
	v_lshlrev_b32_e32 v34, 2, v34
	ds_bpermute_b32 v35, v34, v40
	v_mov_b32_e32 v34, v40
	s_waitcnt lgkmcnt(0)
	v_cndmask_b32_e64 v36, v35, -v35, s[36:37]
	s_waitcnt lgkmcnt(0)
	v_mov_b32_e32 v35, v33
	v_mov_b32_e32 v33, v36
	v_pk_mul_f32 v[32:33], v[34:35], v[32:33]
	s_nop 0
	v_add_f32_e32 v40, v32, v33
.LBB0_1405:
	s_or_b64 exec, exec, s[6:7]
	v_mad_i64_i32 v[32:33], s[6:7], v70, s10, 0
	v_mul_f32_e32 v34, 0x3e16c740, v40
	v_lshl_add_u64 v[32:33], s[70:71], 0, v[32:33]
	v_cvt_pk_bf16_f32 v34, v34, s0
	v_lshl_add_u64 v[32:33], v[128:129], 1, v[32:33]
	global_store_short v[32:33], v34, off
	s_and_saveexec_b64 s[6:7], s[54:55]
	s_cbranch_execz .LBB0_1407
	v_lshlrev_b32_e32 v32, 3, v177
	v_lshl_or_b32 v32, v76, 6, v32
	v_add_u32_e32 v32, 0x20000, v32
	ds_read_b64 v[32:33], v32
	v_and_b32_e32 v35, 64, v226
	v_xor_b32_e32 v34, 8, v226
	v_add_u32_e32 v35, 64, v35
	v_cmp_lt_i32_e32 vcc, v34, v35
	s_nop 1
	v_cndmask_b32_e32 v34, v226, v34, vcc
	v_lshlrev_b32_e32 v34, 2, v34
	ds_bpermute_b32 v35, v34, v41
	v_mov_b32_e32 v34, v41
	s_waitcnt lgkmcnt(0)
	v_cndmask_b32_e64 v36, v35, -v35, s[36:37]
	s_waitcnt lgkmcnt(0)
	v_mov_b32_e32 v35, v33
	v_mov_b32_e32 v33, v36
	v_pk_mul_f32 v[32:33], v[34:35], v[32:33]
	s_nop 0
	v_add_f32_e32 v41, v32, v33
.LBB0_1407:
	s_or_b64 exec, exec, s[6:7]
	v_mad_i64_i32 v[32:33], s[6:7], v52, s10, 0
	v_mul_f32_e32 v34, 0x3e16c740, v41
	v_lshl_add_u64 v[32:33], s[70:71], 0, v[32:33]
	v_cvt_pk_bf16_f32 v34, v34, s0
	v_lshl_add_u64 v[32:33], v[128:129], 1, v[32:33]
	global_store_short v[32:33], v34, off
	s_and_saveexec_b64 s[6:7], s[54:55]
	s_cbranch_execz .LBB0_1409
	v_lshlrev_b32_e32 v32, 3, v177
	v_lshl_or_b32 v32, v75, 6, v32
	v_add_u32_e32 v32, 0x20000, v32
	ds_read_b64 v[32:33], v32
	v_and_b32_e32 v35, 64, v226
	v_xor_b32_e32 v34, 8, v226
	v_add_u32_e32 v35, 64, v35
	v_cmp_lt_i32_e32 vcc, v34, v35
	s_nop 1
	v_cndmask_b32_e32 v34, v226, v34, vcc
	v_lshlrev_b32_e32 v34, 2, v34
	ds_bpermute_b32 v35, v34, v42
	v_mov_b32_e32 v34, v42
	s_waitcnt lgkmcnt(0)
	v_cndmask_b32_e64 v36, v35, -v35, s[36:37]
	s_waitcnt lgkmcnt(0)
	v_mov_b32_e32 v35, v33
	v_mov_b32_e32 v33, v36
	v_pk_mul_f32 v[32:33], v[34:35], v[32:33]
	s_nop 0
	v_add_f32_e32 v42, v32, v33
.LBB0_1409:
	s_or_b64 exec, exec, s[6:7]
	v_mad_i64_i32 v[32:33], s[6:7], v56, s10, 0
	v_mul_f32_e32 v34, 0x3e16c740, v42
	v_lshl_add_u64 v[32:33], s[70:71], 0, v[32:33]
	v_cvt_pk_bf16_f32 v34, v34, s0
	v_lshl_add_u64 v[32:33], v[128:129], 1, v[32:33]
	global_store_short v[32:33], v34, off
	s_and_saveexec_b64 s[6:7], s[54:55]
	s_cbranch_execz .LBB0_1411
	v_lshlrev_b32_e32 v32, 3, v177
	v_lshl_or_b32 v32, v74, 6, v32
	v_add_u32_e32 v32, 0x20000, v32
	ds_read_b64 v[32:33], v32
	v_and_b32_e32 v35, 64, v226
	v_xor_b32_e32 v34, 8, v226
	v_add_u32_e32 v35, 64, v35
	v_cmp_lt_i32_e32 vcc, v34, v35
	s_nop 1
	v_cndmask_b32_e32 v34, v226, v34, vcc
	v_lshlrev_b32_e32 v34, 2, v34
	ds_bpermute_b32 v35, v34, v43
	v_mov_b32_e32 v34, v43
	s_waitcnt lgkmcnt(0)
	v_cndmask_b32_e64 v36, v35, -v35, s[36:37]
	s_waitcnt lgkmcnt(0)
	v_mov_b32_e32 v35, v33
	v_mov_b32_e32 v33, v36
	v_pk_mul_f32 v[32:33], v[34:35], v[32:33]
	s_nop 0
	v_add_f32_e32 v43, v32, v33
.LBB0_1411:
	s_or_b64 exec, exec, s[6:7]
	v_mad_i64_i32 v[32:33], s[6:7], v53, s10, 0
	v_mul_f32_e32 v34, 0x3e16c740, v43
	v_lshl_add_u64 v[32:33], s[70:71], 0, v[32:33]
	v_cvt_pk_bf16_f32 v34, v34, s0
	v_lshl_add_u64 v[32:33], v[128:129], 1, v[32:33]
	global_store_short v[32:33], v34, off
	s_and_saveexec_b64 s[6:7], s[54:55]
	s_cbranch_execz .LBB0_1413
	v_lshlrev_b32_e32 v32, 3, v177
	v_lshl_or_b32 v32, v73, 6, v32
	v_add_u32_e32 v32, 0x20000, v32
	ds_read_b64 v[32:33], v32
	v_and_b32_e32 v35, 64, v226
	v_xor_b32_e32 v34, 8, v226
	v_add_u32_e32 v35, 64, v35
	v_cmp_lt_i32_e32 vcc, v34, v35
	s_nop 1
	v_cndmask_b32_e32 v34, v226, v34, vcc
	v_lshlrev_b32_e32 v34, 2, v34
	ds_bpermute_b32 v35, v34, v44
	v_mov_b32_e32 v34, v44
	s_waitcnt lgkmcnt(0)
	v_cndmask_b32_e64 v36, v35, -v35, s[36:37]
	s_waitcnt lgkmcnt(0)
	v_mov_b32_e32 v35, v33
	v_mov_b32_e32 v33, v36
	v_pk_mul_f32 v[32:33], v[34:35], v[32:33]
	s_nop 0
	v_add_f32_e32 v44, v32, v33
.LBB0_1413:
	s_or_b64 exec, exec, s[6:7]
	v_mad_i64_i32 v[32:33], s[6:7], v57, s10, 0
	v_mul_f32_e32 v34, 0x3e16c740, v44
	v_lshl_add_u64 v[32:33], s[70:71], 0, v[32:33]
	v_cvt_pk_bf16_f32 v34, v34, s0
	v_lshl_add_u64 v[32:33], v[128:129], 1, v[32:33]
	global_store_short v[32:33], v34, off
	s_and_saveexec_b64 s[6:7], s[54:55]
	s_cbranch_execz .LBB0_1415
	v_lshlrev_b32_e32 v32, 3, v177
	v_lshl_or_b32 v32, v72, 6, v32
	v_add_u32_e32 v32, 0x20000, v32
	ds_read_b64 v[32:33], v32
	v_and_b32_e32 v35, 64, v226
	v_xor_b32_e32 v34, 8, v226
	v_add_u32_e32 v35, 64, v35
	v_cmp_lt_i32_e32 vcc, v34, v35
	s_nop 1
	v_cndmask_b32_e32 v34, v226, v34, vcc
	v_lshlrev_b32_e32 v34, 2, v34
	ds_bpermute_b32 v35, v34, v45
	v_mov_b32_e32 v34, v45
	s_waitcnt lgkmcnt(0)
	v_cndmask_b32_e64 v36, v35, -v35, s[36:37]
	s_waitcnt lgkmcnt(0)
	v_mov_b32_e32 v35, v33
	v_mov_b32_e32 v33, v36
	v_pk_mul_f32 v[32:33], v[34:35], v[32:33]
	s_nop 0
	v_add_f32_e32 v45, v32, v33
.LBB0_1415:
	s_or_b64 exec, exec, s[6:7]
	v_mad_i64_i32 v[32:33], s[6:7], v54, s10, 0
	v_mul_f32_e32 v34, 0x3e16c740, v45
	v_lshl_add_u64 v[32:33], s[70:71], 0, v[32:33]
	v_cvt_pk_bf16_f32 v34, v34, s0
	v_lshl_add_u64 v[32:33], v[128:129], 1, v[32:33]
	global_store_short v[32:33], v34, off
	s_and_saveexec_b64 s[6:7], s[54:55]
	s_cbranch_execz .LBB0_1417
	v_lshlrev_b32_e32 v32, 3, v177
	v_lshl_or_b32 v32, v60, 6, v32
	v_add_u32_e32 v32, 0x20000, v32
	ds_read_b64 v[32:33], v32
	v_and_b32_e32 v35, 64, v226
	v_xor_b32_e32 v34, 8, v226
	v_add_u32_e32 v35, 64, v35
	v_cmp_lt_i32_e32 vcc, v34, v35
	s_nop 1
	v_cndmask_b32_e32 v34, v226, v34, vcc
	v_lshlrev_b32_e32 v34, 2, v34
	ds_bpermute_b32 v35, v34, v46
	v_mov_b32_e32 v34, v46
	s_waitcnt lgkmcnt(0)
	v_cndmask_b32_e64 v36, v35, -v35, s[36:37]
	s_waitcnt lgkmcnt(0)
	v_mov_b32_e32 v35, v33
	v_mov_b32_e32 v33, v36
	v_pk_mul_f32 v[32:33], v[34:35], v[32:33]
	s_nop 0
	v_add_f32_e32 v46, v32, v33
.LBB0_1417:
	s_or_b64 exec, exec, s[6:7]
	v_mad_i64_i32 v[32:33], s[6:7], v58, s10, 0
	v_mul_f32_e32 v34, 0x3e16c740, v46
	v_lshl_add_u64 v[32:33], s[70:71], 0, v[32:33]
	v_cvt_pk_bf16_f32 v34, v34, s0
	v_lshl_add_u64 v[32:33], v[128:129], 1, v[32:33]
	global_store_short v[32:33], v34, off
	s_and_saveexec_b64 s[6:7], s[54:55]
	s_cbranch_execz .LBB0_1419
	v_lshlrev_b32_e32 v32, 3, v177
	v_lshl_or_b32 v32, v59, 6, v32
	v_add_u32_e32 v32, 0x20000, v32
	ds_read_b64 v[32:33], v32
	v_and_b32_e32 v35, 64, v226
	v_xor_b32_e32 v34, 8, v226
	v_add_u32_e32 v35, 64, v35
	v_cmp_lt_i32_e32 vcc, v34, v35
	s_nop 1
	v_cndmask_b32_e32 v34, v226, v34, vcc
	v_lshlrev_b32_e32 v34, 2, v34
	ds_bpermute_b32 v35, v34, v47
	v_mov_b32_e32 v34, v47
	s_waitcnt lgkmcnt(0)
	v_cndmask_b32_e64 v36, v35, -v35, s[36:37]
	s_waitcnt lgkmcnt(0)
	v_mov_b32_e32 v35, v33
	v_mov_b32_e32 v33, v36
	v_pk_mul_f32 v[32:33], v[34:35], v[32:33]
	s_nop 0
	v_add_f32_e32 v47, v32, v33

.LBB0_1425:
	v_add_u32_e32 v98, 32, v148
	v_and_b32_e32 v96, 63, v98
	v_bfe_u32 v97, v98, 6, 4
	v_cndmask_b32_e64 v103, v97, v96, s[38:39]
	s_and_saveexec_b64 s[6:7], s[54:55]
	s_cbranch_execz .LBB0_1427
	v_lshlrev_b32_e32 v96, 3, v177
	v_lshl_or_b32 v96, v103, 6, v96
	v_add_u32_e32 v96, 0x20000, v96
	ds_read_b64 v[96:97], v96
	v_and_b32_e32 v100, 64, v226
	v_xor_b32_e32 v99, 8, v226
	v_add_u32_e32 v100, 64, v100
	v_cmp_lt_i32_e32 vcc, v99, v100
	v_mov_b32_e32 v100, v80
	s_waitcnt lgkmcnt(0)
	v_mov_b32_e32 v101, v97
	v_cndmask_b32_e32 v99, v226, v99, vcc
	v_lshlrev_b32_e32 v99, 2, v99
	ds_bpermute_b32 v99, v99, v80
	s_waitcnt lgkmcnt(0)
	v_cndmask_b32_e64 v80, v99, -v99, s[36:37]
	v_mov_b32_e32 v97, v80
	v_pk_mul_f32 v[96:97], v[100:101], v[96:97]
	s_nop 0
	v_add_f32_e32 v80, v96, v97
.LBB0_1427:
	s_or_b64 exec, exec, s[6:7]
	v_mov_b32_e32 v145, v129
	v_lshl_add_u64 v[96:97], v[144:145], 1, s[70:71]
	v_mul_f32_e32 v80, 0x3e16c740, v80
	v_cvt_pk_bf16_f32 v80, v80, s0
	v_mad_i64_i32 v[100:101], s[6:7], v98, s10, v[96:97]
	global_store_short v[100:101], v80, off
	v_add_u32_e32 v80, 33, v148
	v_and_b32_e32 v99, 63, v80
	v_bfe_u32 v100, v80, 6, 4
	v_cndmask_b32_e64 v117, v100, v99, s[38:39]
	s_and_saveexec_b64 s[6:7], s[54:55]
	s_cbranch_execz .LBB0_1429
	v_lshlrev_b32_e32 v99, 3, v177
	v_lshl_or_b32 v99, v117, 6, v99
	v_add_u32_e32 v99, 0x20000, v99
	ds_read_b64 v[100:101], v99
	v_and_b32_e32 v102, 64, v226
	v_xor_b32_e32 v99, 8, v226
	v_add_u32_e32 v102, 64, v102
	v_cmp_lt_i32_e32 vcc, v99, v102
	v_mov_b32_e32 v104, v81
	s_waitcnt lgkmcnt(0)
	v_mov_b32_e32 v105, v101
	v_cndmask_b32_e32 v99, v226, v99, vcc
	v_lshlrev_b32_e32 v99, 2, v99
	ds_bpermute_b32 v99, v99, v81
	s_waitcnt lgkmcnt(0)
	v_cndmask_b32_e64 v81, v99, -v99, s[36:37]
	v_mov_b32_e32 v101, v81
	v_pk_mul_f32 v[100:101], v[104:105], v[100:101]
	s_nop 0
	v_add_f32_e32 v81, v100, v101
.LBB0_1429:
	s_or_b64 exec, exec, s[6:7]
	v_mul_f32_e32 v81, 0x3e16c740, v81
	v_cvt_pk_bf16_f32 v81, v81, s0
	v_mad_i64_i32 v[100:101], s[6:7], v80, s10, v[96:97]
	v_add_u32_e32 v99, 34, v148
	global_store_short v[100:101], v81, off
	v_and_b32_e32 v81, 63, v99
	v_bfe_u32 v100, v99, 6, 4
	v_cndmask_b32_e64 v116, v100, v81, s[38:39]
	s_and_saveexec_b64 s[6:7], s[54:55]
	s_cbranch_execz .LBB0_1431
	v_lshlrev_b32_e32 v81, 3, v177
	v_lshl_or_b32 v81, v116, 6, v81
	v_add_u32_e32 v81, 0x20000, v81
	ds_read_b64 v[100:101], v81
	v_and_b32_e32 v102, 64, v226
	v_xor_b32_e32 v81, 8, v226
	v_add_u32_e32 v102, 64, v102
	v_cmp_lt_i32_e32 vcc, v81, v102
	v_mov_b32_e32 v104, v82
	s_waitcnt lgkmcnt(0)
	v_mov_b32_e32 v105, v101
	v_cndmask_b32_e32 v81, v226, v81, vcc
	v_lshlrev_b32_e32 v81, 2, v81
	ds_bpermute_b32 v81, v81, v82
	s_waitcnt lgkmcnt(0)
	v_cndmask_b32_e64 v81, v81, -v81, s[36:37]
	v_mov_b32_e32 v101, v81
	v_pk_mul_f32 v[100:101], v[104:105], v[100:101]
	s_nop 0
	v_add_f32_e32 v82, v100, v101
.LBB0_1431:
	s_or_b64 exec, exec, s[6:7]
	v_mul_f32_e32 v81, 0x3e16c740, v82
	v_cvt_pk_bf16_f32 v81, v81, s0
	v_mad_i64_i32 v[100:101], s[6:7], v99, s10, v[96:97]
	global_store_short v[100:101], v81, off
	v_add_u32_e32 v81, 35, v148
	v_and_b32_e32 v82, 63, v81
	v_bfe_u32 v100, v81, 6, 4
	v_cndmask_b32_e64 v115, v100, v82, s[38:39]
	s_and_saveexec_b64 s[6:7], s[54:55]
	s_cbranch_execz .LBB0_1433
	v_lshlrev_b32_e32 v82, 3, v177
	v_lshl_or_b32 v82, v115, 6, v82
	v_add_u32_e32 v82, 0x20000, v82
	ds_read_b64 v[100:101], v82
	v_and_b32_e32 v102, 64, v226
	v_xor_b32_e32 v82, 8, v226
	v_add_u32_e32 v102, 64, v102
	v_cmp_lt_i32_e32 vcc, v82, v102
	s_nop 1
	v_cndmask_b32_e32 v82, v226, v82, vcc
	v_lshlrev_b32_e32 v82, 2, v82
	ds_bpermute_b32 v102, v82, v83
	v_mov_b32_e32 v82, v83
	s_waitcnt lgkmcnt(0)
	v_cndmask_b32_e64 v102, v102, -v102, s[36:37]
	s_waitcnt lgkmcnt(0)
	v_mov_b32_e32 v83, v101
	v_mov_b32_e32 v101, v102
	v_pk_mul_f32 v[82:83], v[82:83], v[100:101]
	s_nop 0
	v_add_f32_e32 v83, v82, v83
.LBB0_1433:
	s_or_b64 exec, exec, s[6:7]
	v_mul_f32_e32 v82, 0x3e16c740, v83
	v_cvt_pk_bf16_f32 v100, v82, s0
	v_mad_i64_i32 v[82:83], s[6:7], v81, s10, v[96:97]
	global_store_short v[82:83], v100, off
	v_add_u32_e32 v100, 40, v148
	v_and_b32_e32 v82, 63, v100
	v_bfe_u32 v83, v100, 6, 4
	v_cndmask_b32_e64 v114, v83, v82, s[38:39]
	s_and_saveexec_b64 s[6:7], s[54:55]
	s_cbranch_execz .LBB0_1435
	v_lshlrev_b32_e32 v82, 3, v177
	v_lshl_or_b32 v82, v114, 6, v82
	v_add_u32_e32 v82, 0x20000, v82
	ds_read_b64 v[82:83], v82
	v_and_b32_e32 v102, 64, v226
	v_xor_b32_e32 v101, 8, v226
	v_add_u32_e32 v102, 64, v102
	v_cmp_lt_i32_e32 vcc, v101, v102
	v_mov_b32_e32 v104, v84
	s_waitcnt lgkmcnt(0)
	v_mov_b32_e32 v105, v83
	v_cndmask_b32_e32 v101, v226, v101, vcc
	v_lshlrev_b32_e32 v101, 2, v101
	ds_bpermute_b32 v101, v101, v84
	s_waitcnt lgkmcnt(0)
	v_cndmask_b32_e64 v84, v101, -v101, s[36:37]
	v_mov_b32_e32 v83, v84
	v_pk_mul_f32 v[82:83], v[104:105], v[82:83]
	s_nop 0
	v_add_f32_e32 v84, v82, v83
.LBB0_1435:
	s_or_b64 exec, exec, s[6:7]
	v_mul_f32_e32 v82, 0x3e16c740, v84
	v_cvt_pk_bf16_f32 v84, v82, s0
	v_mad_i64_i32 v[82:83], s[6:7], v100, s10, v[96:97]
	global_store_short v[82:83], v84, off
	v_add_u32_e32 v82, 41, v148
	v_and_b32_e32 v83, 63, v82
	v_bfe_u32 v84, v82, 6, 4
	v_cndmask_b32_e64 v113, v84, v83, s[38:39]
	s_and_saveexec_b64 s[6:7], s[54:55]
	s_cbranch_execz .LBB0_1437
	v_lshlrev_b32_e32 v83, 3, v177
	v_lshl_or_b32 v83, v113, 6, v83
	v_add_u32_e32 v83, 0x20000, v83
	ds_read_b64 v[104:105], v83
	v_and_b32_e32 v84, 64, v226
	v_xor_b32_e32 v83, 8, v226
	v_add_u32_e32 v84, 64, v84
	v_cmp_lt_i32_e32 vcc, v83, v84
	v_mov_b32_e32 v84, v85
	s_nop 0
	v_cndmask_b32_e32 v83, v226, v83, vcc
	v_lshlrev_b32_e32 v83, 2, v83
	ds_bpermute_b32 v83, v83, v85
	s_waitcnt lgkmcnt(0)
	v_cndmask_b32_e64 v83, v83, -v83, s[36:37]
	s_waitcnt lgkmcnt(0)
	v_mov_b32_e32 v85, v105
	v_mov_b32_e32 v105, v83
	v_pk_mul_f32 v[84:85], v[84:85], v[104:105]
	s_nop 0
	v_add_f32_e32 v85, v84, v85
.LBB0_1437:
	s_or_b64 exec, exec, s[6:7]
	v_mul_f32_e32 v83, 0x3e16c740, v85
	v_cvt_pk_bf16_f32 v83, v83, s0
	v_mad_i64_i32 v[84:85], s[6:7], v82, s10, v[96:97]
	v_add_u32_e32 v101, 42, v148
	global_store_short v[84:85], v83, off
	v_and_b32_e32 v83, 63, v101
	v_bfe_u32 v84, v101, 6, 4
	v_cndmask_b32_e64 v111, v84, v83, s[38:39]
	s_and_saveexec_b64 s[6:7], s[54:55]
	s_cbranch_execz .LBB0_1439
	v_lshlrev_b32_e32 v83, 3, v177
	v_lshl_or_b32 v83, v111, 6, v83
	v_add_u32_e32 v83, 0x20000, v83
	ds_read_b64 v[84:85], v83
	v_and_b32_e32 v102, 64, v226
	v_xor_b32_e32 v83, 8, v226
	v_add_u32_e32 v102, 64, v102
	v_cmp_lt_i32_e32 vcc, v83, v102
	v_mov_b32_e32 v104, v86
	s_waitcnt lgkmcnt(0)
	v_mov_b32_e32 v105, v85
	v_cndmask_b32_e32 v83, v226, v83, vcc
	v_lshlrev_b32_e32 v83, 2, v83
	ds_bpermute_b32 v83, v83, v86
	s_waitcnt lgkmcnt(0)
	v_cndmask_b32_e64 v83, v83, -v83, s[36:37]
	v_mov_b32_e32 v85, v83
	v_pk_mul_f32 v[84:85], v[104:105], v[84:85]
	s_nop 0
	v_add_f32_e32 v86, v84, v85
.LBB0_1439:
	s_or_b64 exec, exec, s[6:7]
	v_mul_f32_e32 v83, 0x3e16c740, v86
	v_cvt_pk_bf16_f32 v83, v83, s0
	v_mad_i64_i32 v[84:85], s[6:7], v101, s10, v[96:97]
	global_store_short v[84:85], v83, off
	v_add_u32_e32 v83, 43, v148
	v_and_b32_e32 v84, 63, v83
	v_bfe_u32 v85, v83, 6, 4
	v_cndmask_b32_e64 v110, v85, v84, s[38:39]
	s_and_saveexec_b64 s[6:7], s[54:55]
	s_cbranch_execz .LBB0_1441
	v_lshlrev_b32_e32 v84, 3, v177
	v_lshl_or_b32 v84, v110, 6, v84
	v_add_u32_e32 v84, 0x20000, v84
	ds_read_b64 v[84:85], v84
	v_and_b32_e32 v102, 64, v226
	v_xor_b32_e32 v86, 8, v226
	v_add_u32_e32 v102, 64, v102
	v_cmp_lt_i32_e32 vcc, v86, v102
	s_nop 1
	v_cndmask_b32_e32 v86, v226, v86, vcc
	v_lshlrev_b32_e32 v86, 2, v86
	ds_bpermute_b32 v102, v86, v87
	v_mov_b32_e32 v86, v87
	s_waitcnt lgkmcnt(0)
	v_cndmask_b32_e64 v102, v102, -v102, s[36:37]
	s_waitcnt lgkmcnt(0)
	v_mov_b32_e32 v87, v85
	v_mov_b32_e32 v85, v102
	v_pk_mul_f32 v[84:85], v[86:87], v[84:85]
	s_nop 0
	v_add_f32_e32 v87, v84, v85
.LBB0_1441:
	s_or_b64 exec, exec, s[6:7]
	v_mul_f32_e32 v84, 0x3e16c740, v87
	v_cvt_pk_bf16_f32 v86, v84, s0
	v_mad_i64_i32 v[84:85], s[6:7], v83, s10, v[96:97]
	v_add_u32_e32 v102, 48, v148
	global_store_short v[84:85], v86, off
	v_and_b32_e32 v84, 63, v102
	v_bfe_u32 v85, v102, 6, 4
	v_cndmask_b32_e64 v109, v85, v84, s[38:39]
	s_and_saveexec_b64 s[6:7], s[54:55]
	s_cbranch_execz .LBB0_1443
	v_lshlrev_b32_e32 v84, 3, v177
	v_lshl_or_b32 v84, v109, 6, v84
	v_add_u32_e32 v84, 0x20000, v84
	ds_read_b64 v[84:85], v84
	v_and_b32_e32 v87, 64, v226
	v_xor_b32_e32 v86, 8, v226
	v_add_u32_e32 v87, 64, v87
	v_cmp_lt_i32_e32 vcc, v86, v87
	s_nop 1
	v_cndmask_b32_e32 v86, v226, v86, vcc
	v_lshlrev_b32_e32 v86, 2, v86
	ds_bpermute_b32 v87, v86, v88
	v_mov_b32_e32 v86, v88
	s_waitcnt lgkmcnt(0)
	v_cndmask_b32_e64 v88, v87, -v87, s[36:37]
	s_waitcnt lgkmcnt(0)
	v_mov_b32_e32 v87, v85
	v_mov_b32_e32 v85, v88
	v_pk_mul_f32 v[84:85], v[86:87], v[84:85]
	s_nop 0
	v_add_f32_e32 v88, v84, v85
.LBB0_1443:
	s_or_b64 exec, exec, s[6:7]
	v_mul_f32_e32 v84, 0x3e16c740, v88
	v_cvt_pk_bf16_f32 v86, v84, s0
	v_mad_i64_i32 v[84:85], s[6:7], v102, s10, v[96:97]
	global_store_short v[84:85], v86, off
	v_add_u32_e32 v84, 49, v148
	v_and_b32_e32 v85, 63, v84
	v_bfe_u32 v86, v84, 6, 4
	v_cndmask_b32_e64 v108, v86, v85, s[38:39]
	s_and_saveexec_b64 s[6:7], s[54:55]
	s_cbranch_execz .LBB0_1445
	v_lshlrev_b32_e32 v85, 3, v177
	v_lshl_or_b32 v85, v108, 6, v85
	v_add_u32_e32 v85, 0x20000, v85
	ds_read_b64 v[86:87], v85
	v_and_b32_e32 v88, 64, v226
	v_xor_b32_e32 v85, 8, v226
	v_add_u32_e32 v88, 64, v88
	v_cmp_lt_i32_e32 vcc, v85, v88
	v_mov_b32_e32 v88, v89
	s_nop 0
	v_cndmask_b32_e32 v85, v226, v85, vcc
	v_lshlrev_b32_e32 v85, 2, v85
	ds_bpermute_b32 v85, v85, v89
	s_waitcnt lgkmcnt(0)
	v_cndmask_b32_e64 v85, v85, -v85, s[36:37]
	s_waitcnt lgkmcnt(0)
	v_mov_b32_e32 v89, v87
	v_mov_b32_e32 v87, v85
	v_pk_mul_f32 v[86:87], v[88:89], v[86:87]
	s_nop 0
	v_add_f32_e32 v89, v86, v87
.LBB0_1445:
	s_or_b64 exec, exec, s[6:7]
	v_mul_f32_e32 v85, 0x3e16c740, v89
	v_cvt_pk_bf16_f32 v85, v85, s0
	v_mad_i64_i32 v[86:87], s[6:7], v84, s10, v[96:97]
	v_add_u32_e32 v88, 50, v148
	global_store_short v[86:87], v85, off
	v_and_b32_e32 v85, 63, v88
	v_bfe_u32 v86, v88, 6, 4
	v_cndmask_b32_e64 v107, v86, v85, s[38:39]
	s_and_saveexec_b64 s[6:7], s[54:55]
	s_cbranch_execz .LBB0_1447
	v_lshlrev_b32_e32 v85, 3, v177
	v_lshl_or_b32 v85, v107, 6, v85
	v_add_u32_e32 v85, 0x20000, v85
	ds_read_b64 v[86:87], v85
	v_and_b32_e32 v89, 64, v226
	v_xor_b32_e32 v85, 8, v226
	v_add_u32_e32 v89, 64, v89
	v_cmp_lt_i32_e32 vcc, v85, v89
	v_mov_b32_e32 v104, v90
	s_waitcnt lgkmcnt(0)
	v_mov_b32_e32 v105, v87
	v_cndmask_b32_e32 v85, v226, v85, vcc
	v_lshlrev_b32_e32 v85, 2, v85
	ds_bpermute_b32 v85, v85, v90
	s_waitcnt lgkmcnt(0)
	v_cndmask_b32_e64 v85, v85, -v85, s[36:37]
	v_mov_b32_e32 v87, v85
	v_pk_mul_f32 v[86:87], v[104:105], v[86:87]
	s_nop 0
	v_add_f32_e32 v90, v86, v87
.LBB0_1447:
	s_or_b64 exec, exec, s[6:7]
	v_mul_f32_e32 v85, 0x3e16c740, v90
	v_cvt_pk_bf16_f32 v85, v85, s0
	v_mad_i64_i32 v[86:87], s[6:7], v88, s10, v[96:97]
	global_store_short v[86:87], v85, off
	v_add_u32_e32 v85, 51, v148
	v_and_b32_e32 v86, 63, v85
	v_bfe_u32 v87, v85, 6, 4
	v_cndmask_b32_e64 v106, v87, v86, s[38:39]
	s_and_saveexec_b64 s[6:7], s[54:55]
	s_cbranch_execz .LBB0_1449
	v_lshlrev_b32_e32 v86, 3, v177
	v_lshl_or_b32 v86, v106, 6, v86
	v_add_u32_e32 v86, 0x20000, v86
	ds_read_b64 v[86:87], v86
	v_and_b32_e32 v90, 64, v226
	v_xor_b32_e32 v89, 8, v226
	v_add_u32_e32 v90, 64, v90
	v_cmp_lt_i32_e32 vcc, v89, v90
	v_mov_b32_e32 v90, v91
	s_nop 0
	v_cndmask_b32_e32 v89, v226, v89, vcc
	v_lshlrev_b32_e32 v89, 2, v89
	ds_bpermute_b32 v89, v89, v91
	s_waitcnt lgkmcnt(0)
	v_cndmask_b32_e64 v89, v89, -v89, s[36:37]
	s_waitcnt lgkmcnt(0)
	v_mov_b32_e32 v91, v87
	v_mov_b32_e32 v87, v89
	v_pk_mul_f32 v[86:87], v[90:91], v[86:87]
	s_nop 0
	v_add_f32_e32 v91, v86, v87
.LBB0_1449:
	s_or_b64 exec, exec, s[6:7]
	v_mul_f32_e32 v86, 0x3e16c740, v91
	v_cvt_pk_bf16_f32 v89, v86, s0
	v_mad_i64_i32 v[86:87], s[6:7], v85, s10, v[96:97]
	global_store_short v[86:87], v89, off
	v_add_u32_e32 v89, 56, v148
	v_and_b32_e32 v86, 63, v89
	v_bfe_u32 v87, v89, 6, 4
	v_cndmask_b32_e64 v105, v87, v86, s[38:39]
	s_and_saveexec_b64 s[6:7], s[54:55]
	s_cbranch_execz .LBB0_1451
	v_lshlrev_b32_e32 v86, 3, v177
	v_lshl_or_b32 v86, v105, 6, v86
	v_add_u32_e32 v86, 0x20000, v86
	ds_read_b64 v[86:87], v86
	v_and_b32_e32 v91, 64, v226
	v_xor_b32_e32 v90, 8, v226
	v_add_u32_e32 v91, 64, v91
	v_cmp_lt_i32_e32 vcc, v90, v91
	s_nop 1
	v_cndmask_b32_e32 v90, v226, v90, vcc
	v_lshlrev_b32_e32 v90, 2, v90
	ds_bpermute_b32 v91, v90, v92
	v_mov_b32_e32 v90, v92
	s_waitcnt lgkmcnt(0)
	v_cndmask_b32_e64 v92, v91, -v91, s[36:37]
	s_waitcnt lgkmcnt(0)
	v_mov_b32_e32 v91, v87
	v_mov_b32_e32 v87, v92
	v_pk_mul_f32 v[86:87], v[90:91], v[86:87]
	s_nop 0
	v_add_f32_e32 v92, v86, v87
.LBB0_1451:
	s_or_b64 exec, exec, s[6:7]
	v_mul_f32_e32 v86, 0x3e16c740, v92
	v_cvt_pk_bf16_f32 v90, v86, s0
	v_mad_i64_i32 v[86:87], s[6:7], v89, s10, v[96:97]
	global_store_short v[86:87], v90, off
	v_add_u32_e32 v86, 57, v148
	v_and_b32_e32 v87, 63, v86
	v_bfe_u32 v90, v86, 6, 4
	v_cndmask_b32_e64 v104, v90, v87, s[38:39]
	s_and_saveexec_b64 s[6:7], s[54:55]
	s_cbranch_execz .LBB0_1453
	v_lshlrev_b32_e32 v87, 3, v177
	v_lshl_or_b32 v87, v104, 6, v87
	v_add_u32_e32 v87, 0x20000, v87
	ds_read_b64 v[90:91], v87
	v_and_b32_e32 v92, 64, v226
	v_xor_b32_e32 v87, 8, v226
	v_add_u32_e32 v92, 64, v92
	v_cmp_lt_i32_e32 vcc, v87, v92
	v_mov_b32_e32 v92, v93
	s_nop 0
	v_cndmask_b32_e32 v87, v226, v87, vcc
	v_lshlrev_b32_e32 v87, 2, v87
	ds_bpermute_b32 v87, v87, v93
	s_waitcnt lgkmcnt(0)
	v_cndmask_b32_e64 v87, v87, -v87, s[36:37]
	s_waitcnt lgkmcnt(0)
	v_mov_b32_e32 v93, v91
	v_mov_b32_e32 v91, v87
	v_pk_mul_f32 v[90:91], v[92:93], v[90:91]
	s_nop 0
	v_add_f32_e32 v93, v90, v91
.LBB0_1453:
	s_or_b64 exec, exec, s[6:7]
	v_mul_f32_e32 v87, 0x3e16c740, v93
	v_cvt_pk_bf16_f32 v87, v87, s0
	v_mad_i64_i32 v[90:91], s[6:7], v86, s10, v[96:97]
	global_store_short v[90:91], v87, off
	v_add_u32_e32 v90, 58, v148
	v_and_b32_e32 v87, 63, v90
	v_bfe_u32 v91, v90, 6, 4
	v_cndmask_b32_e64 v92, v91, v87, s[38:39]
	s_and_saveexec_b64 s[6:7], s[54:55]
	s_cbranch_execz .LBB0_1455
	v_lshlrev_b32_e32 v87, 3, v177
	v_lshl_or_b32 v87, v92, 6, v87
	v_add_u32_e32 v87, 0x20000, v87
	ds_read_b64 v[118:119], v87
	v_and_b32_e32 v91, 64, v226
	v_xor_b32_e32 v87, 8, v226
	v_add_u32_e32 v91, 64, v91
	v_cmp_lt_i32_e32 vcc, v87, v91
	v_mov_b32_e32 v120, v94
	s_waitcnt lgkmcnt(0)
	v_mov_b32_e32 v121, v119
	v_cndmask_b32_e32 v87, v226, v87, vcc
	v_lshlrev_b32_e32 v87, 2, v87
	ds_bpermute_b32 v87, v87, v94
	s_waitcnt lgkmcnt(0)
	v_cndmask_b32_e64 v87, v87, -v87, s[36:37]
	v_mov_b32_e32 v119, v87
	v_pk_mul_f32 v[118:119], v[120:121], v[118:119]
	s_nop 0
	v_add_f32_e32 v94, v118, v119
.LBB0_1455:
	s_or_b64 exec, exec, s[6:7]
	v_mul_f32_e32 v87, 0x3e16c740, v94
	v_cvt_pk_bf16_f32 v87, v87, s0
	v_mad_i64_i32 v[118:119], s[6:7], v90, s10, v[96:97]
	global_store_short v[118:119], v87, off
	v_add_u32_e32 v87, 59, v148
	v_and_b32_e32 v91, 63, v87
	v_bfe_u32 v93, v87, 6, 4
	v_cndmask_b32_e64 v91, v93, v91, s[38:39]
	s_and_saveexec_b64 s[6:7], s[54:55]
	s_cbranch_execz .LBB0_1457
	v_lshlrev_b32_e32 v93, 3, v177
	v_lshl_or_b32 v93, v91, 6, v93
	v_add_u32_e32 v93, 0x20000, v93
	ds_read_b64 v[118:119], v93
	v_and_b32_e32 v94, 64, v226
	v_xor_b32_e32 v93, 8, v226
	v_add_u32_e32 v94, 64, v94
	v_cmp_lt_i32_e32 vcc, v93, v94
	v_mov_b32_e32 v94, v95
	s_nop 0
	v_cndmask_b32_e32 v93, v226, v93, vcc
	v_lshlrev_b32_e32 v93, 2, v93
	ds_bpermute_b32 v93, v93, v95
	s_waitcnt lgkmcnt(0)
	v_cndmask_b32_e64 v93, v93, -v93, s[36:37]
	s_waitcnt lgkmcnt(0)
	v_mov_b32_e32 v95, v119
	v_mov_b32_e32 v119, v93
	v_pk_mul_f32 v[94:95], v[94:95], v[118:119]
	s_nop 0
	v_add_f32_e32 v95, v94, v95

.LBB0_1459:
	s_and_saveexec_b64 s[6:7], s[54:55]
	s_cbranch_execz .LBB0_1461
	v_lshlrev_b32_e32 v93, 3, v177
	v_lshl_or_b32 v93, v103, 6, v93
	v_add_u32_e32 v93, 0x20000, v93
	ds_read_b64 v[94:95], v93
	v_and_b32_e32 v96, 64, v226
	v_xor_b32_e32 v93, 8, v226
	v_add_u32_e32 v96, 64, v96
	v_cmp_lt_i32_e32 vcc, v93, v96
	v_mov_b32_e32 v96, v64
	s_waitcnt lgkmcnt(0)
	v_mov_b32_e32 v97, v95
	v_cndmask_b32_e32 v93, v226, v93, vcc
	v_lshlrev_b32_e32 v93, 2, v93
	ds_bpermute_b32 v93, v93, v64
	s_waitcnt lgkmcnt(0)
	v_cndmask_b32_e64 v64, v93, -v93, s[36:37]
	v_mov_b32_e32 v95, v64
	v_pk_mul_f32 v[94:95], v[96:97], v[94:95]
	s_nop 0
	v_add_f32_e32 v64, v94, v95
.LBB0_1461:
	s_or_b64 exec, exec, s[6:7]
	v_mad_i64_i32 v[94:95], s[6:7], v98, s10, 0
	v_mul_f32_e32 v64, 0x3e16c740, v64
	v_lshl_add_u64 v[94:95], s[70:71], 0, v[94:95]
	v_cvt_pk_bf16_f32 v64, v64, s0
	v_lshl_add_u64 v[94:95], v[128:129], 1, v[94:95]
	global_store_short v[94:95], v64, off
	s_and_saveexec_b64 s[6:7], s[54:55]
	s_cbranch_execz .LBB0_1463
	v_lshlrev_b32_e32 v64, 3, v177
	v_lshl_or_b32 v64, v117, 6, v64
	v_add_u32_e32 v64, 0x20000, v64
	ds_read_b64 v[94:95], v64
	v_and_b32_e32 v93, 64, v226
	v_xor_b32_e32 v64, 8, v226
	v_add_u32_e32 v93, 64, v93
	v_cmp_lt_i32_e32 vcc, v64, v93
	s_nop 1
	v_cndmask_b32_e32 v64, v226, v64, vcc
	v_lshlrev_b32_e32 v64, 2, v64
	ds_bpermute_b32 v93, v64, v65
	v_mov_b32_e32 v64, v65
	s_waitcnt lgkmcnt(0)
	v_cndmask_b32_e64 v93, v93, -v93, s[36:37]
	s_waitcnt lgkmcnt(0)
	v_mov_b32_e32 v65, v95
	v_mov_b32_e32 v95, v93
	v_pk_mul_f32 v[64:65], v[64:65], v[94:95]
	s_nop 0
	v_add_f32_e32 v65, v64, v65
.LBB0_1463:
	s_or_b64 exec, exec, s[6:7]
	v_mad_i64_i32 v[94:95], s[6:7], v80, s10, 0
	v_mul_f32_e32 v64, 0x3e16c740, v65
	v_cvt_pk_bf16_f32 v80, v64, s0
	v_lshl_add_u64 v[64:65], s[70:71], 0, v[94:95]
	v_lshl_add_u64 v[64:65], v[128:129], 1, v[64:65]
	global_store_short v[64:65], v80, off
	s_and_saveexec_b64 s[6:7], s[54:55]
	s_cbranch_execz .LBB0_1465
	v_lshlrev_b32_e32 v64, 3, v177
	v_lshl_or_b32 v64, v116, 6, v64
	v_add_u32_e32 v64, 0x20000, v64
	ds_read_b64 v[64:65], v64
	v_and_b32_e32 v93, 64, v226
	v_xor_b32_e32 v80, 8, v226
	v_add_u32_e32 v93, 64, v93
	v_cmp_lt_i32_e32 vcc, v80, v93
	v_mov_b32_e32 v94, v66
	s_waitcnt lgkmcnt(0)
	v_mov_b32_e32 v95, v65
	v_cndmask_b32_e32 v80, v226, v80, vcc
	v_lshlrev_b32_e32 v80, 2, v80
	ds_bpermute_b32 v80, v80, v66
	s_waitcnt lgkmcnt(0)
	v_cndmask_b32_e64 v66, v80, -v80, s[36:37]
	v_mov_b32_e32 v65, v66
	v_pk_mul_f32 v[64:65], v[94:95], v[64:65]
	s_nop 0
	v_add_f32_e32 v66, v64, v65
.LBB0_1465:
	s_or_b64 exec, exec, s[6:7]
	v_mad_i64_i32 v[64:65], s[6:7], v99, s10, 0
	v_mul_f32_e32 v66, 0x3e16c740, v66
	v_lshl_add_u64 v[64:65], s[70:71], 0, v[64:65]
	v_cvt_pk_bf16_f32 v66, v66, s0
	v_lshl_add_u64 v[64:65], v[128:129], 1, v[64:65]
	global_store_short v[64:65], v66, off
	s_and_saveexec_b64 s[6:7], s[54:55]
	s_cbranch_execz .LBB0_1467
	v_lshlrev_b32_e32 v64, 3, v177
	v_lshl_or_b32 v64, v115, 6, v64
	v_add_u32_e32 v64, 0x20000, v64
	ds_read_b64 v[64:65], v64
	v_and_b32_e32 v80, 64, v226
	v_xor_b32_e32 v66, 8, v226
	v_add_u32_e32 v80, 64, v80
	v_cmp_lt_i32_e32 vcc, v66, v80
	s_nop 1
	v_cndmask_b32_e32 v66, v226, v66, vcc
	v_lshlrev_b32_e32 v66, 2, v66
	ds_bpermute_b32 v80, v66, v67
	v_mov_b32_e32 v66, v67
	s_waitcnt lgkmcnt(0)
	v_cndmask_b32_e64 v80, v80, -v80, s[36:37]
	s_waitcnt lgkmcnt(0)
	v_mov_b32_e32 v67, v65
	v_mov_b32_e32 v65, v80
	v_pk_mul_f32 v[64:65], v[66:67], v[64:65]
	s_nop 0
	v_add_f32_e32 v67, v64, v65
.LBB0_1467:
	s_or_b64 exec, exec, s[6:7]
	v_mad_i64_i32 v[64:65], s[6:7], v81, s10, 0
	v_mul_f32_e32 v66, 0x3e16c740, v67
	v_lshl_add_u64 v[64:65], s[70:71], 0, v[64:65]
	v_cvt_pk_bf16_f32 v66, v66, s0
	v_lshl_add_u64 v[64:65], v[128:129], 1, v[64:65]
	global_store_short v[64:65], v66, off
	s_and_saveexec_b64 s[6:7], s[54:55]
	s_cbranch_execz .LBB0_1469
	v_lshlrev_b32_e32 v64, 3, v177
	v_lshl_or_b32 v64, v114, 6, v64
	v_add_u32_e32 v64, 0x20000, v64
	ds_read_b64 v[64:65], v64
	v_and_b32_e32 v67, 64, v226
	v_xor_b32_e32 v66, 8, v226
	v_add_u32_e32 v67, 64, v67
	v_cmp_lt_i32_e32 vcc, v66, v67
	s_nop 1
	v_cndmask_b32_e32 v66, v226, v66, vcc
	v_lshlrev_b32_e32 v66, 2, v66
	ds_bpermute_b32 v67, v66, v68
	v_mov_b32_e32 v66, v68
	s_waitcnt lgkmcnt(0)
	v_cndmask_b32_e64 v68, v67, -v67, s[36:37]
	s_waitcnt lgkmcnt(0)
	v_mov_b32_e32 v67, v65
	v_mov_b32_e32 v65, v68
	v_pk_mul_f32 v[64:65], v[66:67], v[64:65]
	s_nop 0
	v_add_f32_e32 v68, v64, v65
.LBB0_1469:
	s_or_b64 exec, exec, s[6:7]
	v_mad_i64_i32 v[64:65], s[6:7], v100, s10, 0
	v_mul_f32_e32 v66, 0x3e16c740, v68
	v_lshl_add_u64 v[64:65], s[70:71], 0, v[64:65]
	v_cvt_pk_bf16_f32 v66, v66, s0
	v_lshl_add_u64 v[64:65], v[128:129], 1, v[64:65]
	global_store_short v[64:65], v66, off
	s_and_saveexec_b64 s[6:7], s[54:55]
	s_cbranch_execz .LBB0_1471
	v_lshlrev_b32_e32 v64, 3, v177
	v_lshl_or_b32 v64, v113, 6, v64
	v_add_u32_e32 v64, 0x20000, v64
	ds_read_b64 v[64:65], v64
	v_and_b32_e32 v67, 64, v226
	v_xor_b32_e32 v66, 8, v226
	v_add_u32_e32 v67, 64, v67
	v_cmp_lt_i32_e32 vcc, v66, v67
	s_nop 1
	v_cndmask_b32_e32 v66, v226, v66, vcc
	v_lshlrev_b32_e32 v66, 2, v66
	ds_bpermute_b32 v67, v66, v69
	v_mov_b32_e32 v66, v69
	s_waitcnt lgkmcnt(0)
	v_cndmask_b32_e64 v68, v67, -v67, s[36:37]
	s_waitcnt lgkmcnt(0)
	v_mov_b32_e32 v67, v65
	v_mov_b32_e32 v65, v68
	v_pk_mul_f32 v[64:65], v[66:67], v[64:65]
	s_nop 0
	v_add_f32_e32 v69, v64, v65
.LBB0_1471:
	s_or_b64 exec, exec, s[6:7]
	v_mad_i64_i32 v[64:65], s[6:7], v82, s10, 0
	v_mul_f32_e32 v66, 0x3e16c740, v69
	v_lshl_add_u64 v[64:65], s[70:71], 0, v[64:65]
	v_cvt_pk_bf16_f32 v66, v66, s0
	v_lshl_add_u64 v[64:65], v[128:129], 1, v[64:65]
	global_store_short v[64:65], v66, off
	s_and_saveexec_b64 s[6:7], s[54:55]
	s_cbranch_execz .LBB0_1473
	v_lshlrev_b32_e32 v64, 3, v177
	v_lshl_or_b32 v64, v111, 6, v64
	v_add_u32_e32 v64, 0x20000, v64
	ds_read_b64 v[64:65], v64
	v_and_b32_e32 v67, 64, v226
	v_xor_b32_e32 v66, 8, v226
	v_add_u32_e32 v67, 64, v67
	v_cmp_lt_i32_e32 vcc, v66, v67
	s_nop 1
	v_cndmask_b32_e32 v66, v226, v66, vcc
	v_lshlrev_b32_e32 v66, 2, v66
	ds_bpermute_b32 v67, v66, v70
	v_mov_b32_e32 v66, v70
	s_waitcnt lgkmcnt(0)
	v_cndmask_b32_e64 v68, v67, -v67, s[36:37]
	s_waitcnt lgkmcnt(0)
	v_mov_b32_e32 v67, v65
	v_mov_b32_e32 v65, v68
	v_pk_mul_f32 v[64:65], v[66:67], v[64:65]
	s_nop 0
	v_add_f32_e32 v70, v64, v65
.LBB0_1473:
	s_or_b64 exec, exec, s[6:7]
	v_mad_i64_i32 v[64:65], s[6:7], v101, s10, 0
	v_mul_f32_e32 v66, 0x3e16c740, v70
	v_lshl_add_u64 v[64:65], s[70:71], 0, v[64:65]
	v_cvt_pk_bf16_f32 v66, v66, s0
	v_lshl_add_u64 v[64:65], v[128:129], 1, v[64:65]
	global_store_short v[64:65], v66, off
	s_and_saveexec_b64 s[6:7], s[54:55]
	s_cbranch_execz .LBB0_1475
	v_lshlrev_b32_e32 v64, 3, v177
	v_lshl_or_b32 v64, v110, 6, v64
	v_add_u32_e32 v64, 0x20000, v64
	ds_read_b64 v[64:65], v64
	v_and_b32_e32 v67, 64, v226
	v_xor_b32_e32 v66, 8, v226
	v_add_u32_e32 v67, 64, v67
	v_cmp_lt_i32_e32 vcc, v66, v67
	s_nop 1
	v_cndmask_b32_e32 v66, v226, v66, vcc
	v_lshlrev_b32_e32 v66, 2, v66
	ds_bpermute_b32 v67, v66, v71
	v_mov_b32_e32 v66, v71
	s_waitcnt lgkmcnt(0)
	v_cndmask_b32_e64 v68, v67, -v67, s[36:37]
	s_waitcnt lgkmcnt(0)
	v_mov_b32_e32 v67, v65
	v_mov_b32_e32 v65, v68
	v_pk_mul_f32 v[64:65], v[66:67], v[64:65]
	s_nop 0
	v_add_f32_e32 v71, v64, v65
.LBB0_1475:
	s_or_b64 exec, exec, s[6:7]
	v_mad_i64_i32 v[64:65], s[6:7], v83, s10, 0
	v_mul_f32_e32 v66, 0x3e16c740, v71
	v_lshl_add_u64 v[64:65], s[70:71], 0, v[64:65]
	v_cvt_pk_bf16_f32 v66, v66, s0
	v_lshl_add_u64 v[64:65], v[128:129], 1, v[64:65]
	global_store_short v[64:65], v66, off
	s_and_saveexec_b64 s[6:7], s[54:55]
	s_cbranch_execz .LBB0_1477
	v_lshlrev_b32_e32 v64, 3, v177
	v_lshl_or_b32 v64, v109, 6, v64
	v_add_u32_e32 v64, 0x20000, v64
	ds_read_b64 v[64:65], v64
	v_and_b32_e32 v67, 64, v226
	v_xor_b32_e32 v66, 8, v226
	v_add_u32_e32 v67, 64, v67
	v_cmp_lt_i32_e32 vcc, v66, v67
	s_nop 1
	v_cndmask_b32_e32 v66, v226, v66, vcc
	v_lshlrev_b32_e32 v66, 2, v66
	ds_bpermute_b32 v67, v66, v72
	v_mov_b32_e32 v66, v72
	s_waitcnt lgkmcnt(0)
	v_cndmask_b32_e64 v68, v67, -v67, s[36:37]
	s_waitcnt lgkmcnt(0)
	v_mov_b32_e32 v67, v65
	v_mov_b32_e32 v65, v68
	v_pk_mul_f32 v[64:65], v[66:67], v[64:65]
	s_nop 0
	v_add_f32_e32 v72, v64, v65
.LBB0_1477:
	s_or_b64 exec, exec, s[6:7]
	v_mad_i64_i32 v[64:65], s[6:7], v102, s10, 0
	v_mul_f32_e32 v66, 0x3e16c740, v72
	v_lshl_add_u64 v[64:65], s[70:71], 0, v[64:65]
	v_cvt_pk_bf16_f32 v66, v66, s0
	v_lshl_add_u64 v[64:65], v[128:129], 1, v[64:65]
	global_store_short v[64:65], v66, off
	s_and_saveexec_b64 s[6:7], s[54:55]
	s_cbranch_execz .LBB0_1479
	v_lshlrev_b32_e32 v64, 3, v177
	v_lshl_or_b32 v64, v108, 6, v64
	v_add_u32_e32 v64, 0x20000, v64
	ds_read_b64 v[64:65], v64
	v_and_b32_e32 v67, 64, v226
	v_xor_b32_e32 v66, 8, v226
	v_add_u32_e32 v67, 64, v67
	v_cmp_lt_i32_e32 vcc, v66, v67
	s_nop 1
	v_cndmask_b32_e32 v66, v226, v66, vcc
	v_lshlrev_b32_e32 v66, 2, v66
	ds_bpermute_b32 v67, v66, v73
	v_mov_b32_e32 v66, v73
	s_waitcnt lgkmcnt(0)
	v_cndmask_b32_e64 v68, v67, -v67, s[36:37]
	s_waitcnt lgkmcnt(0)
	v_mov_b32_e32 v67, v65
	v_mov_b32_e32 v65, v68
	v_pk_mul_f32 v[64:65], v[66:67], v[64:65]
	s_nop 0
	v_add_f32_e32 v73, v64, v65
.LBB0_1479:
	s_or_b64 exec, exec, s[6:7]
	v_mad_i64_i32 v[64:65], s[6:7], v84, s10, 0
	v_mul_f32_e32 v66, 0x3e16c740, v73
	v_lshl_add_u64 v[64:65], s[70:71], 0, v[64:65]
	v_cvt_pk_bf16_f32 v66, v66, s0
	v_lshl_add_u64 v[64:65], v[128:129], 1, v[64:65]
	global_store_short v[64:65], v66, off
	s_and_saveexec_b64 s[6:7], s[54:55]
	s_cbranch_execz .LBB0_1481
	v_lshlrev_b32_e32 v64, 3, v177
	v_lshl_or_b32 v64, v107, 6, v64
	v_add_u32_e32 v64, 0x20000, v64
	ds_read_b64 v[64:65], v64
	v_and_b32_e32 v67, 64, v226
	v_xor_b32_e32 v66, 8, v226
	v_add_u32_e32 v67, 64, v67
	v_cmp_lt_i32_e32 vcc, v66, v67
	s_nop 1
	v_cndmask_b32_e32 v66, v226, v66, vcc
	v_lshlrev_b32_e32 v66, 2, v66
	ds_bpermute_b32 v67, v66, v74
	v_mov_b32_e32 v66, v74
	s_waitcnt lgkmcnt(0)
	v_cndmask_b32_e64 v68, v67, -v67, s[36:37]
	s_waitcnt lgkmcnt(0)
	v_mov_b32_e32 v67, v65
	v_mov_b32_e32 v65, v68
	v_pk_mul_f32 v[64:65], v[66:67], v[64:65]
	s_nop 0
	v_add_f32_e32 v74, v64, v65
.LBB0_1481:
	s_or_b64 exec, exec, s[6:7]
	v_mad_i64_i32 v[64:65], s[6:7], v88, s10, 0
	v_mul_f32_e32 v66, 0x3e16c740, v74
	v_lshl_add_u64 v[64:65], s[70:71], 0, v[64:65]
	v_cvt_pk_bf16_f32 v66, v66, s0
	v_lshl_add_u64 v[64:65], v[128:129], 1, v[64:65]
	global_store_short v[64:65], v66, off
	s_and_saveexec_b64 s[6:7], s[54:55]
	s_cbranch_execz .LBB0_1483
	v_lshlrev_b32_e32 v64, 3, v177
	v_lshl_or_b32 v64, v106, 6, v64
	v_add_u32_e32 v64, 0x20000, v64
	ds_read_b64 v[64:65], v64
	v_and_b32_e32 v67, 64, v226
	v_xor_b32_e32 v66, 8, v226
	v_add_u32_e32 v67, 64, v67
	v_cmp_lt_i32_e32 vcc, v66, v67
	s_nop 1
	v_cndmask_b32_e32 v66, v226, v66, vcc
	v_lshlrev_b32_e32 v66, 2, v66
	ds_bpermute_b32 v67, v66, v75
	v_mov_b32_e32 v66, v75
	s_waitcnt lgkmcnt(0)
	v_cndmask_b32_e64 v68, v67, -v67, s[36:37]
	s_waitcnt lgkmcnt(0)
	v_mov_b32_e32 v67, v65
	v_mov_b32_e32 v65, v68
	v_pk_mul_f32 v[64:65], v[66:67], v[64:65]
	s_nop 0
	v_add_f32_e32 v75, v64, v65
.LBB0_1483:
	s_or_b64 exec, exec, s[6:7]
	v_mad_i64_i32 v[64:65], s[6:7], v85, s10, 0
	v_mul_f32_e32 v66, 0x3e16c740, v75
	v_lshl_add_u64 v[64:65], s[70:71], 0, v[64:65]
	v_cvt_pk_bf16_f32 v66, v66, s0
	v_lshl_add_u64 v[64:65], v[128:129], 1, v[64:65]
	global_store_short v[64:65], v66, off
	s_and_saveexec_b64 s[6:7], s[54:55]
	s_cbranch_execz .LBB0_1485
	v_lshlrev_b32_e32 v64, 3, v177
	v_lshl_or_b32 v64, v105, 6, v64
	v_add_u32_e32 v64, 0x20000, v64
	ds_read_b64 v[64:65], v64
	v_and_b32_e32 v67, 64, v226
	v_xor_b32_e32 v66, 8, v226
	v_add_u32_e32 v67, 64, v67
	v_cmp_lt_i32_e32 vcc, v66, v67
	s_nop 1
	v_cndmask_b32_e32 v66, v226, v66, vcc
	v_lshlrev_b32_e32 v66, 2, v66
	ds_bpermute_b32 v67, v66, v76
	v_mov_b32_e32 v66, v76
	s_waitcnt lgkmcnt(0)
	v_cndmask_b32_e64 v68, v67, -v67, s[36:37]
	s_waitcnt lgkmcnt(0)
	v_mov_b32_e32 v67, v65
	v_mov_b32_e32 v65, v68
	v_pk_mul_f32 v[64:65], v[66:67], v[64:65]
	s_nop 0
	v_add_f32_e32 v76, v64, v65
.LBB0_1485:
	s_or_b64 exec, exec, s[6:7]
	v_mad_i64_i32 v[64:65], s[6:7], v89, s10, 0
	v_mul_f32_e32 v66, 0x3e16c740, v76
	v_lshl_add_u64 v[64:65], s[70:71], 0, v[64:65]
	v_cvt_pk_bf16_f32 v66, v66, s0
	v_lshl_add_u64 v[64:65], v[128:129], 1, v[64:65]
	global_store_short v[64:65], v66, off
	s_and_saveexec_b64 s[6:7], s[54:55]
	s_cbranch_execz .LBB0_1487
	v_lshlrev_b32_e32 v64, 3, v177
	v_lshl_or_b32 v64, v104, 6, v64
	v_add_u32_e32 v64, 0x20000, v64
	ds_read_b64 v[64:65], v64
	v_and_b32_e32 v67, 64, v226
	v_xor_b32_e32 v66, 8, v226
	v_add_u32_e32 v67, 64, v67
	v_cmp_lt_i32_e32 vcc, v66, v67
	s_nop 1
	v_cndmask_b32_e32 v66, v226, v66, vcc
	v_lshlrev_b32_e32 v66, 2, v66
	ds_bpermute_b32 v67, v66, v77
	v_mov_b32_e32 v66, v77
	s_waitcnt lgkmcnt(0)
	v_cndmask_b32_e64 v68, v67, -v67, s[36:37]
	s_waitcnt lgkmcnt(0)
	v_mov_b32_e32 v67, v65
	v_mov_b32_e32 v65, v68
	v_pk_mul_f32 v[64:65], v[66:67], v[64:65]
	s_nop 0
	v_add_f32_e32 v77, v64, v65
.LBB0_1487:
	s_or_b64 exec, exec, s[6:7]
	v_mad_i64_i32 v[64:65], s[6:7], v86, s10, 0
	v_mul_f32_e32 v66, 0x3e16c740, v77
	v_lshl_add_u64 v[64:65], s[70:71], 0, v[64:65]
	v_cvt_pk_bf16_f32 v66, v66, s0
	v_lshl_add_u64 v[64:65], v[128:129], 1, v[64:65]
	global_store_short v[64:65], v66, off
	s_and_saveexec_b64 s[6:7], s[54:55]
	s_cbranch_execz .LBB0_1489
	v_lshlrev_b32_e32 v64, 3, v177
	v_lshl_or_b32 v64, v92, 6, v64
	v_add_u32_e32 v64, 0x20000, v64
	ds_read_b64 v[64:65], v64
	v_and_b32_e32 v67, 64, v226
	v_xor_b32_e32 v66, 8, v226
	v_add_u32_e32 v67, 64, v67
	v_cmp_lt_i32_e32 vcc, v66, v67
	s_nop 1
	v_cndmask_b32_e32 v66, v226, v66, vcc
	v_lshlrev_b32_e32 v66, 2, v66
	ds_bpermute_b32 v67, v66, v78
	v_mov_b32_e32 v66, v78
	s_waitcnt lgkmcnt(0)
	v_cndmask_b32_e64 v68, v67, -v67, s[36:37]
	s_waitcnt lgkmcnt(0)
	v_mov_b32_e32 v67, v65
	v_mov_b32_e32 v65, v68
	v_pk_mul_f32 v[64:65], v[66:67], v[64:65]
	s_nop 0
	v_add_f32_e32 v78, v64, v65
.LBB0_1489:
	s_or_b64 exec, exec, s[6:7]
	v_mad_i64_i32 v[64:65], s[6:7], v90, s10, 0
	v_mul_f32_e32 v66, 0x3e16c740, v78
	v_lshl_add_u64 v[64:65], s[70:71], 0, v[64:65]
	v_cvt_pk_bf16_f32 v66, v66, s0
	v_lshl_add_u64 v[64:65], v[128:129], 1, v[64:65]
	global_store_short v[64:65], v66, off
	s_and_saveexec_b64 s[6:7], s[54:55]
	s_cbranch_execz .LBB0_1491
	v_lshlrev_b32_e32 v64, 3, v177
	v_lshl_or_b32 v64, v91, 6, v64
	v_add_u32_e32 v64, 0x20000, v64
	ds_read_b64 v[64:65], v64
	v_and_b32_e32 v67, 64, v226
	v_xor_b32_e32 v66, 8, v226
	v_add_u32_e32 v67, 64, v67
	v_cmp_lt_i32_e32 vcc, v66, v67
	s_nop 1
	v_cndmask_b32_e32 v66, v226, v66, vcc
	v_lshlrev_b32_e32 v66, 2, v66
	ds_bpermute_b32 v67, v66, v79
	v_mov_b32_e32 v66, v79
	s_waitcnt lgkmcnt(0)
	v_cndmask_b32_e64 v68, v67, -v67, s[36:37]
	s_waitcnt lgkmcnt(0)
	v_mov_b32_e32 v67, v65
	v_mov_b32_e32 v65, v68
	v_pk_mul_f32 v[64:65], v[66:67], v[64:65]
	s_nop 0
	v_add_f32_e32 v79, v64, v65

.LBB0_1495:
	v_add_u32_e32 v35, 0x60, v148
	v_and_b32_e32 v32, 63, v35
	v_bfe_u32 v33, v35, 6, 4
	v_lshlrev_b32_e32 v34, 3, v177
	v_cndmask_b32_e64 v40, v33, v32, s[38:39]
	s_and_saveexec_b64 s[6:7], s[44:45]
	s_cbranch_execz .LBB0_1497
	v_lshl_or_b32 v32, v40, 6, v34
	v_add_u32_e32 v32, 0x20000, v32
	ds_read_b64 v[32:33], v32
	v_and_b32_e32 v37, 64, v226
	v_xor_b32_e32 v36, 8, v226
	v_add_u32_e32 v37, 64, v37
	v_cmp_lt_i32_e32 vcc, v36, v37
	s_nop 1
	v_cndmask_b32_e32 v36, v226, v36, vcc
	v_lshlrev_b32_e32 v36, 2, v36
	ds_bpermute_b32 v37, v36, v16
	v_mov_b32_e32 v36, v16
	s_waitcnt lgkmcnt(0)
	v_cndmask_b32_e64 v16, v37, -v37, s[36:37]
	s_waitcnt lgkmcnt(0)
	v_mov_b32_e32 v37, v33
	v_mov_b32_e32 v33, v16
	v_pk_mul_f32 v[32:33], v[36:37], v[32:33]
	s_nop 0
	v_add_f32_e32 v16, v32, v33
.LBB0_1497:
	s_or_b64 exec, exec, s[6:7]
	v_mov_b32_e32 v145, v129
	v_lshl_add_u64 v[32:33], v[144:145], 1, s[70:71]
	v_mul_f32_e32 v16, 0x3e16c740, v16
	v_cvt_pk_bf16_f32 v16, v16, s0
	v_mad_i64_i32 v[36:37], s[6:7], v35, s10, v[32:33]
	global_store_short v[36:37], v16, off
	v_add_u32_e32 v16, 0x61, v148
	v_and_b32_e32 v36, 63, v16
	v_bfe_u32 v37, v16, 6, 4
	v_cndmask_b32_e64 v53, v37, v36, s[38:39]
	s_and_saveexec_b64 s[6:7], s[44:45]
	s_cbranch_execz .LBB0_1499
	v_lshl_or_b32 v36, v53, 6, v34
	v_add_u32_e32 v36, 0x20000, v36
	ds_read_b64 v[36:37], v36
	v_and_b32_e32 v39, 64, v226
	v_xor_b32_e32 v38, 8, v226
	v_add_u32_e32 v39, 64, v39
	v_cmp_lt_i32_e32 vcc, v38, v39
	s_nop 1
	v_cndmask_b32_e32 v38, v226, v38, vcc
	v_lshlrev_b32_e32 v38, 2, v38
	ds_bpermute_b32 v39, v38, v17
	v_mov_b32_e32 v38, v17
	s_waitcnt lgkmcnt(0)
	v_cndmask_b32_e64 v17, v39, -v39, s[36:37]
	s_waitcnt lgkmcnt(0)
	v_mov_b32_e32 v39, v37
	v_mov_b32_e32 v37, v17
	v_pk_mul_f32 v[36:37], v[38:39], v[36:37]
	s_nop 0
	v_add_f32_e32 v17, v36, v37
.LBB0_1499:
	s_or_b64 exec, exec, s[6:7]
	v_mul_f32_e32 v17, 0x3e16c740, v17
	v_cvt_pk_bf16_f32 v17, v17, s0
	v_mad_i64_i32 v[36:37], s[6:7], v16, s10, v[32:33]
	global_store_short v[36:37], v17, off
	v_add_u32_e32 v36, 0x62, v148
	v_and_b32_e32 v17, 63, v36
	v_bfe_u32 v37, v36, 6, 4
	v_cndmask_b32_e64 v52, v37, v17, s[38:39]
	s_and_saveexec_b64 s[6:7], s[44:45]
	s_cbranch_execz .LBB0_1501
	v_lshl_or_b32 v17, v52, 6, v34
	v_add_u32_e32 v17, 0x20000, v17
	ds_read_b64 v[38:39], v17
	v_and_b32_e32 v37, 64, v226
	v_xor_b32_e32 v17, 8, v226
	v_add_u32_e32 v37, 64, v37
	v_cmp_lt_i32_e32 vcc, v17, v37
	v_mov_b32_e32 v42, v18
	s_waitcnt lgkmcnt(0)
	v_mov_b32_e32 v43, v39
	v_cndmask_b32_e32 v17, v226, v17, vcc
	v_lshlrev_b32_e32 v17, 2, v17
	ds_bpermute_b32 v17, v17, v18
	s_waitcnt lgkmcnt(0)
	v_cndmask_b32_e64 v17, v17, -v17, s[36:37]
	v_mov_b32_e32 v39, v17
	v_pk_mul_f32 v[38:39], v[42:43], v[38:39]
	s_nop 0
	v_add_f32_e32 v18, v38, v39
.LBB0_1501:
	s_or_b64 exec, exec, s[6:7]
	v_mul_f32_e32 v17, 0x3e16c740, v18
	v_cvt_pk_bf16_f32 v17, v17, s0
	v_mad_i64_i32 v[38:39], s[6:7], v36, s10, v[32:33]
	global_store_short v[38:39], v17, off
	v_add_u32_e32 v17, 0x63, v148
	v_and_b32_e32 v18, 63, v17
	v_bfe_u32 v37, v17, 6, 4
	v_cndmask_b32_e64 v51, v37, v18, s[38:39]
	s_and_saveexec_b64 s[6:7], s[44:45]
	s_cbranch_execz .LBB0_1503
	v_lshl_or_b32 v18, v51, 6, v34
	v_add_u32_e32 v18, 0x20000, v18
	ds_read_b64 v[38:39], v18
	v_and_b32_e32 v37, 64, v226
	v_xor_b32_e32 v18, 8, v226
	v_add_u32_e32 v37, 64, v37
	v_cmp_lt_i32_e32 vcc, v18, v37
	s_nop 1
	v_cndmask_b32_e32 v18, v226, v18, vcc
	v_lshlrev_b32_e32 v18, 2, v18
	ds_bpermute_b32 v37, v18, v19
	v_mov_b32_e32 v18, v19
	s_waitcnt lgkmcnt(0)
	v_cndmask_b32_e64 v37, v37, -v37, s[36:37]
	s_waitcnt lgkmcnt(0)
	v_mov_b32_e32 v19, v39
	v_mov_b32_e32 v39, v37
	v_pk_mul_f32 v[18:19], v[18:19], v[38:39]
	s_nop 0
	v_add_f32_e32 v19, v18, v19
.LBB0_1503:
	s_or_b64 exec, exec, s[6:7]
	v_mul_f32_e32 v18, 0x3e16c740, v19
	v_cvt_pk_bf16_f32 v37, v18, s0
	v_mad_i64_i32 v[18:19], s[6:7], v17, s10, v[32:33]
	global_store_short v[18:19], v37, off
	v_add_u32_e32 v37, 0x68, v148
	v_and_b32_e32 v18, 63, v37
	v_bfe_u32 v19, v37, 6, 4
	v_cndmask_b32_e64 v50, v19, v18, s[38:39]
	s_and_saveexec_b64 s[6:7], s[44:45]
	s_cbranch_execz .LBB0_1505
	v_lshl_or_b32 v18, v50, 6, v34
	v_add_u32_e32 v18, 0x20000, v18
	ds_read_b64 v[18:19], v18
	v_and_b32_e32 v39, 64, v226
	v_xor_b32_e32 v38, 8, v226
	v_add_u32_e32 v39, 64, v39
	v_cmp_lt_i32_e32 vcc, v38, v39
	s_nop 1
	v_cndmask_b32_e32 v38, v226, v38, vcc
	v_lshlrev_b32_e32 v38, 2, v38
	ds_bpermute_b32 v39, v38, v20
	v_mov_b32_e32 v38, v20
	s_waitcnt lgkmcnt(0)
	v_cndmask_b32_e64 v20, v39, -v39, s[36:37]
	s_waitcnt lgkmcnt(0)
	v_mov_b32_e32 v39, v19
	v_mov_b32_e32 v19, v20
	v_pk_mul_f32 v[18:19], v[38:39], v[18:19]
	s_nop 0
	v_add_f32_e32 v20, v18, v19
.LBB0_1505:
	s_or_b64 exec, exec, s[6:7]
	v_mul_f32_e32 v18, 0x3e16c740, v20
	v_cvt_pk_bf16_f32 v20, v18, s0
	v_mad_i64_i32 v[18:19], s[6:7], v37, s10, v[32:33]
	global_store_short v[18:19], v20, off
	v_add_u32_e32 v18, 0x69, v148
	v_and_b32_e32 v19, 63, v18
	v_bfe_u32 v20, v18, 6, 4
	v_cndmask_b32_e64 v49, v20, v19, s[38:39]
	s_and_saveexec_b64 s[6:7], s[44:45]
	s_cbranch_execz .LBB0_1507
	v_lshl_or_b32 v19, v49, 6, v34
	v_add_u32_e32 v19, 0x20000, v19
	ds_read_b64 v[38:39], v19
	v_and_b32_e32 v20, 64, v226
	v_xor_b32_e32 v19, 8, v226
	v_add_u32_e32 v20, 64, v20
	v_cmp_lt_i32_e32 vcc, v19, v20
	v_mov_b32_e32 v20, v21
	s_nop 0
	v_cndmask_b32_e32 v19, v226, v19, vcc
	v_lshlrev_b32_e32 v19, 2, v19
	ds_bpermute_b32 v19, v19, v21
	s_waitcnt lgkmcnt(0)
	v_cndmask_b32_e64 v19, v19, -v19, s[36:37]
	s_waitcnt lgkmcnt(0)
	v_mov_b32_e32 v21, v39
	v_mov_b32_e32 v39, v19
	v_pk_mul_f32 v[20:21], v[20:21], v[38:39]
	s_nop 0
	v_add_f32_e32 v21, v20, v21
.LBB0_1507:
	s_or_b64 exec, exec, s[6:7]
	v_mul_f32_e32 v19, 0x3e16c740, v21
	v_cvt_pk_bf16_f32 v19, v19, s0
	v_mad_i64_i32 v[20:21], s[6:7], v18, s10, v[32:33]
	v_add_u32_e32 v38, 0x6a, v148
	global_store_short v[20:21], v19, off
	v_and_b32_e32 v19, 63, v38
	v_bfe_u32 v20, v38, 6, 4
	v_cndmask_b32_e64 v48, v20, v19, s[38:39]
	s_and_saveexec_b64 s[6:7], s[44:45]
	s_cbranch_execz .LBB0_1509
	v_lshl_or_b32 v19, v48, 6, v34
	v_add_u32_e32 v19, 0x20000, v19
	ds_read_b64 v[20:21], v19
	v_and_b32_e32 v39, 64, v226
	v_xor_b32_e32 v19, 8, v226
	v_add_u32_e32 v39, 64, v39
	v_cmp_lt_i32_e32 vcc, v19, v39
	v_mov_b32_e32 v42, v22
	s_waitcnt lgkmcnt(0)
	v_mov_b32_e32 v43, v21
	v_cndmask_b32_e32 v19, v226, v19, vcc
	v_lshlrev_b32_e32 v19, 2, v19
	ds_bpermute_b32 v19, v19, v22
	s_waitcnt lgkmcnt(0)
	v_cndmask_b32_e64 v19, v19, -v19, s[36:37]
	v_mov_b32_e32 v21, v19
	v_pk_mul_f32 v[20:21], v[42:43], v[20:21]
	s_nop 0
	v_add_f32_e32 v22, v20, v21
.LBB0_1509:
	s_or_b64 exec, exec, s[6:7]
	v_mul_f32_e32 v19, 0x3e16c740, v22
	v_cvt_pk_bf16_f32 v19, v19, s0
	v_mad_i64_i32 v[20:21], s[6:7], v38, s10, v[32:33]
	global_store_short v[20:21], v19, off
	v_add_u32_e32 v19, 0x6b, v148
	v_and_b32_e32 v20, 63, v19
	v_bfe_u32 v21, v19, 6, 4
	v_cndmask_b32_e64 v47, v21, v20, s[38:39]
	s_and_saveexec_b64 s[6:7], s[44:45]
	s_cbranch_execz .LBB0_1511
	v_lshl_or_b32 v20, v47, 6, v34
	v_add_u32_e32 v20, 0x20000, v20
	ds_read_b64 v[20:21], v20
	v_and_b32_e32 v39, 64, v226
	v_xor_b32_e32 v22, 8, v226
	v_add_u32_e32 v39, 64, v39
	v_cmp_lt_i32_e32 vcc, v22, v39
	s_nop 1
	v_cndmask_b32_e32 v22, v226, v22, vcc
	v_lshlrev_b32_e32 v22, 2, v22
	ds_bpermute_b32 v39, v22, v23
	v_mov_b32_e32 v22, v23
	s_waitcnt lgkmcnt(0)
	v_cndmask_b32_e64 v39, v39, -v39, s[36:37]
	s_waitcnt lgkmcnt(0)
	v_mov_b32_e32 v23, v21
	v_mov_b32_e32 v21, v39
	v_pk_mul_f32 v[20:21], v[22:23], v[20:21]
	s_nop 0
	v_add_f32_e32 v23, v20, v21
.LBB0_1511:
	s_or_b64 exec, exec, s[6:7]
	v_mul_f32_e32 v20, 0x3e16c740, v23
	v_cvt_pk_bf16_f32 v22, v20, s0
	v_mad_i64_i32 v[20:21], s[6:7], v19, s10, v[32:33]
	v_add_u32_e32 v39, 0x70, v148
	global_store_short v[20:21], v22, off
	v_and_b32_e32 v20, 63, v39
	v_bfe_u32 v21, v39, 6, 4
	v_cndmask_b32_e64 v46, v21, v20, s[38:39]
	s_and_saveexec_b64 s[6:7], s[44:45]
	s_cbranch_execz .LBB0_1513
	v_lshl_or_b32 v20, v46, 6, v34
	v_add_u32_e32 v20, 0x20000, v20
	ds_read_b64 v[20:21], v20
	v_and_b32_e32 v23, 64, v226
	v_xor_b32_e32 v22, 8, v226
	v_add_u32_e32 v23, 64, v23
	v_cmp_lt_i32_e32 vcc, v22, v23
	s_nop 1
	v_cndmask_b32_e32 v22, v226, v22, vcc
	v_lshlrev_b32_e32 v22, 2, v22
	ds_bpermute_b32 v23, v22, v24
	v_mov_b32_e32 v22, v24
	s_waitcnt lgkmcnt(0)
	v_cndmask_b32_e64 v24, v23, -v23, s[36:37]
	s_waitcnt lgkmcnt(0)
	v_mov_b32_e32 v23, v21
	v_mov_b32_e32 v21, v24
	v_pk_mul_f32 v[20:21], v[22:23], v[20:21]
	s_nop 0
	v_add_f32_e32 v24, v20, v21
.LBB0_1513:
	s_or_b64 exec, exec, s[6:7]
	v_mul_f32_e32 v20, 0x3e16c740, v24
	v_cvt_pk_bf16_f32 v22, v20, s0
	v_mad_i64_i32 v[20:21], s[6:7], v39, s10, v[32:33]
	global_store_short v[20:21], v22, off
	v_add_u32_e32 v20, 0x71, v148
	v_and_b32_e32 v21, 63, v20
	v_bfe_u32 v22, v20, 6, 4
	v_cndmask_b32_e64 v45, v22, v21, s[38:39]
	s_and_saveexec_b64 s[6:7], s[44:45]
	s_cbranch_execz .LBB0_1515
	v_lshl_or_b32 v21, v45, 6, v34
	v_add_u32_e32 v21, 0x20000, v21
	ds_read_b64 v[22:23], v21
	v_and_b32_e32 v24, 64, v226
	v_xor_b32_e32 v21, 8, v226
	v_add_u32_e32 v24, 64, v24
	v_cmp_lt_i32_e32 vcc, v21, v24
	v_mov_b32_e32 v24, v25
	s_nop 0
	v_cndmask_b32_e32 v21, v226, v21, vcc
	v_lshlrev_b32_e32 v21, 2, v21
	ds_bpermute_b32 v21, v21, v25
	s_waitcnt lgkmcnt(0)
	v_cndmask_b32_e64 v21, v21, -v21, s[36:37]
	s_waitcnt lgkmcnt(0)
	v_mov_b32_e32 v25, v23
	v_mov_b32_e32 v23, v21
	v_pk_mul_f32 v[22:23], v[24:25], v[22:23]
	s_nop 0
	v_add_f32_e32 v25, v22, v23
.LBB0_1515:
	s_or_b64 exec, exec, s[6:7]
	v_mul_f32_e32 v21, 0x3e16c740, v25
	v_cvt_pk_bf16_f32 v21, v21, s0
	v_mad_i64_i32 v[22:23], s[6:7], v20, s10, v[32:33]
	v_add_u32_e32 v24, 0x72, v148
	global_store_short v[22:23], v21, off
	v_and_b32_e32 v21, 63, v24
	v_bfe_u32 v22, v24, 6, 4
	v_cndmask_b32_e64 v44, v22, v21, s[38:39]
	s_and_saveexec_b64 s[6:7], s[44:45]
	s_cbranch_execz .LBB0_1517
	v_lshl_or_b32 v21, v44, 6, v34
	v_add_u32_e32 v21, 0x20000, v21
	ds_read_b64 v[22:23], v21
	v_and_b32_e32 v25, 64, v226
	v_xor_b32_e32 v21, 8, v226
	v_add_u32_e32 v25, 64, v25
	v_cmp_lt_i32_e32 vcc, v21, v25
	v_mov_b32_e32 v42, v26
	s_waitcnt lgkmcnt(0)
	v_mov_b32_e32 v43, v23
	v_cndmask_b32_e32 v21, v226, v21, vcc
	v_lshlrev_b32_e32 v21, 2, v21
	ds_bpermute_b32 v21, v21, v26
	s_waitcnt lgkmcnt(0)
	v_cndmask_b32_e64 v21, v21, -v21, s[36:37]
	v_mov_b32_e32 v23, v21
	v_pk_mul_f32 v[22:23], v[42:43], v[22:23]
	s_nop 0
	v_add_f32_e32 v26, v22, v23
.LBB0_1517:
	s_or_b64 exec, exec, s[6:7]
	v_mul_f32_e32 v21, 0x3e16c740, v26
	v_cvt_pk_bf16_f32 v21, v21, s0
	v_mad_i64_i32 v[22:23], s[6:7], v24, s10, v[32:33]
	global_store_short v[22:23], v21, off
	v_add_u32_e32 v21, 0x73, v148
	v_and_b32_e32 v22, 63, v21
	v_bfe_u32 v23, v21, 6, 4
	v_cndmask_b32_e64 v43, v23, v22, s[38:39]
	s_and_saveexec_b64 s[6:7], s[44:45]
	s_cbranch_execz .LBB0_1519
	v_lshl_or_b32 v22, v43, 6, v34
	v_add_u32_e32 v22, 0x20000, v22
	ds_read_b64 v[22:23], v22
	v_and_b32_e32 v26, 64, v226
	v_xor_b32_e32 v25, 8, v226
	v_add_u32_e32 v26, 64, v26
	v_cmp_lt_i32_e32 vcc, v25, v26
	v_mov_b32_e32 v26, v27
	s_nop 0
	v_cndmask_b32_e32 v25, v226, v25, vcc
	v_lshlrev_b32_e32 v25, 2, v25
	ds_bpermute_b32 v25, v25, v27
	s_waitcnt lgkmcnt(0)
	v_cndmask_b32_e64 v25, v25, -v25, s[36:37]
	s_waitcnt lgkmcnt(0)
	v_mov_b32_e32 v27, v23
	v_mov_b32_e32 v23, v25
	v_pk_mul_f32 v[22:23], v[26:27], v[22:23]
	s_nop 0
	v_add_f32_e32 v27, v22, v23
.LBB0_1519:
	s_or_b64 exec, exec, s[6:7]
	v_mul_f32_e32 v22, 0x3e16c740, v27
	v_cvt_pk_bf16_f32 v25, v22, s0
	v_mad_i64_i32 v[22:23], s[6:7], v21, s10, v[32:33]
	global_store_short v[22:23], v25, off
	v_add_u32_e32 v25, 0x78, v148
	v_and_b32_e32 v22, 63, v25
	v_bfe_u32 v23, v25, 6, 4
	v_cndmask_b32_e64 v42, v23, v22, s[38:39]
	s_and_saveexec_b64 s[6:7], s[44:45]
	s_cbranch_execz .LBB0_1521
	v_lshl_or_b32 v22, v42, 6, v34
	v_add_u32_e32 v22, 0x20000, v22
	ds_read_b64 v[22:23], v22
	v_and_b32_e32 v27, 64, v226
	v_xor_b32_e32 v26, 8, v226
	v_add_u32_e32 v27, 64, v27
	v_cmp_lt_i32_e32 vcc, v26, v27
	s_nop 1
	v_cndmask_b32_e32 v26, v226, v26, vcc
	v_lshlrev_b32_e32 v26, 2, v26
	ds_bpermute_b32 v27, v26, v28
	v_mov_b32_e32 v26, v28
	s_waitcnt lgkmcnt(0)
	v_cndmask_b32_e64 v28, v27, -v27, s[36:37]
	s_waitcnt lgkmcnt(0)
	v_mov_b32_e32 v27, v23
	v_mov_b32_e32 v23, v28
	v_pk_mul_f32 v[22:23], v[26:27], v[22:23]
	s_nop 0
	v_add_f32_e32 v28, v22, v23
.LBB0_1521:
	s_or_b64 exec, exec, s[6:7]
	v_mul_f32_e32 v22, 0x3e16c740, v28
	v_cvt_pk_bf16_f32 v26, v22, s0
	v_mad_i64_i32 v[22:23], s[6:7], v25, s10, v[32:33]
	global_store_short v[22:23], v26, off
	v_add_u32_e32 v22, 0x79, v148
	v_and_b32_e32 v23, 63, v22
	v_bfe_u32 v26, v22, 6, 4
	v_cndmask_b32_e64 v41, v26, v23, s[38:39]
	s_and_saveexec_b64 s[6:7], s[44:45]
	s_cbranch_execz .LBB0_1523
	v_lshl_or_b32 v23, v41, 6, v34
	v_add_u32_e32 v23, 0x20000, v23
	ds_read_b64 v[26:27], v23
	v_and_b32_e32 v28, 64, v226
	v_xor_b32_e32 v23, 8, v226
	v_add_u32_e32 v28, 64, v28
	v_cmp_lt_i32_e32 vcc, v23, v28
	v_mov_b32_e32 v28, v29
	s_nop 0
	v_cndmask_b32_e32 v23, v226, v23, vcc
	v_lshlrev_b32_e32 v23, 2, v23
	ds_bpermute_b32 v23, v23, v29
	s_waitcnt lgkmcnt(0)
	v_cndmask_b32_e64 v23, v23, -v23, s[36:37]
	s_waitcnt lgkmcnt(0)
	v_mov_b32_e32 v29, v27
	v_mov_b32_e32 v27, v23
	v_pk_mul_f32 v[26:27], v[28:29], v[26:27]
	s_nop 0
	v_add_f32_e32 v29, v26, v27
.LBB0_1523:
	s_or_b64 exec, exec, s[6:7]
	v_mul_f32_e32 v23, 0x3e16c740, v29
	v_cvt_pk_bf16_f32 v23, v23, s0
	v_mad_i64_i32 v[26:27], s[6:7], v22, s10, v[32:33]
	global_store_short v[26:27], v23, off
	v_add_u32_e32 v26, 0x7a, v148
	v_and_b32_e32 v23, 63, v26
	v_bfe_u32 v27, v26, 6, 4
	v_cndmask_b32_e64 v28, v27, v23, s[38:39]
	s_and_saveexec_b64 s[6:7], s[44:45]
	s_cbranch_execz .LBB0_1525
	v_lshl_or_b32 v23, v28, 6, v34
	v_add_u32_e32 v23, 0x20000, v23
	ds_read_b64 v[54:55], v23
	v_and_b32_e32 v27, 64, v226
	v_xor_b32_e32 v23, 8, v226
	v_add_u32_e32 v27, 64, v27
	v_cmp_lt_i32_e32 vcc, v23, v27
	v_mov_b32_e32 v56, v30
	s_waitcnt lgkmcnt(0)
	v_mov_b32_e32 v57, v55
	v_cndmask_b32_e32 v23, v226, v23, vcc
	v_lshlrev_b32_e32 v23, 2, v23
	ds_bpermute_b32 v23, v23, v30
	s_waitcnt lgkmcnt(0)
	v_cndmask_b32_e64 v23, v23, -v23, s[36:37]
	v_mov_b32_e32 v55, v23
	v_pk_mul_f32 v[54:55], v[56:57], v[54:55]
	s_nop 0
	v_add_f32_e32 v30, v54, v55
.LBB0_1525:
	s_or_b64 exec, exec, s[6:7]
	v_mul_f32_e32 v23, 0x3e16c740, v30
	v_cvt_pk_bf16_f32 v23, v23, s0
	v_mad_i64_i32 v[54:55], s[6:7], v26, s10, v[32:33]
	global_store_short v[54:55], v23, off
	v_add_u32_e32 v23, 0x7b, v148
	v_and_b32_e32 v27, 63, v23
	v_bfe_u32 v29, v23, 6, 4
	v_cndmask_b32_e64 v27, v29, v27, s[38:39]
	s_and_saveexec_b64 s[6:7], s[44:45]
	s_cbranch_execz .LBB0_1527
	v_lshl_or_b32 v29, v27, 6, v34
	v_add_u32_e32 v29, 0x20000, v29
	ds_read_b64 v[54:55], v29
	v_and_b32_e32 v30, 64, v226
	v_xor_b32_e32 v29, 8, v226
	v_add_u32_e32 v30, 64, v30
	v_cmp_lt_i32_e32 vcc, v29, v30
	v_mov_b32_e32 v30, v31
	s_nop 0
	v_cndmask_b32_e32 v29, v226, v29, vcc
	v_lshlrev_b32_e32 v29, 2, v29
	ds_bpermute_b32 v29, v29, v31
	s_waitcnt lgkmcnt(0)
	v_cndmask_b32_e64 v29, v29, -v29, s[36:37]
	s_waitcnt lgkmcnt(0)
	v_mov_b32_e32 v31, v55
	v_mov_b32_e32 v55, v29
	v_pk_mul_f32 v[30:31], v[30:31], v[54:55]
	s_nop 0
	v_add_f32_e32 v31, v30, v31

.LBB0_1529:
	s_and_saveexec_b64 s[6:7], s[0:1]
	s_cbranch_execz .LBB0_1531
	v_lshl_or_b32 v29, v40, 6, v34
	v_add_u32_e32 v29, 0x20000, v29
	ds_read_b64 v[30:31], v29
	v_and_b32_e32 v32, 64, v226
	v_xor_b32_e32 v29, 8, v226
	v_add_u32_e32 v32, 64, v32
	v_cmp_lt_i32_e32 vcc, v29, v32
	v_mov_b32_e32 v32, v0
	s_waitcnt lgkmcnt(0)
	v_mov_b32_e32 v33, v31
	v_cndmask_b32_e32 v29, v226, v29, vcc
	v_lshlrev_b32_e32 v29, 2, v29
	ds_bpermute_b32 v29, v29, v0
	s_waitcnt lgkmcnt(0)
	v_cndmask_b32_e64 v0, v29, -v29, s[36:37]
	v_mov_b32_e32 v31, v0
	v_pk_mul_f32 v[30:31], v[32:33], v[30:31]
	s_nop 0
	v_add_f32_e32 v0, v30, v31
.LBB0_1531:
	s_or_b64 exec, exec, s[6:7]
	v_mad_i64_i32 v[30:31], s[6:7], v35, s10, 0
	v_mul_f32_e32 v0, 0x3e16c740, v0
	v_lshl_add_u64 v[30:31], s[70:71], 0, v[30:31]
	v_cvt_pk_bf16_f32 v0, v0, s0
	v_lshl_add_u64 v[30:31], v[128:129], 1, v[30:31]
	global_store_short v[30:31], v0, off
	s_and_saveexec_b64 s[6:7], s[0:1]
	s_cbranch_execz .LBB0_1533
	v_lshl_or_b32 v0, v53, 6, v34
	v_add_u32_e32 v0, 0x20000, v0
	ds_read_b64 v[30:31], v0
	v_and_b32_e32 v29, 64, v226
	v_xor_b32_e32 v0, 8, v226
	v_add_u32_e32 v29, 64, v29
	v_cmp_lt_i32_e32 vcc, v0, v29
	s_nop 1
	v_cndmask_b32_e32 v0, v226, v0, vcc
	v_lshlrev_b32_e32 v0, 2, v0
	ds_bpermute_b32 v29, v0, v1
	v_mov_b32_e32 v0, v1
	s_waitcnt lgkmcnt(0)
	v_cndmask_b32_e64 v29, v29, -v29, s[36:37]
	s_waitcnt lgkmcnt(0)
	v_mov_b32_e32 v1, v31
	v_mov_b32_e32 v31, v29
	v_pk_mul_f32 v[0:1], v[0:1], v[30:31]
	s_nop 0
	v_add_f32_e32 v1, v0, v1
.LBB0_1533:
	s_or_b64 exec, exec, s[6:7]
	v_mad_i64_i32 v[30:31], s[6:7], v16, s10, 0
	v_mul_f32_e32 v0, 0x3e16c740, v1
	v_cvt_pk_bf16_f32 v16, v0, s0
	v_lshl_add_u64 v[0:1], s[70:71], 0, v[30:31]
	v_lshl_add_u64 v[0:1], v[128:129], 1, v[0:1]
	global_store_short v[0:1], v16, off
	s_and_saveexec_b64 s[6:7], s[0:1]
	s_cbranch_execz .LBB0_1535
	v_lshl_or_b32 v0, v52, 6, v34
	v_add_u32_e32 v0, 0x20000, v0
	ds_read_b64 v[0:1], v0
	v_and_b32_e32 v29, 64, v226
	v_xor_b32_e32 v16, 8, v226
	v_add_u32_e32 v29, 64, v29
	v_cmp_lt_i32_e32 vcc, v16, v29
	v_mov_b32_e32 v30, v2
	s_waitcnt lgkmcnt(0)
	v_mov_b32_e32 v31, v1
	v_cndmask_b32_e32 v16, v226, v16, vcc
	v_lshlrev_b32_e32 v16, 2, v16
	ds_bpermute_b32 v16, v16, v2
	s_waitcnt lgkmcnt(0)
	v_cndmask_b32_e64 v2, v16, -v16, s[36:37]
	v_mov_b32_e32 v1, v2
	v_pk_mul_f32 v[0:1], v[30:31], v[0:1]
	s_nop 0
	v_add_f32_e32 v2, v0, v1
.LBB0_1535:
	s_or_b64 exec, exec, s[6:7]
	v_mad_i64_i32 v[0:1], s[6:7], v36, s10, 0
	v_mul_f32_e32 v2, 0x3e16c740, v2
	v_lshl_add_u64 v[0:1], s[70:71], 0, v[0:1]
	v_cvt_pk_bf16_f32 v2, v2, s0
	v_lshl_add_u64 v[0:1], v[128:129], 1, v[0:1]
	global_store_short v[0:1], v2, off
	s_and_saveexec_b64 s[6:7], s[0:1]
	s_cbranch_execz .LBB0_1537
	v_lshl_or_b32 v0, v51, 6, v34
	v_add_u32_e32 v0, 0x20000, v0
	ds_read_b64 v[0:1], v0
	v_and_b32_e32 v16, 64, v226
	v_xor_b32_e32 v2, 8, v226
	v_add_u32_e32 v16, 64, v16
	v_cmp_lt_i32_e32 vcc, v2, v16
	s_nop 1
	v_cndmask_b32_e32 v2, v226, v2, vcc
	v_lshlrev_b32_e32 v2, 2, v2
	ds_bpermute_b32 v16, v2, v3
	v_mov_b32_e32 v2, v3
	s_waitcnt lgkmcnt(0)
	v_cndmask_b32_e64 v16, v16, -v16, s[36:37]
	s_waitcnt lgkmcnt(0)
	v_mov_b32_e32 v3, v1
	v_mov_b32_e32 v1, v16
	v_pk_mul_f32 v[0:1], v[2:3], v[0:1]
	s_nop 0
	v_add_f32_e32 v3, v0, v1
.LBB0_1537:
	s_or_b64 exec, exec, s[6:7]
	v_mad_i64_i32 v[0:1], s[6:7], v17, s10, 0
	v_mul_f32_e32 v2, 0x3e16c740, v3
	v_lshl_add_u64 v[0:1], s[70:71], 0, v[0:1]
	v_cvt_pk_bf16_f32 v2, v2, s0
	v_lshl_add_u64 v[0:1], v[128:129], 1, v[0:1]
	global_store_short v[0:1], v2, off
	s_and_saveexec_b64 s[6:7], s[0:1]
	s_cbranch_execz .LBB0_1539
	v_lshl_or_b32 v0, v50, 6, v34
	v_add_u32_e32 v0, 0x20000, v0
	ds_read_b64 v[0:1], v0
	v_and_b32_e32 v3, 64, v226
	v_xor_b32_e32 v2, 8, v226
	v_add_u32_e32 v3, 64, v3
	v_cmp_lt_i32_e32 vcc, v2, v3
	s_nop 1
	v_cndmask_b32_e32 v2, v226, v2, vcc
	v_lshlrev_b32_e32 v2, 2, v2
	ds_bpermute_b32 v3, v2, v4
	v_mov_b32_e32 v2, v4
	s_waitcnt lgkmcnt(0)
	v_cndmask_b32_e64 v4, v3, -v3, s[36:37]
	s_waitcnt lgkmcnt(0)
	v_mov_b32_e32 v3, v1
	v_mov_b32_e32 v1, v4
	v_pk_mul_f32 v[0:1], v[2:3], v[0:1]
	s_nop 0
	v_add_f32_e32 v4, v0, v1
.LBB0_1539:
	s_or_b64 exec, exec, s[6:7]
	v_mad_i64_i32 v[0:1], s[6:7], v37, s10, 0
	v_mul_f32_e32 v2, 0x3e16c740, v4
	v_lshl_add_u64 v[0:1], s[70:71], 0, v[0:1]
	v_cvt_pk_bf16_f32 v2, v2, s0
	v_lshl_add_u64 v[0:1], v[128:129], 1, v[0:1]
	global_store_short v[0:1], v2, off
	s_and_saveexec_b64 s[6:7], s[0:1]
	s_cbranch_execz .LBB0_1541
	v_lshl_or_b32 v0, v49, 6, v34
	v_add_u32_e32 v0, 0x20000, v0
	ds_read_b64 v[0:1], v0
	v_and_b32_e32 v3, 64, v226
	v_xor_b32_e32 v2, 8, v226
	v_add_u32_e32 v3, 64, v3
	v_cmp_lt_i32_e32 vcc, v2, v3
	s_nop 1
	v_cndmask_b32_e32 v2, v226, v2, vcc
	v_lshlrev_b32_e32 v2, 2, v2
	ds_bpermute_b32 v3, v2, v5
	v_mov_b32_e32 v2, v5
	s_waitcnt lgkmcnt(0)
	v_cndmask_b32_e64 v4, v3, -v3, s[36:37]
	s_waitcnt lgkmcnt(0)
	v_mov_b32_e32 v3, v1
	v_mov_b32_e32 v1, v4
	v_pk_mul_f32 v[0:1], v[2:3], v[0:1]
	s_nop 0
	v_add_f32_e32 v5, v0, v1
.LBB0_1541:
	s_or_b64 exec, exec, s[6:7]
	v_mad_i64_i32 v[0:1], s[6:7], v18, s10, 0
	v_mul_f32_e32 v2, 0x3e16c740, v5
	v_lshl_add_u64 v[0:1], s[70:71], 0, v[0:1]
	v_cvt_pk_bf16_f32 v2, v2, s0
	v_lshl_add_u64 v[0:1], v[128:129], 1, v[0:1]
	global_store_short v[0:1], v2, off
	s_and_saveexec_b64 s[6:7], s[0:1]
	s_cbranch_execz .LBB0_1543
	v_lshl_or_b32 v0, v48, 6, v34
	v_add_u32_e32 v0, 0x20000, v0
	ds_read_b64 v[0:1], v0
	v_and_b32_e32 v3, 64, v226
	v_xor_b32_e32 v2, 8, v226
	v_add_u32_e32 v3, 64, v3
	v_cmp_lt_i32_e32 vcc, v2, v3
	s_nop 1
	v_cndmask_b32_e32 v2, v226, v2, vcc
	v_lshlrev_b32_e32 v2, 2, v2
	ds_bpermute_b32 v3, v2, v6
	v_mov_b32_e32 v2, v6
	s_waitcnt lgkmcnt(0)
	v_cndmask_b32_e64 v4, v3, -v3, s[36:37]
	s_waitcnt lgkmcnt(0)
	v_mov_b32_e32 v3, v1
	v_mov_b32_e32 v1, v4
	v_pk_mul_f32 v[0:1], v[2:3], v[0:1]
	s_nop 0
	v_add_f32_e32 v6, v0, v1
.LBB0_1543:
	s_or_b64 exec, exec, s[6:7]
	v_mad_i64_i32 v[0:1], s[6:7], v38, s10, 0
	v_mul_f32_e32 v2, 0x3e16c740, v6
	v_lshl_add_u64 v[0:1], s[70:71], 0, v[0:1]
	v_cvt_pk_bf16_f32 v2, v2, s0
	v_lshl_add_u64 v[0:1], v[128:129], 1, v[0:1]
	global_store_short v[0:1], v2, off
	s_and_saveexec_b64 s[6:7], s[0:1]
	s_cbranch_execz .LBB0_1545
	v_lshl_or_b32 v0, v47, 6, v34
	v_add_u32_e32 v0, 0x20000, v0
	ds_read_b64 v[0:1], v0
	v_and_b32_e32 v3, 64, v226
	v_xor_b32_e32 v2, 8, v226
	v_add_u32_e32 v3, 64, v3
	v_cmp_lt_i32_e32 vcc, v2, v3
	s_nop 1
	v_cndmask_b32_e32 v2, v226, v2, vcc
	v_lshlrev_b32_e32 v2, 2, v2
	ds_bpermute_b32 v3, v2, v7
	v_mov_b32_e32 v2, v7
	s_waitcnt lgkmcnt(0)
	v_cndmask_b32_e64 v4, v3, -v3, s[36:37]
	s_waitcnt lgkmcnt(0)
	v_mov_b32_e32 v3, v1
	v_mov_b32_e32 v1, v4
	v_pk_mul_f32 v[0:1], v[2:3], v[0:1]
	s_nop 0
	v_add_f32_e32 v7, v0, v1
.LBB0_1545:
	s_or_b64 exec, exec, s[6:7]
	v_mad_i64_i32 v[0:1], s[6:7], v19, s10, 0
	v_mul_f32_e32 v2, 0x3e16c740, v7
	v_lshl_add_u64 v[0:1], s[70:71], 0, v[0:1]
	v_cvt_pk_bf16_f32 v2, v2, s0
	v_lshl_add_u64 v[0:1], v[128:129], 1, v[0:1]
	global_store_short v[0:1], v2, off
	s_and_saveexec_b64 s[6:7], s[0:1]
	s_cbranch_execz .LBB0_1547
	v_lshl_or_b32 v0, v46, 6, v34
	v_add_u32_e32 v0, 0x20000, v0
	ds_read_b64 v[0:1], v0
	v_and_b32_e32 v3, 64, v226
	v_xor_b32_e32 v2, 8, v226
	v_add_u32_e32 v3, 64, v3
	v_cmp_lt_i32_e32 vcc, v2, v3
	s_nop 1
	v_cndmask_b32_e32 v2, v226, v2, vcc
	v_lshlrev_b32_e32 v2, 2, v2
	ds_bpermute_b32 v3, v2, v8
	v_mov_b32_e32 v2, v8
	s_waitcnt lgkmcnt(0)
	v_cndmask_b32_e64 v4, v3, -v3, s[36:37]
	s_waitcnt lgkmcnt(0)
	v_mov_b32_e32 v3, v1
	v_mov_b32_e32 v1, v4
	v_pk_mul_f32 v[0:1], v[2:3], v[0:1]
	s_nop 0
	v_add_f32_e32 v8, v0, v1
.LBB0_1547:
	s_or_b64 exec, exec, s[6:7]
	v_mad_i64_i32 v[0:1], s[6:7], v39, s10, 0
	v_mul_f32_e32 v2, 0x3e16c740, v8
	v_lshl_add_u64 v[0:1], s[70:71], 0, v[0:1]
	v_cvt_pk_bf16_f32 v2, v2, s0
	v_lshl_add_u64 v[0:1], v[128:129], 1, v[0:1]
	global_store_short v[0:1], v2, off
	s_and_saveexec_b64 s[6:7], s[0:1]
	s_cbranch_execz .LBB0_1549
	v_lshl_or_b32 v0, v45, 6, v34
	v_add_u32_e32 v0, 0x20000, v0
	ds_read_b64 v[0:1], v0
	v_and_b32_e32 v3, 64, v226
	v_xor_b32_e32 v2, 8, v226
	v_add_u32_e32 v3, 64, v3
	v_cmp_lt_i32_e32 vcc, v2, v3
	s_nop 1
	v_cndmask_b32_e32 v2, v226, v2, vcc
	v_lshlrev_b32_e32 v2, 2, v2
	ds_bpermute_b32 v3, v2, v9
	v_mov_b32_e32 v2, v9
	s_waitcnt lgkmcnt(0)
	v_cndmask_b32_e64 v4, v3, -v3, s[36:37]
	s_waitcnt lgkmcnt(0)
	v_mov_b32_e32 v3, v1
	v_mov_b32_e32 v1, v4
	v_pk_mul_f32 v[0:1], v[2:3], v[0:1]
	s_nop 0
	v_add_f32_e32 v9, v0, v1
.LBB0_1549:
	s_or_b64 exec, exec, s[6:7]
	v_mad_i64_i32 v[0:1], s[6:7], v20, s10, 0
	v_mul_f32_e32 v2, 0x3e16c740, v9
	v_lshl_add_u64 v[0:1], s[70:71], 0, v[0:1]
	v_cvt_pk_bf16_f32 v2, v2, s0
	v_lshl_add_u64 v[0:1], v[128:129], 1, v[0:1]
	global_store_short v[0:1], v2, off
	s_and_saveexec_b64 s[6:7], s[0:1]
	s_cbranch_execz .LBB0_1551
	v_lshl_or_b32 v0, v44, 6, v34
	v_add_u32_e32 v0, 0x20000, v0
	ds_read_b64 v[0:1], v0
	v_and_b32_e32 v3, 64, v226
	v_xor_b32_e32 v2, 8, v226
	v_add_u32_e32 v3, 64, v3
	v_cmp_lt_i32_e32 vcc, v2, v3
	s_nop 1
	v_cndmask_b32_e32 v2, v226, v2, vcc
	v_lshlrev_b32_e32 v2, 2, v2
	ds_bpermute_b32 v3, v2, v10
	v_mov_b32_e32 v2, v10
	s_waitcnt lgkmcnt(0)
	v_cndmask_b32_e64 v4, v3, -v3, s[36:37]
	s_waitcnt lgkmcnt(0)
	v_mov_b32_e32 v3, v1
	v_mov_b32_e32 v1, v4
	v_pk_mul_f32 v[0:1], v[2:3], v[0:1]
	s_nop 0
	v_add_f32_e32 v10, v0, v1
.LBB0_1551:
	s_or_b64 exec, exec, s[6:7]
	v_mad_i64_i32 v[0:1], s[6:7], v24, s10, 0
	v_mul_f32_e32 v2, 0x3e16c740, v10
	v_lshl_add_u64 v[0:1], s[70:71], 0, v[0:1]
	v_cvt_pk_bf16_f32 v2, v2, s0
	v_lshl_add_u64 v[0:1], v[128:129], 1, v[0:1]
	global_store_short v[0:1], v2, off
	s_and_saveexec_b64 s[6:7], s[0:1]
	s_cbranch_execz .LBB0_1553
	v_lshl_or_b32 v0, v43, 6, v34
	v_add_u32_e32 v0, 0x20000, v0
	ds_read_b64 v[0:1], v0
	v_and_b32_e32 v3, 64, v226
	v_xor_b32_e32 v2, 8, v226
	v_add_u32_e32 v3, 64, v3
	v_cmp_lt_i32_e32 vcc, v2, v3
	s_nop 1
	v_cndmask_b32_e32 v2, v226, v2, vcc
	v_lshlrev_b32_e32 v2, 2, v2
	ds_bpermute_b32 v3, v2, v11
	v_mov_b32_e32 v2, v11
	s_waitcnt lgkmcnt(0)
	v_cndmask_b32_e64 v4, v3, -v3, s[36:37]
	s_waitcnt lgkmcnt(0)
	v_mov_b32_e32 v3, v1
	v_mov_b32_e32 v1, v4
	v_pk_mul_f32 v[0:1], v[2:3], v[0:1]
	s_nop 0
	v_add_f32_e32 v11, v0, v1
.LBB0_1553:
	s_or_b64 exec, exec, s[6:7]
	v_mad_i64_i32 v[0:1], s[6:7], v21, s10, 0
	v_mul_f32_e32 v2, 0x3e16c740, v11
	v_lshl_add_u64 v[0:1], s[70:71], 0, v[0:1]
	v_cvt_pk_bf16_f32 v2, v2, s0
	v_lshl_add_u64 v[0:1], v[128:129], 1, v[0:1]
	global_store_short v[0:1], v2, off
	s_and_saveexec_b64 s[6:7], s[0:1]
	s_cbranch_execz .LBB0_1555
	v_lshl_or_b32 v0, v42, 6, v34
	v_add_u32_e32 v0, 0x20000, v0
	ds_read_b64 v[0:1], v0
	v_and_b32_e32 v3, 64, v226
	v_xor_b32_e32 v2, 8, v226
	v_add_u32_e32 v3, 64, v3
	v_cmp_lt_i32_e32 vcc, v2, v3
	s_nop 1
	v_cndmask_b32_e32 v2, v226, v2, vcc
	v_lshlrev_b32_e32 v2, 2, v2
	ds_bpermute_b32 v3, v2, v12
	v_mov_b32_e32 v2, v12
	s_waitcnt lgkmcnt(0)
	v_cndmask_b32_e64 v4, v3, -v3, s[36:37]
	s_waitcnt lgkmcnt(0)
	v_mov_b32_e32 v3, v1
	v_mov_b32_e32 v1, v4
	v_pk_mul_f32 v[0:1], v[2:3], v[0:1]
	s_nop 0
	v_add_f32_e32 v12, v0, v1
.LBB0_1555:
	s_or_b64 exec, exec, s[6:7]
	v_mad_i64_i32 v[0:1], s[6:7], v25, s10, 0
	v_mul_f32_e32 v2, 0x3e16c740, v12
	v_lshl_add_u64 v[0:1], s[70:71], 0, v[0:1]
	v_cvt_pk_bf16_f32 v2, v2, s0
	v_lshl_add_u64 v[0:1], v[128:129], 1, v[0:1]
	global_store_short v[0:1], v2, off
	s_and_saveexec_b64 s[6:7], s[0:1]
	s_cbranch_execz .LBB0_1557
	v_lshl_or_b32 v0, v41, 6, v34
	v_add_u32_e32 v0, 0x20000, v0
	ds_read_b64 v[0:1], v0
	v_and_b32_e32 v3, 64, v226
	v_xor_b32_e32 v2, 8, v226
	v_add_u32_e32 v3, 64, v3
	v_cmp_lt_i32_e32 vcc, v2, v3
	s_nop 1
	v_cndmask_b32_e32 v2, v226, v2, vcc
	v_lshlrev_b32_e32 v2, 2, v2
	ds_bpermute_b32 v3, v2, v13
	v_mov_b32_e32 v2, v13
	s_waitcnt lgkmcnt(0)
	v_cndmask_b32_e64 v4, v3, -v3, s[36:37]
	s_waitcnt lgkmcnt(0)
	v_mov_b32_e32 v3, v1
	v_mov_b32_e32 v1, v4
	v_pk_mul_f32 v[0:1], v[2:3], v[0:1]
	s_nop 0
	v_add_f32_e32 v13, v0, v1
.LBB0_1557:
	s_or_b64 exec, exec, s[6:7]
	v_mad_i64_i32 v[0:1], s[6:7], v22, s10, 0
	v_mul_f32_e32 v2, 0x3e16c740, v13
	v_lshl_add_u64 v[0:1], s[70:71], 0, v[0:1]
	v_cvt_pk_bf16_f32 v2, v2, s0
	v_lshl_add_u64 v[0:1], v[128:129], 1, v[0:1]
	global_store_short v[0:1], v2, off
	s_and_saveexec_b64 s[6:7], s[0:1]
	s_cbranch_execz .LBB0_1559
	v_lshl_or_b32 v0, v28, 6, v34
	v_add_u32_e32 v0, 0x20000, v0
	ds_read_b64 v[0:1], v0
	v_and_b32_e32 v3, 64, v226
	v_xor_b32_e32 v2, 8, v226
	v_add_u32_e32 v3, 64, v3
	v_cmp_lt_i32_e32 vcc, v2, v3
	s_nop 1
	v_cndmask_b32_e32 v2, v226, v2, vcc
	v_lshlrev_b32_e32 v2, 2, v2
	ds_bpermute_b32 v3, v2, v14
	v_mov_b32_e32 v2, v14
	s_waitcnt lgkmcnt(0)
	v_cndmask_b32_e64 v4, v3, -v3, s[36:37]
	s_waitcnt lgkmcnt(0)
	v_mov_b32_e32 v3, v1
	v_mov_b32_e32 v1, v4
	v_pk_mul_f32 v[0:1], v[2:3], v[0:1]
	s_nop 0
	v_add_f32_e32 v14, v0, v1
.LBB0_1559:
	s_or_b64 exec, exec, s[6:7]
	v_mad_i64_i32 v[0:1], s[6:7], v26, s10, 0
	v_mul_f32_e32 v2, 0x3e16c740, v14
	v_lshl_add_u64 v[0:1], s[70:71], 0, v[0:1]
	v_cvt_pk_bf16_f32 v2, v2, s0
	v_lshl_add_u64 v[0:1], v[128:129], 1, v[0:1]
	global_store_short v[0:1], v2, off
	s_and_saveexec_b64 s[6:7], s[0:1]
	s_cbranch_execz .LBB0_1221
	v_lshl_or_b32 v0, v27, 6, v34
	v_add_u32_e32 v0, 0x20000, v0
	ds_read_b64 v[0:1], v0
	v_and_b32_e32 v3, 64, v226
	v_xor_b32_e32 v2, 8, v226
	v_add_u32_e32 v3, 64, v3
	v_cmp_lt_i32_e32 vcc, v2, v3
	s_nop 1
	v_cndmask_b32_e32 v2, v226, v2, vcc
	v_lshlrev_b32_e32 v2, 2, v2
	ds_bpermute_b32 v3, v2, v15
	v_mov_b32_e32 v2, v15
	s_waitcnt lgkmcnt(0)
	v_cndmask_b32_e64 v4, v3, -v3, s[36:37]
	s_waitcnt lgkmcnt(0)
	v_mov_b32_e32 v3, v1
	v_mov_b32_e32 v1, v4
	v_pk_mul_f32 v[0:1], v[2:3], v[0:1]
	s_nop 0
	v_add_f32_e32 v15, v0, v1
	s_branch .LBB0_1221
